# v6 + K-loop LDS-DMA loads use scalar-base addressing (16 64-bit VALU adds per iteration removed, m0 gaps filled by ds_reads)
# speedup vs baseline: 1.0050x; 1.0050x over previous
.LBB0_38:
	s_add_u32 s10, s8, 0x100
	s_addc_u32 s11, s9, 0
	s_add_i32 s48, 0, 0x10000
	s_cmp_eq_u32 s22, 40
	s_cselect_b32 s15, s1, s11
	s_cselect_b32 s14, s0, s10
	s_cselect_b32 s13, s37, s90
	s_cselect_b32 s12, s36, s21
	s_add_i32 s49, 0, 0x14000
	v_add_u32_e32 v154, s48, v143
	v_add_u32_e32 v158, s49, v143
	ds_read_b128 v[138:141], v154
	ds_read_b128 v[146:149], v154 offset:1024
	ds_read_b128 v[150:153], v154 offset:2048
	ds_read_b128 v[154:157], v154 offset:3072
	ds_read_b128 v[162:165], v158
	ds_read_b128 v[166:169], v158 offset:1024
	ds_read_b128 v[170:173], v158 offset:2048
	ds_read_b128 v[174:177], v158 offset:3072
	s_add_i32 m0, s29, 0xc000
	ds_read_b128 v[178:181], v145
	ds_read_b128 v[182:185], v145 offset:1024
	ds_read_b128 v[186:189], v145 offset:2048
	ds_read_b128 v[190:193], v145 offset:3072
	ds_read_b128 v[194:197], v145 offset:4096
	ds_read_b128 v[198:201], v145 offset:5120
	ds_read_b128 v[202:205], v145 offset:6144
	global_load_lds_dwordx4 v136, s[8:9]
	s_add_i32 m0, s29, 0xe000
	ds_read_b128 v[206:209], v145 offset:7168
	global_load_lds_dwordx4 v134, s[8:9]
	s_waitcnt vmcnt(8)
	s_waitcnt lgkmcnt(0)
	s_barrier
	v_mfma_f32_16x16x32_bf16 v[124:127], v[138:141], v[178:181], v[124:127]
	v_mfma_f32_16x16x32_bf16 v[120:123], v[150:153], v[178:181], v[120:123]
	v_mfma_f32_16x16x32_bf16 v[108:111], v[138:141], v[186:189], v[108:111]
	v_mfma_f32_16x16x32_bf16 v[104:107], v[150:153], v[186:189], v[104:107]
	v_mfma_f32_16x16x32_bf16 v[92:95], v[138:141], v[194:197], v[92:95]
	v_mfma_f32_16x16x32_bf16 v[88:91], v[150:153], v[194:197], v[88:91]
	v_mfma_f32_16x16x32_bf16 v[76:79], v[138:141], v[202:205], v[76:79]
	v_mfma_f32_16x16x32_bf16 v[72:75], v[150:153], v[202:205], v[72:75]
	v_mfma_f32_16x16x32_bf16 v[124:127], v[146:149], v[182:185], v[124:127]
	v_mfma_f32_16x16x32_bf16 v[120:123], v[154:157], v[182:185], v[120:123]
	v_mfma_f32_16x16x32_bf16 v[108:111], v[146:149], v[190:193], v[108:111]
	v_mfma_f32_16x16x32_bf16 v[104:107], v[154:157], v[190:193], v[104:107]
	v_mfma_f32_16x16x32_bf16 v[92:95], v[146:149], v[198:201], v[92:95]
	v_mfma_f32_16x16x32_bf16 v[88:91], v[154:157], v[198:201], v[88:91]
	v_mfma_f32_16x16x32_bf16 v[76:79], v[146:149], v[206:209], v[76:79]
	v_mfma_f32_16x16x32_bf16 v[72:75], v[154:157], v[206:209], v[72:75]
	v_mfma_f32_16x16x32_bf16 v[116:119], v[162:165], v[178:181], v[116:119]
	v_mfma_f32_16x16x32_bf16 v[112:115], v[170:173], v[178:181], v[112:115]
	v_mfma_f32_16x16x32_bf16 v[100:103], v[162:165], v[186:189], v[100:103]
	v_mfma_f32_16x16x32_bf16 v[96:99], v[170:173], v[186:189], v[96:99]
	v_mfma_f32_16x16x32_bf16 v[84:87], v[162:165], v[194:197], v[84:87]
	v_mfma_f32_16x16x32_bf16 v[80:83], v[170:173], v[194:197], v[80:83]
	v_mfma_f32_16x16x32_bf16 v[68:71], v[162:165], v[202:205], v[68:71]
	v_mfma_f32_16x16x32_bf16 v[64:67], v[170:173], v[202:205], v[64:67]
	v_mfma_f32_16x16x32_bf16 v[116:119], v[166:169], v[182:185], v[116:119]
	v_mfma_f32_16x16x32_bf16 v[112:115], v[174:177], v[182:185], v[112:115]
	v_mfma_f32_16x16x32_bf16 v[100:103], v[166:169], v[190:193], v[100:103]
	v_mfma_f32_16x16x32_bf16 v[96:99], v[174:177], v[190:193], v[96:99]
	v_mfma_f32_16x16x32_bf16 v[84:87], v[166:169], v[198:201], v[84:87]
	v_mfma_f32_16x16x32_bf16 v[80:83], v[174:177], v[198:201], v[80:83]
	v_mfma_f32_16x16x32_bf16 v[68:71], v[166:169], v[206:209], v[68:71]
	v_mfma_f32_16x16x32_bf16 v[64:67], v[174:177], v[206:209], v[64:67]
	s_barrier
	s_add_i32 s8, s48, s28
	s_mov_b32 m0, s8
	ds_read_b128 v[178:181], v145 offset:16384
	ds_read_b128 v[182:185], v145 offset:17408
	ds_read_b128 v[186:189], v145 offset:18432
	ds_read_b128 v[190:193], v145 offset:19456
	global_load_lds_dwordx4 v160, s[12:13]
	s_add_i32 m0, s8, 0x2000
	s_add_u32 s8, s12, 0xb0000
	s_addc_u32 s9, s13, 0
	s_add_i32 s48, s49, s28
	global_load_lds_dwordx4 v132, s[12:13]
	s_mov_b32 m0, s48
	ds_read_b128 v[206:209], v145 offset:23552
	global_load_lds_dwordx4 v160, s[8:9]
	s_add_i32 m0, s48, 0x2000
	ds_read_b128 v[202:205], v145 offset:22528
	global_load_lds_dwordx4 v132, s[8:9]
	s_mov_b32 m0, s29
	ds_read_b128 v[198:201], v145 offset:21504
	global_load_lds_dwordx4 v128, s[14:15]
	s_mov_b32 m0, s30
	ds_read_b128 v[194:197], v145 offset:20480
	global_load_lds_dwordx4 v130, s[14:15]
	s_waitcnt vmcnt(8)
	s_waitcnt lgkmcnt(0)
	s_barrier
	v_mfma_f32_16x16x32_bf16 v[60:63], v[138:141], v[178:181], v[60:63]
	v_mfma_f32_16x16x32_bf16 v[56:59], v[150:153], v[178:181], v[56:59]
	v_mfma_f32_16x16x32_bf16 v[44:47], v[138:141], v[186:189], v[44:47]
	v_mfma_f32_16x16x32_bf16 v[40:43], v[150:153], v[186:189], v[40:43]
	v_mfma_f32_16x16x32_bf16 v[28:31], v[138:141], v[194:197], v[28:31]
	v_mfma_f32_16x16x32_bf16 v[24:27], v[150:153], v[194:197], v[24:27]
	v_mfma_f32_16x16x32_bf16 v[12:15], v[138:141], v[202:205], v[12:15]
	v_mfma_f32_16x16x32_bf16 v[8:11], v[150:153], v[202:205], v[8:11]
	v_mfma_f32_16x16x32_bf16 v[60:63], v[146:149], v[182:185], v[60:63]
	v_mfma_f32_16x16x32_bf16 v[56:59], v[154:157], v[182:185], v[56:59]
	v_mfma_f32_16x16x32_bf16 v[44:47], v[146:149], v[190:193], v[44:47]
	v_mfma_f32_16x16x32_bf16 v[40:43], v[154:157], v[190:193], v[40:43]
	v_mfma_f32_16x16x32_bf16 v[28:31], v[146:149], v[198:201], v[28:31]
	v_mfma_f32_16x16x32_bf16 v[24:27], v[154:157], v[198:201], v[24:27]
	v_mfma_f32_16x16x32_bf16 v[12:15], v[146:149], v[206:209], v[12:15]
	v_mfma_f32_16x16x32_bf16 v[8:11], v[154:157], v[206:209], v[8:11]
	v_mfma_f32_16x16x32_bf16 v[52:55], v[162:165], v[178:181], v[52:55]
	v_mfma_f32_16x16x32_bf16 v[48:51], v[170:173], v[178:181], v[48:51]
	v_mfma_f32_16x16x32_bf16 v[36:39], v[162:165], v[186:189], v[36:39]
	v_mfma_f32_16x16x32_bf16 v[32:35], v[170:173], v[186:189], v[32:35]
	v_mfma_f32_16x16x32_bf16 v[20:23], v[162:165], v[194:197], v[20:23]
	v_mfma_f32_16x16x32_bf16 v[16:19], v[170:173], v[194:197], v[16:19]
	v_mfma_f32_16x16x32_bf16 v[4:7], v[162:165], v[202:205], v[4:7]
	v_mfma_f32_16x16x32_bf16 v[0:3], v[170:173], v[202:205], v[0:3]
	v_mfma_f32_16x16x32_bf16 v[52:55], v[166:169], v[182:185], v[52:55]
	v_mfma_f32_16x16x32_bf16 v[48:51], v[174:177], v[182:185], v[48:51]
	v_mfma_f32_16x16x32_bf16 v[36:39], v[166:169], v[190:193], v[36:39]
	v_mfma_f32_16x16x32_bf16 v[32:35], v[174:177], v[190:193], v[32:35]
	v_mfma_f32_16x16x32_bf16 v[20:23], v[166:169], v[198:201], v[20:23]
	v_mfma_f32_16x16x32_bf16 v[16:19], v[174:177], v[198:201], v[16:19]
	v_mfma_f32_16x16x32_bf16 v[4:7], v[166:169], v[206:209], v[4:7]
	v_mfma_f32_16x16x32_bf16 v[0:3], v[174:177], v[206:209], v[0:3]
	s_barrier
	s_add_i32 s48, 0, 0x18000
	s_add_i32 s49, 0, 0x1c000
	v_add_u32_e32 v154, s48, v143
	v_add_u32_e32 v174, s49, v143
	ds_read_b128 v[138:141], v154
	ds_read_b128 v[146:149], v154 offset:1024
	ds_read_b128 v[150:153], v154 offset:2048
	ds_read_b128 v[154:157], v154 offset:3072
	ds_read_b128 v[162:165], v174
	ds_read_b128 v[166:169], v174 offset:1024
	ds_read_b128 v[170:173], v174 offset:2048
	ds_read_b128 v[174:177], v174 offset:3072
	s_add_u32 s8, s14, 0xb0000
	s_addc_u32 s9, s15, 0
	s_mov_b32 m0, s31
	ds_read_b128 v[178:181], v145 offset:32768
	ds_read_b128 v[182:185], v145 offset:33792
	ds_read_b128 v[186:189], v145 offset:34816
	ds_read_b128 v[190:193], v145 offset:35840
	ds_read_b128 v[194:197], v145 offset:36864
	ds_read_b128 v[198:201], v145 offset:37888
	ds_read_b128 v[202:205], v145 offset:38912
	global_load_lds_dwordx4 v128, s[8:9]
	s_mov_b32 m0, s33
	ds_read_b128 v[206:209], v145 offset:39936
	global_load_lds_dwordx4 v130, s[8:9]
	s_waitcnt vmcnt(8)
	s_waitcnt lgkmcnt(0)
	s_barrier
	v_mfma_f32_16x16x32_bf16 v[124:127], v[138:141], v[178:181], v[124:127]
	v_mfma_f32_16x16x32_bf16 v[120:123], v[150:153], v[178:181], v[120:123]
	v_mfma_f32_16x16x32_bf16 v[108:111], v[138:141], v[186:189], v[108:111]
	v_mfma_f32_16x16x32_bf16 v[104:107], v[150:153], v[186:189], v[104:107]
	v_mfma_f32_16x16x32_bf16 v[92:95], v[138:141], v[194:197], v[92:95]
	v_mfma_f32_16x16x32_bf16 v[88:91], v[150:153], v[194:197], v[88:91]
	v_mfma_f32_16x16x32_bf16 v[76:79], v[138:141], v[202:205], v[76:79]
	v_mfma_f32_16x16x32_bf16 v[72:75], v[150:153], v[202:205], v[72:75]
	v_mfma_f32_16x16x32_bf16 v[124:127], v[146:149], v[182:185], v[124:127]
	v_mfma_f32_16x16x32_bf16 v[120:123], v[154:157], v[182:185], v[120:123]
	v_mfma_f32_16x16x32_bf16 v[108:111], v[146:149], v[190:193], v[108:111]
	v_mfma_f32_16x16x32_bf16 v[104:107], v[154:157], v[190:193], v[104:107]
	v_mfma_f32_16x16x32_bf16 v[92:95], v[146:149], v[198:201], v[92:95]
	v_mfma_f32_16x16x32_bf16 v[88:91], v[154:157], v[198:201], v[88:91]
	v_mfma_f32_16x16x32_bf16 v[76:79], v[146:149], v[206:209], v[76:79]
	v_mfma_f32_16x16x32_bf16 v[72:75], v[154:157], v[206:209], v[72:75]
	v_mfma_f32_16x16x32_bf16 v[116:119], v[162:165], v[178:181], v[116:119]
	v_mfma_f32_16x16x32_bf16 v[112:115], v[170:173], v[178:181], v[112:115]
	v_mfma_f32_16x16x32_bf16 v[100:103], v[162:165], v[186:189], v[100:103]
	v_mfma_f32_16x16x32_bf16 v[96:99], v[170:173], v[186:189], v[96:99]
	v_mfma_f32_16x16x32_bf16 v[84:87], v[162:165], v[194:197], v[84:87]
	v_mfma_f32_16x16x32_bf16 v[80:83], v[170:173], v[194:197], v[80:83]
	v_mfma_f32_16x16x32_bf16 v[68:71], v[162:165], v[202:205], v[68:71]
	v_mfma_f32_16x16x32_bf16 v[64:67], v[170:173], v[202:205], v[64:67]
	v_mfma_f32_16x16x32_bf16 v[116:119], v[166:169], v[182:185], v[116:119]
	v_mfma_f32_16x16x32_bf16 v[112:115], v[174:177], v[182:185], v[112:115]
	v_mfma_f32_16x16x32_bf16 v[100:103], v[166:169], v[190:193], v[100:103]
	v_mfma_f32_16x16x32_bf16 v[96:99], v[174:177], v[190:193], v[96:99]
	v_mfma_f32_16x16x32_bf16 v[84:87], v[166:169], v[198:201], v[84:87]
	v_mfma_f32_16x16x32_bf16 v[80:83], v[174:177], v[198:201], v[80:83]
	v_mfma_f32_16x16x32_bf16 v[68:71], v[166:169], v[206:209], v[68:71]
	v_mfma_f32_16x16x32_bf16 v[64:67], v[174:177], v[206:209], v[64:67]
	s_barrier
	s_add_i32 s8, s48, s28
	s_add_i32 m0, s8, 0xffffff80
	ds_read_b128 v[178:181], v145 offset:49152
	ds_read_b128 v[182:185], v145 offset:50176
	ds_read_b128 v[186:189], v145 offset:51200
	ds_read_b128 v[190:193], v145 offset:52224
	global_load_lds_dwordx4 v160, s[12:13] offset:128
	s_add_i32 m0, s8, 0x1f80
	s_add_u32 s8, s12, 0xb0080
	s_addc_u32 s9, s13, 0
	global_load_lds_dwordx4 v132, s[12:13] offset:128
	s_add_i32 s12, s49, s28
	s_mov_b32 m0, s12
	ds_read_b128 v[206:209], v145 offset:56320
	global_load_lds_dwordx4 v160, s[8:9]
	s_add_i32 m0, s12, 0x2000
	ds_read_b128 v[202:205], v145 offset:55296
	global_load_lds_dwordx4 v132, s[8:9]
	s_add_i32 m0, s34, 0xffffff80
	ds_read_b128 v[198:201], v145 offset:54272
	global_load_lds_dwordx4 v128, s[14:15] offset:128
	s_add_i32 m0, s35, 0xffffff80
	ds_read_b128 v[194:197], v145 offset:53248
	global_load_lds_dwordx4 v130, s[14:15] offset:128
	s_waitcnt vmcnt(8)
	s_waitcnt lgkmcnt(0)
	s_barrier
	v_mfma_f32_16x16x32_bf16 v[60:63], v[138:141], v[178:181], v[60:63]
	v_mfma_f32_16x16x32_bf16 v[56:59], v[150:153], v[178:181], v[56:59]
	v_mfma_f32_16x16x32_bf16 v[44:47], v[138:141], v[186:189], v[44:47]
	v_mfma_f32_16x16x32_bf16 v[40:43], v[150:153], v[186:189], v[40:43]
	v_mfma_f32_16x16x32_bf16 v[28:31], v[138:141], v[194:197], v[28:31]
	v_mfma_f32_16x16x32_bf16 v[24:27], v[150:153], v[194:197], v[24:27]
	v_mfma_f32_16x16x32_bf16 v[12:15], v[138:141], v[202:205], v[12:15]
	v_mfma_f32_16x16x32_bf16 v[8:11], v[150:153], v[202:205], v[8:11]
	v_mfma_f32_16x16x32_bf16 v[60:63], v[146:149], v[182:185], v[60:63]
	v_mfma_f32_16x16x32_bf16 v[56:59], v[154:157], v[182:185], v[56:59]
	v_mfma_f32_16x16x32_bf16 v[44:47], v[146:149], v[190:193], v[44:47]
	v_mfma_f32_16x16x32_bf16 v[40:43], v[154:157], v[190:193], v[40:43]
	v_mfma_f32_16x16x32_bf16 v[28:31], v[146:149], v[198:201], v[28:31]
	v_mfma_f32_16x16x32_bf16 v[24:27], v[154:157], v[198:201], v[24:27]
	v_mfma_f32_16x16x32_bf16 v[12:15], v[146:149], v[206:209], v[12:15]
	v_mfma_f32_16x16x32_bf16 v[8:11], v[154:157], v[206:209], v[8:11]
	v_mfma_f32_16x16x32_bf16 v[52:55], v[162:165], v[178:181], v[52:55]
	v_mfma_f32_16x16x32_bf16 v[48:51], v[170:173], v[178:181], v[48:51]
	v_mfma_f32_16x16x32_bf16 v[36:39], v[162:165], v[186:189], v[36:39]
	v_mfma_f32_16x16x32_bf16 v[32:35], v[170:173], v[186:189], v[32:35]
	v_mfma_f32_16x16x32_bf16 v[20:23], v[162:165], v[194:197], v[20:23]
	v_mfma_f32_16x16x32_bf16 v[16:19], v[170:173], v[194:197], v[16:19]
	v_mfma_f32_16x16x32_bf16 v[4:7], v[162:165], v[202:205], v[4:7]
	v_mfma_f32_16x16x32_bf16 v[0:3], v[170:173], v[202:205], v[0:3]
	v_mfma_f32_16x16x32_bf16 v[52:55], v[166:169], v[182:185], v[52:55]
	v_mfma_f32_16x16x32_bf16 v[48:51], v[174:177], v[182:185], v[48:51]
	v_mfma_f32_16x16x32_bf16 v[36:39], v[166:169], v[190:193], v[36:39]
	v_mfma_f32_16x16x32_bf16 v[32:35], v[174:177], v[190:193], v[32:35]
	v_mfma_f32_16x16x32_bf16 v[20:23], v[166:169], v[198:201], v[20:23]
	v_mfma_f32_16x16x32_bf16 v[16:19], v[174:177], v[198:201], v[16:19]
	v_mfma_f32_16x16x32_bf16 v[4:7], v[166:169], v[206:209], v[4:7]
	v_mfma_f32_16x16x32_bf16 v[0:3], v[174:177], v[206:209], v[0:3]
	s_barrier
	s_add_i32 s22, s22, 2
	s_add_u32 s21, s21, 0x100
	s_addc_u32 s90, s90, 0
	s_cmp_gt_u32 s22, 41
	s_mov_b64 s[8:9], s[10:11]
	s_cbranch_scc0 .LBB0_38
	v_lshl_add_u32 v140, s44, 8, v142
	v_lshl_or_b32 v138, s45, 8, v144
	v_lshlrev_b32_e32 v139, 12, v140
	v_lshl_add_u32 v139, v138, 2, v139
	v_lshlrev_b32_e32 v141, 11, v140
	v_lshl_add_u32 v138, v138, 1, v141
	s_mov_b64 s[8:9], s[4:5]
	global_load_dwordx4 v[146:149], v138, s[8:9]
	global_load_dwordx4 v[150:153], v138, s[8:9] offset:256
	s_add_u32 s8, s8, 0x8000
	s_addc_u32 s9, s9, 0
	global_load_dwordx4 v[154:157], v138, s[8:9]
	global_load_dwordx4 v[162:165], v138, s[8:9] offset:256
	s_add_u32 s8, s8, 0x8000
	s_addc_u32 s9, s9, 0
	global_load_dwordx4 v[166:169], v138, s[8:9]
	global_load_dwordx4 v[174:177], v138, s[8:9] offset:256
	s_add_u32 s8, s8, 0x8000
	s_addc_u32 s9, s9, 0
	global_load_dwordx4 v[178:181], v138, s[8:9]
	global_load_dwordx4 v[182:185], v138, s[8:9] offset:256
	s_add_u32 s8, s8, 0x28000
	s_addc_u32 s9, s9, 0
	global_load_dwordx4 v[186:189], v138, s[8:9]
	global_load_dwordx4 v[190:193], v138, s[8:9] offset:256
	s_add_u32 s8, s8, 0x8000
	s_addc_u32 s9, s9, 0
	global_load_dwordx4 v[194:197], v138, s[8:9]
	global_load_dwordx4 v[198:201], v138, s[8:9] offset:256
	s_add_u32 s8, s8, 0x8000
	s_addc_u32 s9, s9, 0
	global_load_dwordx4 v[202:205], v138, s[8:9]
	global_load_dwordx4 v[206:209], v138, s[8:9] offset:256
	s_add_u32 s8, s8, 0x8000
	s_addc_u32 s9, s9, 0
	global_load_dwordx4 v[210:213], v138, s[8:9]
	global_load_dwordx4 v[214:217], v138, s[8:9] offset:256
	s_and_b64 vcc, exec, s[6:7]
	s_cbranch_vccz .LBB0_41
	s_barrier

.LBB0_56:
	s_add_u32 s12, s10, 0xfffc0080
	s_addc_u32 s13, s11, -1
	s_add_i32 s48, 0, 0x10000
	s_cmp_eq_u32 s22, 12
	s_cselect_b32 s15, s20, s13
	s_cselect_b32 s14, s37, s12
	s_cselect_b32 s13, s41, s21
	s_cselect_b32 s12, s91, s96
	s_add_i32 s50, 0, 0x14000
	v_add_u32_e32 v154, s48, v147
	v_add_u32_e32 v158, s50, v147
	ds_read_b128 v[138:141], v154
	ds_read_b128 v[142:145], v154 offset:1024
	ds_read_b128 v[150:153], v154 offset:2048
	ds_read_b128 v[154:157], v154 offset:3072
	ds_read_b128 v[162:165], v158
	ds_read_b128 v[166:169], v158 offset:1024
	ds_read_b128 v[170:173], v158 offset:2048
	ds_read_b128 v[174:177], v158 offset:3072
	s_add_i32 m0, s30, 0xc000
	ds_read_b128 v[178:181], v149
	ds_read_b128 v[182:185], v149 offset:1024
	ds_read_b128 v[186:189], v149 offset:2048
	ds_read_b128 v[190:193], v149 offset:3072
	ds_read_b128 v[194:197], v149 offset:4096
	ds_read_b128 v[198:201], v149 offset:5120
	ds_read_b128 v[202:205], v149 offset:6144
	global_load_lds_dwordx4 v136, s[10:11]
	s_add_i32 m0, s30, 0xe000
	ds_read_b128 v[206:209], v149 offset:7168
	global_load_lds_dwordx4 v134, s[10:11]
	s_waitcnt vmcnt(8)
	s_waitcnt lgkmcnt(0)
	s_barrier
	v_mfma_f32_16x16x32_bf16 v[124:127], v[138:141], v[178:181], v[124:127]
	v_mfma_f32_16x16x32_bf16 v[116:119], v[150:153], v[178:181], v[116:119]
	v_mfma_f32_16x16x32_bf16 v[108:111], v[138:141], v[186:189], v[108:111]
	v_mfma_f32_16x16x32_bf16 v[100:103], v[150:153], v[186:189], v[100:103]
	v_mfma_f32_16x16x32_bf16 v[92:95], v[138:141], v[194:197], v[92:95]
	v_mfma_f32_16x16x32_bf16 v[84:87], v[150:153], v[194:197], v[84:87]
	v_mfma_f32_16x16x32_bf16 v[76:79], v[138:141], v[202:205], v[76:79]
	v_mfma_f32_16x16x32_bf16 v[64:67], v[150:153], v[202:205], v[64:67]
	v_mfma_f32_16x16x32_bf16 v[124:127], v[142:145], v[182:185], v[124:127]
	v_mfma_f32_16x16x32_bf16 v[116:119], v[154:157], v[182:185], v[116:119]
	v_mfma_f32_16x16x32_bf16 v[108:111], v[142:145], v[190:193], v[108:111]
	v_mfma_f32_16x16x32_bf16 v[100:103], v[154:157], v[190:193], v[100:103]
	v_mfma_f32_16x16x32_bf16 v[92:95], v[142:145], v[198:201], v[92:95]
	v_mfma_f32_16x16x32_bf16 v[84:87], v[154:157], v[198:201], v[84:87]
	v_mfma_f32_16x16x32_bf16 v[76:79], v[142:145], v[206:209], v[76:79]
	v_mfma_f32_16x16x32_bf16 v[64:67], v[154:157], v[206:209], v[64:67]
	v_mfma_f32_16x16x32_bf16 v[120:123], v[162:165], v[178:181], v[120:123]
	v_mfma_f32_16x16x32_bf16 v[112:115], v[170:173], v[178:181], v[112:115]
	v_mfma_f32_16x16x32_bf16 v[104:107], v[162:165], v[186:189], v[104:107]
	v_mfma_f32_16x16x32_bf16 v[96:99], v[170:173], v[186:189], v[96:99]
	v_mfma_f32_16x16x32_bf16 v[88:91], v[162:165], v[194:197], v[88:91]
	v_mfma_f32_16x16x32_bf16 v[80:83], v[170:173], v[194:197], v[80:83]
	v_mfma_f32_16x16x32_bf16 v[72:75], v[162:165], v[202:205], v[72:75]
	v_mfma_f32_16x16x32_bf16 v[68:71], v[170:173], v[202:205], v[68:71]
	v_mfma_f32_16x16x32_bf16 v[120:123], v[166:169], v[182:185], v[120:123]
	v_mfma_f32_16x16x32_bf16 v[112:115], v[174:177], v[182:185], v[112:115]
	v_mfma_f32_16x16x32_bf16 v[104:107], v[166:169], v[190:193], v[104:107]
	v_mfma_f32_16x16x32_bf16 v[96:99], v[174:177], v[190:193], v[96:99]
	v_mfma_f32_16x16x32_bf16 v[88:91], v[166:169], v[198:201], v[88:91]
	v_mfma_f32_16x16x32_bf16 v[80:83], v[174:177], v[198:201], v[80:83]
	v_mfma_f32_16x16x32_bf16 v[72:75], v[166:169], v[206:209], v[72:75]
	v_mfma_f32_16x16x32_bf16 v[68:71], v[174:177], v[206:209], v[68:71]
	s_barrier
	s_add_i32 s48, s48, s28
	s_mov_b32 m0, s48
	ds_read_b128 v[178:181], v149 offset:16384
	ds_read_b128 v[182:185], v149 offset:17408
	ds_read_b128 v[186:189], v149 offset:18432
	ds_read_b128 v[190:193], v149 offset:19456
	global_load_lds_dwordx4 v160, s[12:13]
	s_add_i32 m0, s48, 0x2000
	s_add_u32 s48, s12, 0x40000
	s_addc_u32 s49, s13, 0
	s_add_i32 s50, s50, s28
	global_load_lds_dwordx4 v128, s[12:13]
	s_mov_b32 m0, s50
	ds_read_b128 v[206:209], v149 offset:23552
	global_load_lds_dwordx4 v160, s[48:49]
	s_add_i32 m0, s50, 0x2000
	ds_read_b128 v[202:205], v149 offset:22528
	global_load_lds_dwordx4 v128, s[48:49]
	s_mov_b32 m0, s30
	ds_read_b128 v[198:201], v149 offset:21504
	global_load_lds_dwordx4 v132, s[14:15]
	s_mov_b32 m0, s31
	ds_read_b128 v[194:197], v149 offset:20480
	global_load_lds_dwordx4 v130, s[14:15]
	s_waitcnt vmcnt(8)
	s_waitcnt lgkmcnt(0)
	s_barrier
	v_mfma_f32_16x16x32_bf16 v[60:63], v[138:141], v[178:181], v[60:63]
	v_mfma_f32_16x16x32_bf16 v[48:51], v[150:153], v[178:181], v[48:51]
	v_mfma_f32_16x16x32_bf16 v[44:47], v[138:141], v[186:189], v[44:47]
	v_mfma_f32_16x16x32_bf16 v[32:35], v[150:153], v[186:189], v[32:35]
	v_mfma_f32_16x16x32_bf16 v[28:31], v[138:141], v[194:197], v[28:31]
	v_mfma_f32_16x16x32_bf16 v[16:19], v[150:153], v[194:197], v[16:19]
	v_mfma_f32_16x16x32_bf16 v[12:15], v[138:141], v[202:205], v[12:15]
	v_mfma_f32_16x16x32_bf16 v[0:3], v[150:153], v[202:205], v[0:3]
	v_mfma_f32_16x16x32_bf16 v[60:63], v[142:145], v[182:185], v[60:63]
	v_mfma_f32_16x16x32_bf16 v[48:51], v[154:157], v[182:185], v[48:51]
	v_mfma_f32_16x16x32_bf16 v[44:47], v[142:145], v[190:193], v[44:47]
	v_mfma_f32_16x16x32_bf16 v[32:35], v[154:157], v[190:193], v[32:35]
	v_mfma_f32_16x16x32_bf16 v[28:31], v[142:145], v[198:201], v[28:31]
	v_mfma_f32_16x16x32_bf16 v[16:19], v[154:157], v[198:201], v[16:19]
	v_mfma_f32_16x16x32_bf16 v[12:15], v[142:145], v[206:209], v[12:15]
	v_mfma_f32_16x16x32_bf16 v[0:3], v[154:157], v[206:209], v[0:3]
	v_mfma_f32_16x16x32_bf16 v[56:59], v[162:165], v[178:181], v[56:59]
	v_mfma_f32_16x16x32_bf16 v[52:55], v[170:173], v[178:181], v[52:55]
	v_mfma_f32_16x16x32_bf16 v[40:43], v[162:165], v[186:189], v[40:43]
	v_mfma_f32_16x16x32_bf16 v[36:39], v[170:173], v[186:189], v[36:39]
	v_mfma_f32_16x16x32_bf16 v[24:27], v[162:165], v[194:197], v[24:27]
	v_mfma_f32_16x16x32_bf16 v[20:23], v[170:173], v[194:197], v[20:23]
	v_mfma_f32_16x16x32_bf16 v[8:11], v[162:165], v[202:205], v[8:11]
	v_mfma_f32_16x16x32_bf16 v[4:7], v[170:173], v[202:205], v[4:7]
	v_mfma_f32_16x16x32_bf16 v[56:59], v[166:169], v[182:185], v[56:59]
	v_mfma_f32_16x16x32_bf16 v[52:55], v[174:177], v[182:185], v[52:55]
	v_mfma_f32_16x16x32_bf16 v[40:43], v[166:169], v[190:193], v[40:43]
	v_mfma_f32_16x16x32_bf16 v[36:39], v[174:177], v[190:193], v[36:39]
	v_mfma_f32_16x16x32_bf16 v[24:27], v[166:169], v[198:201], v[24:27]
	v_mfma_f32_16x16x32_bf16 v[20:23], v[174:177], v[198:201], v[20:23]
	v_mfma_f32_16x16x32_bf16 v[8:11], v[166:169], v[206:209], v[8:11]
	v_mfma_f32_16x16x32_bf16 v[4:7], v[174:177], v[206:209], v[4:7]
	s_barrier
	s_add_i32 s48, 0, 0x18000
	s_add_i32 s49, 0, 0x1c000
	v_add_u32_e32 v154, s48, v147
	v_add_u32_e32 v174, s49, v147
	ds_read_b128 v[138:141], v154
	ds_read_b128 v[142:145], v154 offset:1024
	ds_read_b128 v[150:153], v154 offset:2048
	ds_read_b128 v[154:157], v154 offset:3072
	ds_read_b128 v[162:165], v174
	ds_read_b128 v[166:169], v174 offset:1024
	ds_read_b128 v[170:173], v174 offset:2048
	ds_read_b128 v[174:177], v174 offset:3072
	s_mov_b64 s[100:101], s[14:15]
	s_add_u32 s14, s14, 0x40000
	s_addc_u32 s15, s15, 0
	s_mov_b32 m0, s33
	ds_read_b128 v[178:181], v149 offset:32768
	ds_read_b128 v[182:185], v149 offset:33792
	ds_read_b128 v[186:189], v149 offset:34816
	ds_read_b128 v[190:193], v149 offset:35840
	ds_read_b128 v[194:197], v149 offset:36864
	ds_read_b128 v[198:201], v149 offset:37888
	ds_read_b128 v[202:205], v149 offset:38912
	global_load_lds_dwordx4 v132, s[14:15]
	s_mov_b32 m0, s34
	ds_read_b128 v[206:209], v149 offset:39936
	global_load_lds_dwordx4 v130, s[14:15]
	s_waitcnt vmcnt(8)
	s_waitcnt lgkmcnt(0)
	s_barrier
	v_mfma_f32_16x16x32_bf16 v[124:127], v[138:141], v[178:181], v[124:127]
	v_mfma_f32_16x16x32_bf16 v[116:119], v[150:153], v[178:181], v[116:119]
	v_mfma_f32_16x16x32_bf16 v[108:111], v[138:141], v[186:189], v[108:111]
	v_mfma_f32_16x16x32_bf16 v[100:103], v[150:153], v[186:189], v[100:103]
	v_mfma_f32_16x16x32_bf16 v[92:95], v[138:141], v[194:197], v[92:95]
	v_mfma_f32_16x16x32_bf16 v[84:87], v[150:153], v[194:197], v[84:87]
	v_mfma_f32_16x16x32_bf16 v[76:79], v[138:141], v[202:205], v[76:79]
	v_mfma_f32_16x16x32_bf16 v[64:67], v[150:153], v[202:205], v[64:67]
	v_mfma_f32_16x16x32_bf16 v[124:127], v[142:145], v[182:185], v[124:127]
	v_mfma_f32_16x16x32_bf16 v[116:119], v[154:157], v[182:185], v[116:119]
	v_mfma_f32_16x16x32_bf16 v[108:111], v[142:145], v[190:193], v[108:111]
	v_mfma_f32_16x16x32_bf16 v[100:103], v[154:157], v[190:193], v[100:103]
	v_mfma_f32_16x16x32_bf16 v[92:95], v[142:145], v[198:201], v[92:95]
	v_mfma_f32_16x16x32_bf16 v[84:87], v[154:157], v[198:201], v[84:87]
	v_mfma_f32_16x16x32_bf16 v[76:79], v[142:145], v[206:209], v[76:79]
	v_mfma_f32_16x16x32_bf16 v[64:67], v[154:157], v[206:209], v[64:67]
	v_mfma_f32_16x16x32_bf16 v[120:123], v[162:165], v[178:181], v[120:123]
	v_mfma_f32_16x16x32_bf16 v[112:115], v[170:173], v[178:181], v[112:115]
	v_mfma_f32_16x16x32_bf16 v[104:107], v[162:165], v[186:189], v[104:107]
	v_mfma_f32_16x16x32_bf16 v[96:99], v[170:173], v[186:189], v[96:99]
	v_mfma_f32_16x16x32_bf16 v[88:91], v[162:165], v[194:197], v[88:91]
	v_mfma_f32_16x16x32_bf16 v[80:83], v[170:173], v[194:197], v[80:83]
	v_mfma_f32_16x16x32_bf16 v[72:75], v[162:165], v[202:205], v[72:75]
	v_mfma_f32_16x16x32_bf16 v[68:71], v[170:173], v[202:205], v[68:71]
	v_mfma_f32_16x16x32_bf16 v[120:123], v[166:169], v[182:185], v[120:123]
	v_mfma_f32_16x16x32_bf16 v[112:115], v[174:177], v[182:185], v[112:115]
	v_mfma_f32_16x16x32_bf16 v[104:107], v[166:169], v[190:193], v[104:107]
	v_mfma_f32_16x16x32_bf16 v[96:99], v[174:177], v[190:193], v[96:99]
	v_mfma_f32_16x16x32_bf16 v[88:91], v[166:169], v[198:201], v[88:91]
	v_mfma_f32_16x16x32_bf16 v[80:83], v[174:177], v[198:201], v[80:83]
	v_mfma_f32_16x16x32_bf16 v[72:75], v[166:169], v[206:209], v[72:75]
	v_mfma_f32_16x16x32_bf16 v[68:71], v[174:177], v[206:209], v[68:71]
	s_barrier
	s_add_i32 s14, s48, s28
	s_add_i32 m0, s14, 0xffffff80
	ds_read_b128 v[178:181], v149 offset:49152
	ds_read_b128 v[182:185], v149 offset:50176
	ds_read_b128 v[186:189], v149 offset:51200
	global_load_lds_dwordx4 v160, s[12:13] offset:128
	s_add_i32 m0, s14, 0x1f80
	ds_read_b128 v[206:209], v149 offset:56320
	global_load_lds_dwordx4 v128, s[12:13] offset:128
	s_add_u32 s12, s12, 0x40080
	s_addc_u32 s13, s13, 0
	s_add_i32 s14, s49, s28
	s_mov_b32 m0, s14
	ds_read_b128 v[202:205], v149 offset:55296
	global_load_lds_dwordx4 v160, s[12:13]
	s_add_i32 m0, s14, 0x2000
	ds_read_b128 v[198:201], v149 offset:54272
	global_load_lds_dwordx4 v128, s[12:13]
	s_add_i32 m0, s35, 0xffffff80
	ds_read_b128 v[194:197], v149 offset:53248
	global_load_lds_dwordx4 v132, s[100:101] offset:128
	s_add_i32 m0, s90, 0xffffff80
	ds_read_b128 v[190:193], v149 offset:52224
	global_load_lds_dwordx4 v130, s[100:101] offset:128
	s_waitcnt vmcnt(8)
	s_waitcnt lgkmcnt(0)
	s_barrier
	v_mfma_f32_16x16x32_bf16 v[60:63], v[138:141], v[178:181], v[60:63]
	v_mfma_f32_16x16x32_bf16 v[48:51], v[150:153], v[178:181], v[48:51]
	v_mfma_f32_16x16x32_bf16 v[44:47], v[138:141], v[186:189], v[44:47]
	v_mfma_f32_16x16x32_bf16 v[32:35], v[150:153], v[186:189], v[32:35]
	v_mfma_f32_16x16x32_bf16 v[28:31], v[138:141], v[194:197], v[28:31]
	v_mfma_f32_16x16x32_bf16 v[16:19], v[150:153], v[194:197], v[16:19]
	v_mfma_f32_16x16x32_bf16 v[12:15], v[138:141], v[202:205], v[12:15]
	v_mfma_f32_16x16x32_bf16 v[0:3], v[150:153], v[202:205], v[0:3]
	v_mfma_f32_16x16x32_bf16 v[60:63], v[142:145], v[182:185], v[60:63]
	v_mfma_f32_16x16x32_bf16 v[48:51], v[154:157], v[182:185], v[48:51]
	v_mfma_f32_16x16x32_bf16 v[44:47], v[142:145], v[190:193], v[44:47]
	v_mfma_f32_16x16x32_bf16 v[32:35], v[154:157], v[190:193], v[32:35]
	v_mfma_f32_16x16x32_bf16 v[28:31], v[142:145], v[198:201], v[28:31]
	v_mfma_f32_16x16x32_bf16 v[16:19], v[154:157], v[198:201], v[16:19]
	v_mfma_f32_16x16x32_bf16 v[12:15], v[142:145], v[206:209], v[12:15]
	v_mfma_f32_16x16x32_bf16 v[0:3], v[154:157], v[206:209], v[0:3]
	v_mfma_f32_16x16x32_bf16 v[56:59], v[162:165], v[178:181], v[56:59]
	v_mfma_f32_16x16x32_bf16 v[52:55], v[170:173], v[178:181], v[52:55]
	v_mfma_f32_16x16x32_bf16 v[40:43], v[162:165], v[186:189], v[40:43]
	v_mfma_f32_16x16x32_bf16 v[36:39], v[170:173], v[186:189], v[36:39]
	v_mfma_f32_16x16x32_bf16 v[24:27], v[162:165], v[194:197], v[24:27]
	v_mfma_f32_16x16x32_bf16 v[20:23], v[170:173], v[194:197], v[20:23]
	v_mfma_f32_16x16x32_bf16 v[8:11], v[162:165], v[202:205], v[8:11]
	v_mfma_f32_16x16x32_bf16 v[4:7], v[170:173], v[202:205], v[4:7]
	v_mfma_f32_16x16x32_bf16 v[56:59], v[166:169], v[182:185], v[56:59]
	v_mfma_f32_16x16x32_bf16 v[52:55], v[174:177], v[182:185], v[52:55]
	v_mfma_f32_16x16x32_bf16 v[40:43], v[166:169], v[190:193], v[40:43]
	v_mfma_f32_16x16x32_bf16 v[36:39], v[174:177], v[190:193], v[36:39]
	v_mfma_f32_16x16x32_bf16 v[24:27], v[166:169], v[198:201], v[24:27]
	v_mfma_f32_16x16x32_bf16 v[20:23], v[174:177], v[198:201], v[20:23]
	v_mfma_f32_16x16x32_bf16 v[8:11], v[166:169], v[206:209], v[8:11]
	v_mfma_f32_16x16x32_bf16 v[4:7], v[174:177], v[206:209], v[4:7]
	s_barrier
	s_add_i32 s22, s22, 2
	s_add_u32 s96, s96, 0x100
	s_addc_u32 s21, s21, 0
	s_add_u32 s10, s10, 0x100
	s_addc_u32 s11, s11, 0
	s_cmp_gt_u32 s22, 13
	s_cbranch_scc0 .LBB0_56
	v_lshl_add_u32 v192, s8, 8, v146
	v_lshlrev_b32_e32 v192, 3, v192
	global_load_dwordx2 v[176:177], v192, s[4:5]
	global_load_dwordx2 v[178:179], v192, s[4:5] offset:128
	global_load_dwordx2 v[180:181], v192, s[4:5] offset:256
	global_load_dwordx2 v[182:183], v192, s[4:5] offset:384
	global_load_dwordx2 v[184:185], v192, s[4:5] offset:1024
	global_load_dwordx2 v[186:187], v192, s[4:5] offset:1152
	global_load_dwordx2 v[188:189], v192, s[4:5] offset:1280
	global_load_dwordx2 v[190:191], v192, s[4:5] offset:1408
	s_and_b64 vcc, exec, s[6:7]
	s_cbranch_vccz .LBB0_59
	s_barrier

.LBB0_84:
	s_add_u32 s12, vcc_lo, 0xfffc0080
	s_addc_u32 s13, vcc_hi, -1
	s_add_i32 s48, 0, 0x10000
	s_cmp_eq_u32 s22, 12
	s_cselect_b32 s15, s9, s13
	s_cselect_b32 s14, s20, s12
	s_cselect_b32 s13, s37, s21
	s_cselect_b32 s12, s45, s90
	s_add_i32 s50, 0, 0x14000
	v_add_u32_e32 v154, s48, v143
	v_add_u32_e32 v158, s50, v143
	ds_read_b128 v[138:141], v154
	ds_read_b128 v[146:149], v154 offset:1024
	ds_read_b128 v[150:153], v154 offset:2048
	ds_read_b128 v[154:157], v154 offset:3072
	ds_read_b128 v[162:165], v158
	ds_read_b128 v[166:169], v158 offset:1024
	ds_read_b128 v[170:173], v158 offset:2048
	ds_read_b128 v[174:177], v158 offset:3072
	s_add_i32 m0, s11, 0xc000
	ds_read_b128 v[178:181], v145
	ds_read_b128 v[182:185], v145 offset:1024
	ds_read_b128 v[186:189], v145 offset:2048
	ds_read_b128 v[190:193], v145 offset:3072
	ds_read_b128 v[194:197], v145 offset:4096
	ds_read_b128 v[198:201], v145 offset:5120
	ds_read_b128 v[202:205], v145 offset:6144
	global_load_lds_dwordx4 v136, vcc
	s_add_i32 m0, s11, 0xe000
	ds_read_b128 v[206:209], v145 offset:7168
	global_load_lds_dwordx4 v134, vcc
	s_waitcnt vmcnt(8)
	s_waitcnt lgkmcnt(0)
	s_barrier
	v_mfma_f32_16x16x32_bf16 v[124:127], v[138:141], v[178:181], v[124:127]
	v_mfma_f32_16x16x32_bf16 v[120:123], v[150:153], v[178:181], v[120:123]
	v_mfma_f32_16x16x32_bf16 v[108:111], v[138:141], v[186:189], v[108:111]
	v_mfma_f32_16x16x32_bf16 v[104:107], v[150:153], v[186:189], v[104:107]
	v_mfma_f32_16x16x32_bf16 v[92:95], v[138:141], v[194:197], v[92:95]
	v_mfma_f32_16x16x32_bf16 v[88:91], v[150:153], v[194:197], v[88:91]
	v_mfma_f32_16x16x32_bf16 v[76:79], v[138:141], v[202:205], v[76:79]
	v_mfma_f32_16x16x32_bf16 v[72:75], v[150:153], v[202:205], v[72:75]
	v_mfma_f32_16x16x32_bf16 v[124:127], v[146:149], v[182:185], v[124:127]
	v_mfma_f32_16x16x32_bf16 v[120:123], v[154:157], v[182:185], v[120:123]
	v_mfma_f32_16x16x32_bf16 v[108:111], v[146:149], v[190:193], v[108:111]
	v_mfma_f32_16x16x32_bf16 v[104:107], v[154:157], v[190:193], v[104:107]
	v_mfma_f32_16x16x32_bf16 v[92:95], v[146:149], v[198:201], v[92:95]
	v_mfma_f32_16x16x32_bf16 v[88:91], v[154:157], v[198:201], v[88:91]
	v_mfma_f32_16x16x32_bf16 v[76:79], v[146:149], v[206:209], v[76:79]
	v_mfma_f32_16x16x32_bf16 v[72:75], v[154:157], v[206:209], v[72:75]
	v_mfma_f32_16x16x32_bf16 v[116:119], v[162:165], v[178:181], v[116:119]
	v_mfma_f32_16x16x32_bf16 v[112:115], v[170:173], v[178:181], v[112:115]
	v_mfma_f32_16x16x32_bf16 v[100:103], v[162:165], v[186:189], v[100:103]
	v_mfma_f32_16x16x32_bf16 v[96:99], v[170:173], v[186:189], v[96:99]
	v_mfma_f32_16x16x32_bf16 v[84:87], v[162:165], v[194:197], v[84:87]
	v_mfma_f32_16x16x32_bf16 v[80:83], v[170:173], v[194:197], v[80:83]
	v_mfma_f32_16x16x32_bf16 v[68:71], v[162:165], v[202:205], v[68:71]
	v_mfma_f32_16x16x32_bf16 v[64:67], v[170:173], v[202:205], v[64:67]
	v_mfma_f32_16x16x32_bf16 v[116:119], v[166:169], v[182:185], v[116:119]
	v_mfma_f32_16x16x32_bf16 v[112:115], v[174:177], v[182:185], v[112:115]
	v_mfma_f32_16x16x32_bf16 v[100:103], v[166:169], v[190:193], v[100:103]
	v_mfma_f32_16x16x32_bf16 v[96:99], v[174:177], v[190:193], v[96:99]
	v_mfma_f32_16x16x32_bf16 v[84:87], v[166:169], v[198:201], v[84:87]
	v_mfma_f32_16x16x32_bf16 v[80:83], v[174:177], v[198:201], v[80:83]
	v_mfma_f32_16x16x32_bf16 v[68:71], v[166:169], v[206:209], v[68:71]
	v_mfma_f32_16x16x32_bf16 v[64:67], v[174:177], v[206:209], v[64:67]
	s_barrier
	s_add_i32 s48, s48, s28
	s_mov_b32 m0, s48
	ds_read_b128 v[178:181], v145 offset:16384
	ds_read_b128 v[182:185], v145 offset:17408
	ds_read_b128 v[186:189], v145 offset:18432
	ds_read_b128 v[190:193], v145 offset:19456
	global_load_lds_dwordx4 v160, s[12:13]
	s_add_i32 m0, s48, 0x2000
	s_add_u32 s48, s12, 0x40000
	s_addc_u32 s49, s13, 0
	s_add_i32 s50, s50, s28
	global_load_lds_dwordx4 v132, s[12:13]
	s_mov_b32 m0, s50
	ds_read_b128 v[206:209], v145 offset:23552
	global_load_lds_dwordx4 v160, s[48:49]
	s_add_i32 m0, s50, 0x2000
	ds_read_b128 v[202:205], v145 offset:22528
	global_load_lds_dwordx4 v132, s[48:49]
	s_mov_b32 m0, s11
	ds_read_b128 v[198:201], v145 offset:21504
	global_load_lds_dwordx4 v128, s[14:15]
	s_mov_b32 m0, s29
	ds_read_b128 v[194:197], v145 offset:20480
	global_load_lds_dwordx4 v130, s[14:15]
	s_waitcnt vmcnt(8)
	s_waitcnt lgkmcnt(0)
	s_barrier
	v_mfma_f32_16x16x32_bf16 v[60:63], v[138:141], v[178:181], v[60:63]
	v_mfma_f32_16x16x32_bf16 v[56:59], v[150:153], v[178:181], v[56:59]
	v_mfma_f32_16x16x32_bf16 v[44:47], v[138:141], v[186:189], v[44:47]
	v_mfma_f32_16x16x32_bf16 v[40:43], v[150:153], v[186:189], v[40:43]
	v_mfma_f32_16x16x32_bf16 v[28:31], v[138:141], v[194:197], v[28:31]
	v_mfma_f32_16x16x32_bf16 v[24:27], v[150:153], v[194:197], v[24:27]
	v_mfma_f32_16x16x32_bf16 v[12:15], v[138:141], v[202:205], v[12:15]
	v_mfma_f32_16x16x32_bf16 v[8:11], v[150:153], v[202:205], v[8:11]
	v_mfma_f32_16x16x32_bf16 v[60:63], v[146:149], v[182:185], v[60:63]
	v_mfma_f32_16x16x32_bf16 v[56:59], v[154:157], v[182:185], v[56:59]
	v_mfma_f32_16x16x32_bf16 v[44:47], v[146:149], v[190:193], v[44:47]
	v_mfma_f32_16x16x32_bf16 v[40:43], v[154:157], v[190:193], v[40:43]
	v_mfma_f32_16x16x32_bf16 v[28:31], v[146:149], v[198:201], v[28:31]
	v_mfma_f32_16x16x32_bf16 v[24:27], v[154:157], v[198:201], v[24:27]
	v_mfma_f32_16x16x32_bf16 v[12:15], v[146:149], v[206:209], v[12:15]
	v_mfma_f32_16x16x32_bf16 v[8:11], v[154:157], v[206:209], v[8:11]
	v_mfma_f32_16x16x32_bf16 v[52:55], v[162:165], v[178:181], v[52:55]
	v_mfma_f32_16x16x32_bf16 v[48:51], v[170:173], v[178:181], v[48:51]
	v_mfma_f32_16x16x32_bf16 v[36:39], v[162:165], v[186:189], v[36:39]
	v_mfma_f32_16x16x32_bf16 v[32:35], v[170:173], v[186:189], v[32:35]
	v_mfma_f32_16x16x32_bf16 v[20:23], v[162:165], v[194:197], v[20:23]
	v_mfma_f32_16x16x32_bf16 v[16:19], v[170:173], v[194:197], v[16:19]
	v_mfma_f32_16x16x32_bf16 v[4:7], v[162:165], v[202:205], v[4:7]
	v_mfma_f32_16x16x32_bf16 v[0:3], v[170:173], v[202:205], v[0:3]
	v_mfma_f32_16x16x32_bf16 v[52:55], v[166:169], v[182:185], v[52:55]
	v_mfma_f32_16x16x32_bf16 v[48:51], v[174:177], v[182:185], v[48:51]
	v_mfma_f32_16x16x32_bf16 v[36:39], v[166:169], v[190:193], v[36:39]
	v_mfma_f32_16x16x32_bf16 v[32:35], v[174:177], v[190:193], v[32:35]
	v_mfma_f32_16x16x32_bf16 v[20:23], v[166:169], v[198:201], v[20:23]
	v_mfma_f32_16x16x32_bf16 v[16:19], v[174:177], v[198:201], v[16:19]
	v_mfma_f32_16x16x32_bf16 v[4:7], v[166:169], v[206:209], v[4:7]
	v_mfma_f32_16x16x32_bf16 v[0:3], v[174:177], v[206:209], v[0:3]
	s_barrier
	s_add_i32 s48, 0, 0x18000
	s_add_i32 s49, 0, 0x1c000
	v_add_u32_e32 v154, s48, v143
	v_add_u32_e32 v174, s49, v143
	ds_read_b128 v[138:141], v154
	ds_read_b128 v[146:149], v154 offset:1024
	ds_read_b128 v[150:153], v154 offset:2048
	ds_read_b128 v[154:157], v154 offset:3072
	ds_read_b128 v[162:165], v174
	ds_read_b128 v[166:169], v174 offset:1024
	ds_read_b128 v[170:173], v174 offset:2048
	ds_read_b128 v[174:177], v174 offset:3072
	s_mov_b64 s[100:101], s[14:15]
	s_add_u32 s14, s14, 0x40000
	s_addc_u32 s15, s15, 0
	s_mov_b32 m0, s30
	ds_read_b128 v[178:181], v145 offset:32768
	ds_read_b128 v[182:185], v145 offset:33792
	ds_read_b128 v[186:189], v145 offset:34816
	ds_read_b128 v[190:193], v145 offset:35840
	ds_read_b128 v[194:197], v145 offset:36864
	ds_read_b128 v[198:201], v145 offset:37888
	ds_read_b128 v[202:205], v145 offset:38912
	global_load_lds_dwordx4 v128, s[14:15]
	s_mov_b32 m0, s31
	ds_read_b128 v[206:209], v145 offset:39936
	global_load_lds_dwordx4 v130, s[14:15]
	s_waitcnt vmcnt(8)
	s_waitcnt lgkmcnt(0)
	s_barrier
	v_mfma_f32_16x16x32_bf16 v[124:127], v[138:141], v[178:181], v[124:127]
	v_mfma_f32_16x16x32_bf16 v[120:123], v[150:153], v[178:181], v[120:123]
	v_mfma_f32_16x16x32_bf16 v[108:111], v[138:141], v[186:189], v[108:111]
	v_mfma_f32_16x16x32_bf16 v[104:107], v[150:153], v[186:189], v[104:107]
	v_mfma_f32_16x16x32_bf16 v[92:95], v[138:141], v[194:197], v[92:95]
	v_mfma_f32_16x16x32_bf16 v[88:91], v[150:153], v[194:197], v[88:91]
	v_mfma_f32_16x16x32_bf16 v[76:79], v[138:141], v[202:205], v[76:79]
	v_mfma_f32_16x16x32_bf16 v[72:75], v[150:153], v[202:205], v[72:75]
	v_mfma_f32_16x16x32_bf16 v[124:127], v[146:149], v[182:185], v[124:127]
	v_mfma_f32_16x16x32_bf16 v[120:123], v[154:157], v[182:185], v[120:123]
	v_mfma_f32_16x16x32_bf16 v[108:111], v[146:149], v[190:193], v[108:111]
	v_mfma_f32_16x16x32_bf16 v[104:107], v[154:157], v[190:193], v[104:107]
	v_mfma_f32_16x16x32_bf16 v[92:95], v[146:149], v[198:201], v[92:95]
	v_mfma_f32_16x16x32_bf16 v[88:91], v[154:157], v[198:201], v[88:91]
	v_mfma_f32_16x16x32_bf16 v[76:79], v[146:149], v[206:209], v[76:79]
	v_mfma_f32_16x16x32_bf16 v[72:75], v[154:157], v[206:209], v[72:75]
	v_mfma_f32_16x16x32_bf16 v[116:119], v[162:165], v[178:181], v[116:119]
	v_mfma_f32_16x16x32_bf16 v[112:115], v[170:173], v[178:181], v[112:115]
	v_mfma_f32_16x16x32_bf16 v[100:103], v[162:165], v[186:189], v[100:103]
	v_mfma_f32_16x16x32_bf16 v[96:99], v[170:173], v[186:189], v[96:99]
	v_mfma_f32_16x16x32_bf16 v[84:87], v[162:165], v[194:197], v[84:87]
	v_mfma_f32_16x16x32_bf16 v[80:83], v[170:173], v[194:197], v[80:83]
	v_mfma_f32_16x16x32_bf16 v[68:71], v[162:165], v[202:205], v[68:71]
	v_mfma_f32_16x16x32_bf16 v[64:67], v[170:173], v[202:205], v[64:67]
	v_mfma_f32_16x16x32_bf16 v[116:119], v[166:169], v[182:185], v[116:119]
	v_mfma_f32_16x16x32_bf16 v[112:115], v[174:177], v[182:185], v[112:115]
	v_mfma_f32_16x16x32_bf16 v[100:103], v[166:169], v[190:193], v[100:103]
	v_mfma_f32_16x16x32_bf16 v[96:99], v[174:177], v[190:193], v[96:99]
	v_mfma_f32_16x16x32_bf16 v[84:87], v[166:169], v[198:201], v[84:87]
	v_mfma_f32_16x16x32_bf16 v[80:83], v[174:177], v[198:201], v[80:83]
	v_mfma_f32_16x16x32_bf16 v[68:71], v[166:169], v[206:209], v[68:71]
	v_mfma_f32_16x16x32_bf16 v[64:67], v[174:177], v[206:209], v[64:67]
	s_barrier
	s_add_i32 s14, s48, s28
	s_add_i32 m0, s14, 0xffffff80
	ds_read_b128 v[178:181], v145 offset:49152
	ds_read_b128 v[182:185], v145 offset:50176
	ds_read_b128 v[186:189], v145 offset:51200
	global_load_lds_dwordx4 v160, s[12:13] offset:128
	s_add_i32 m0, s14, 0x1f80
	ds_read_b128 v[206:209], v145 offset:56320
	global_load_lds_dwordx4 v132, s[12:13] offset:128
	s_add_u32 s12, s12, 0x40080
	s_addc_u32 s13, s13, 0
	s_add_i32 s14, s49, s28
	s_mov_b32 m0, s14
	ds_read_b128 v[202:205], v145 offset:55296
	global_load_lds_dwordx4 v160, s[12:13]
	s_add_i32 m0, s14, 0x2000
	ds_read_b128 v[198:201], v145 offset:54272
	global_load_lds_dwordx4 v132, s[12:13]
	s_add_i32 m0, s33, 0xffffff80
	ds_read_b128 v[194:197], v145 offset:53248
	global_load_lds_dwordx4 v128, s[100:101] offset:128
	s_add_i32 m0, s34, 0xffffff80
	ds_read_b128 v[190:193], v145 offset:52224
	global_load_lds_dwordx4 v130, s[100:101] offset:128
	s_waitcnt vmcnt(8)
	s_waitcnt lgkmcnt(0)
	s_barrier
	v_mfma_f32_16x16x32_bf16 v[60:63], v[138:141], v[178:181], v[60:63]
	v_mfma_f32_16x16x32_bf16 v[56:59], v[150:153], v[178:181], v[56:59]
	v_mfma_f32_16x16x32_bf16 v[44:47], v[138:141], v[186:189], v[44:47]
	v_mfma_f32_16x16x32_bf16 v[40:43], v[150:153], v[186:189], v[40:43]
	v_mfma_f32_16x16x32_bf16 v[28:31], v[138:141], v[194:197], v[28:31]
	v_mfma_f32_16x16x32_bf16 v[24:27], v[150:153], v[194:197], v[24:27]
	v_mfma_f32_16x16x32_bf16 v[12:15], v[138:141], v[202:205], v[12:15]
	v_mfma_f32_16x16x32_bf16 v[8:11], v[150:153], v[202:205], v[8:11]
	v_mfma_f32_16x16x32_bf16 v[60:63], v[146:149], v[182:185], v[60:63]
	v_mfma_f32_16x16x32_bf16 v[56:59], v[154:157], v[182:185], v[56:59]
	v_mfma_f32_16x16x32_bf16 v[44:47], v[146:149], v[190:193], v[44:47]
	v_mfma_f32_16x16x32_bf16 v[40:43], v[154:157], v[190:193], v[40:43]
	v_mfma_f32_16x16x32_bf16 v[28:31], v[146:149], v[198:201], v[28:31]
	v_mfma_f32_16x16x32_bf16 v[24:27], v[154:157], v[198:201], v[24:27]
	v_mfma_f32_16x16x32_bf16 v[12:15], v[146:149], v[206:209], v[12:15]
	v_mfma_f32_16x16x32_bf16 v[8:11], v[154:157], v[206:209], v[8:11]
	v_mfma_f32_16x16x32_bf16 v[52:55], v[162:165], v[178:181], v[52:55]
	v_mfma_f32_16x16x32_bf16 v[48:51], v[170:173], v[178:181], v[48:51]
	v_mfma_f32_16x16x32_bf16 v[36:39], v[162:165], v[186:189], v[36:39]
	v_mfma_f32_16x16x32_bf16 v[32:35], v[170:173], v[186:189], v[32:35]
	v_mfma_f32_16x16x32_bf16 v[20:23], v[162:165], v[194:197], v[20:23]
	v_mfma_f32_16x16x32_bf16 v[16:19], v[170:173], v[194:197], v[16:19]
	v_mfma_f32_16x16x32_bf16 v[4:7], v[162:165], v[202:205], v[4:7]
	v_mfma_f32_16x16x32_bf16 v[0:3], v[170:173], v[202:205], v[0:3]
	v_mfma_f32_16x16x32_bf16 v[52:55], v[166:169], v[182:185], v[52:55]
	v_mfma_f32_16x16x32_bf16 v[48:51], v[174:177], v[182:185], v[48:51]
	v_mfma_f32_16x16x32_bf16 v[36:39], v[166:169], v[190:193], v[36:39]
	v_mfma_f32_16x16x32_bf16 v[32:35], v[174:177], v[190:193], v[32:35]
	v_mfma_f32_16x16x32_bf16 v[20:23], v[166:169], v[198:201], v[20:23]
	v_mfma_f32_16x16x32_bf16 v[16:19], v[174:177], v[198:201], v[16:19]
	v_mfma_f32_16x16x32_bf16 v[4:7], v[166:169], v[206:209], v[4:7]
	v_mfma_f32_16x16x32_bf16 v[0:3], v[174:177], v[206:209], v[0:3]
	s_barrier
	s_add_i32 s22, s22, 2
	s_add_u32 s90, s90, 0x100
	s_addc_u32 s21, s21, 0
	s_add_u32 vcc_lo, vcc_lo, 0x100
	s_addc_u32 vcc_hi, vcc_hi, 0
	s_cmp_gt_u32 s22, 13
	s_cbranch_scc0 .LBB0_84
	v_lshl_add_u32 v140, s8, 8, v142
	v_lshl_or_b32 v138, s10, 8, v144
	v_lshlrev_b32_e32 v141, 11, v140
	v_lshl_add_u32 v138, v138, 1, v141
	v_lshlrev_b32_e32 v139, 3, v140
	s_mov_b64 s[8:9], s[2:3]
	global_load_dwordx4 v[146:149], v138, s[8:9]
	global_load_dwordx4 v[150:153], v138, s[8:9] offset:256
	s_add_u32 s8, s8, 0x8000
	s_addc_u32 s9, s9, 0
	global_load_dwordx4 v[154:157], v138, s[8:9]
	global_load_dwordx4 v[162:165], v138, s[8:9] offset:256
	s_add_u32 s8, s8, 0x8000
	s_addc_u32 s9, s9, 0
	global_load_dwordx4 v[166:169], v138, s[8:9]
	global_load_dwordx4 v[174:177], v138, s[8:9] offset:256
	s_add_u32 s8, s8, 0x8000
	s_addc_u32 s9, s9, 0
	global_load_dwordx4 v[178:181], v138, s[8:9]
	global_load_dwordx4 v[182:185], v138, s[8:9] offset:256
	s_add_u32 s8, s8, 0x28000
	s_addc_u32 s9, s9, 0
	global_load_dwordx4 v[186:189], v138, s[8:9]
	global_load_dwordx4 v[190:193], v138, s[8:9] offset:256
	s_add_u32 s8, s8, 0x8000
	s_addc_u32 s9, s9, 0
	global_load_dwordx4 v[194:197], v138, s[8:9]
	global_load_dwordx4 v[198:201], v138, s[8:9] offset:256
	s_add_u32 s8, s8, 0x8000
	s_addc_u32 s9, s9, 0
	global_load_dwordx4 v[202:205], v138, s[8:9]
	global_load_dwordx4 v[206:209], v138, s[8:9] offset:256
	s_add_u32 s8, s8, 0x8000
	s_addc_u32 s9, s9, 0
	global_load_dwordx4 v[210:213], v138, s[8:9]
	global_load_dwordx4 v[214:217], v138, s[8:9] offset:256
	s_and_b64 vcc, exec, s[6:7]
	s_cbranch_vccz .LBB0_87
	s_barrier

.LBB0_139:
	s_add_u32 s14, s10, 0xfffc0080
	s_addc_u32 s15, s11, -1
	s_add_i32 s48, 0, 0x10000
	s_cmp_eq_u32 s22, 12
	s_cselect_b32 s93, s9, s15
	s_cselect_b32 s92, s41, s14
	s_cselect_b32 s15, s45, s21
	s_cselect_b32 s14, vcc_lo, vcc_hi
	s_add_i32 s50, 0, 0x14000
	v_add_u32_e32 v140, s48, v202
	v_add_u32_e32 v156, s50, v202
	ds_read_b128 v[128:131], v140
	ds_read_b128 v[132:135], v140 offset:1024
	ds_read_b128 v[136:139], v140 offset:2048
	ds_read_b128 v[140:143], v140 offset:3072
	ds_read_b128 v[144:147], v156
	ds_read_b128 v[148:151], v156 offset:1024
	ds_read_b128 v[152:155], v156 offset:2048
	ds_read_b128 v[156:159], v156 offset:3072
	s_add_i32 m0, s31, 0xc000
	ds_read_b128 v[188:191], v204
	ds_read_b128 v[192:195], v204 offset:1024
	ds_read_b128 v[196:199], v204 offset:2048
	ds_read_b128 v[206:209], v204 offset:3072
	ds_read_b128 v[210:213], v204 offset:4096
	ds_read_b128 v[214:217], v204 offset:5120
	ds_read_b128 v[238:241], v204 offset:6144
	global_load_lds_dwordx4 v186, s[10:11]
	s_add_i32 m0, s31, 0xe000
	ds_read_b128 v[246:249], v204 offset:7168
	global_load_lds_dwordx4 v184, s[10:11]
	s_waitcnt vmcnt(8)
	s_waitcnt lgkmcnt(0)
	s_barrier
	v_mfma_f32_16x16x32_bf16 v[124:127], v[128:131], v[188:191], v[124:127]
	v_mfma_f32_16x16x32_bf16 v[120:123], v[136:139], v[188:191], v[120:123]
	v_mfma_f32_16x16x32_bf16 v[108:111], v[128:131], v[196:199], v[108:111]
	v_mfma_f32_16x16x32_bf16 v[104:107], v[136:139], v[196:199], v[104:107]
	v_mfma_f32_16x16x32_bf16 v[92:95], v[128:131], v[210:213], v[92:95]
	v_mfma_f32_16x16x32_bf16 v[88:91], v[136:139], v[210:213], v[88:91]
	v_mfma_f32_16x16x32_bf16 v[76:79], v[128:131], v[238:241], v[76:79]
	v_mfma_f32_16x16x32_bf16 v[72:75], v[136:139], v[238:241], v[72:75]
	v_mfma_f32_16x16x32_bf16 v[124:127], v[132:135], v[192:195], v[124:127]
	v_mfma_f32_16x16x32_bf16 v[120:123], v[140:143], v[192:195], v[120:123]
	v_mfma_f32_16x16x32_bf16 v[108:111], v[132:135], v[206:209], v[108:111]
	v_mfma_f32_16x16x32_bf16 v[104:107], v[140:143], v[206:209], v[104:107]
	v_mfma_f32_16x16x32_bf16 v[92:95], v[132:135], v[214:217], v[92:95]
	v_mfma_f32_16x16x32_bf16 v[88:91], v[140:143], v[214:217], v[88:91]
	v_mfma_f32_16x16x32_bf16 v[76:79], v[132:135], v[246:249], v[76:79]
	v_mfma_f32_16x16x32_bf16 v[72:75], v[140:143], v[246:249], v[72:75]
	v_mfma_f32_16x16x32_bf16 v[116:119], v[144:147], v[188:191], v[116:119]
	v_mfma_f32_16x16x32_bf16 v[112:115], v[152:155], v[188:191], v[112:115]
	v_mfma_f32_16x16x32_bf16 v[100:103], v[144:147], v[196:199], v[100:103]
	v_mfma_f32_16x16x32_bf16 v[96:99], v[152:155], v[196:199], v[96:99]
	v_mfma_f32_16x16x32_bf16 v[84:87], v[144:147], v[210:213], v[84:87]
	v_mfma_f32_16x16x32_bf16 v[80:83], v[152:155], v[210:213], v[80:83]
	v_mfma_f32_16x16x32_bf16 v[68:71], v[144:147], v[238:241], v[68:71]
	v_mfma_f32_16x16x32_bf16 v[64:67], v[152:155], v[238:241], v[64:67]
	v_mfma_f32_16x16x32_bf16 v[116:119], v[148:151], v[192:195], v[116:119]
	v_mfma_f32_16x16x32_bf16 v[112:115], v[156:159], v[192:195], v[112:115]
	v_mfma_f32_16x16x32_bf16 v[100:103], v[148:151], v[206:209], v[100:103]
	v_mfma_f32_16x16x32_bf16 v[96:99], v[156:159], v[206:209], v[96:99]
	v_mfma_f32_16x16x32_bf16 v[84:87], v[148:151], v[214:217], v[84:87]
	v_mfma_f32_16x16x32_bf16 v[80:83], v[156:159], v[214:217], v[80:83]
	v_mfma_f32_16x16x32_bf16 v[68:71], v[148:151], v[246:249], v[68:71]
	v_mfma_f32_16x16x32_bf16 v[64:67], v[156:159], v[246:249], v[64:67]
	s_barrier
	s_add_i32 s48, s48, s29
	s_mov_b32 m0, s48
	ds_read_b128 v[188:191], v204 offset:16384
	ds_read_b128 v[192:195], v204 offset:17408
	ds_read_b128 v[196:199], v204 offset:18432
	ds_read_b128 v[206:209], v204 offset:19456
	global_load_lds_dwordx4 v178, s[14:15]
	s_add_i32 m0, s48, 0x2000
	s_add_u32 s48, s14, 0x40000
	s_addc_u32 s49, s15, 0
	s_add_i32 s50, s50, s29
	global_load_lds_dwordx4 v174, s[14:15]
	s_mov_b32 m0, s50
	ds_read_b128 v[246:249], v204 offset:23552
	global_load_lds_dwordx4 v178, s[48:49]
	s_add_i32 m0, s50, 0x2000
	ds_read_b128 v[238:241], v204 offset:22528
	global_load_lds_dwordx4 v174, s[48:49]
	s_mov_b32 m0, s31
	ds_read_b128 v[214:217], v204 offset:21504
	global_load_lds_dwordx4 v180, s[92:93]
	s_mov_b32 m0, s34
	ds_read_b128 v[210:213], v204 offset:20480
	global_load_lds_dwordx4 v176, s[92:93]
	s_waitcnt vmcnt(8)
	s_waitcnt lgkmcnt(0)
	s_barrier
	v_mfma_f32_16x16x32_bf16 v[60:63], v[128:131], v[188:191], v[60:63]
	v_mfma_f32_16x16x32_bf16 v[56:59], v[136:139], v[188:191], v[56:59]
	v_mfma_f32_16x16x32_bf16 v[44:47], v[128:131], v[196:199], v[44:47]
	v_mfma_f32_16x16x32_bf16 v[40:43], v[136:139], v[196:199], v[40:43]
	v_mfma_f32_16x16x32_bf16 v[28:31], v[128:131], v[210:213], v[28:31]
	v_mfma_f32_16x16x32_bf16 v[24:27], v[136:139], v[210:213], v[24:27]
	v_mfma_f32_16x16x32_bf16 v[12:15], v[128:131], v[238:241], v[12:15]
	v_mfma_f32_16x16x32_bf16 v[8:11], v[136:139], v[238:241], v[8:11]
	v_mfma_f32_16x16x32_bf16 v[60:63], v[132:135], v[192:195], v[60:63]
	v_mfma_f32_16x16x32_bf16 v[56:59], v[140:143], v[192:195], v[56:59]
	v_mfma_f32_16x16x32_bf16 v[44:47], v[132:135], v[206:209], v[44:47]
	v_mfma_f32_16x16x32_bf16 v[40:43], v[140:143], v[206:209], v[40:43]
	v_mfma_f32_16x16x32_bf16 v[28:31], v[132:135], v[214:217], v[28:31]
	v_mfma_f32_16x16x32_bf16 v[24:27], v[140:143], v[214:217], v[24:27]
	v_mfma_f32_16x16x32_bf16 v[12:15], v[132:135], v[246:249], v[12:15]
	v_mfma_f32_16x16x32_bf16 v[8:11], v[140:143], v[246:249], v[8:11]
	v_mfma_f32_16x16x32_bf16 v[52:55], v[144:147], v[188:191], v[52:55]
	v_mfma_f32_16x16x32_bf16 v[48:51], v[152:155], v[188:191], v[48:51]
	v_mfma_f32_16x16x32_bf16 v[36:39], v[144:147], v[196:199], v[36:39]
	v_mfma_f32_16x16x32_bf16 v[32:35], v[152:155], v[196:199], v[32:35]
	v_mfma_f32_16x16x32_bf16 v[20:23], v[144:147], v[210:213], v[20:23]
	v_mfma_f32_16x16x32_bf16 v[16:19], v[152:155], v[210:213], v[16:19]
	v_mfma_f32_16x16x32_bf16 v[4:7], v[144:147], v[238:241], v[4:7]
	v_mfma_f32_16x16x32_bf16 v[0:3], v[152:155], v[238:241], v[0:3]
	v_mfma_f32_16x16x32_bf16 v[52:55], v[148:151], v[192:195], v[52:55]
	v_mfma_f32_16x16x32_bf16 v[48:51], v[156:159], v[192:195], v[48:51]
	v_mfma_f32_16x16x32_bf16 v[36:39], v[148:151], v[206:209], v[36:39]
	v_mfma_f32_16x16x32_bf16 v[32:35], v[156:159], v[206:209], v[32:35]
	v_mfma_f32_16x16x32_bf16 v[20:23], v[148:151], v[214:217], v[20:23]
	v_mfma_f32_16x16x32_bf16 v[16:19], v[156:159], v[214:217], v[16:19]
	v_mfma_f32_16x16x32_bf16 v[4:7], v[148:151], v[246:249], v[4:7]
	v_mfma_f32_16x16x32_bf16 v[0:3], v[156:159], v[246:249], v[0:3]
	s_barrier
	s_add_i32 s50, 0, 0x18000
	s_add_i32 s51, 0, 0x1c000
	v_add_u32_e32 v140, s50, v202
	v_add_u32_e32 v156, s51, v202
	ds_read_b128 v[128:131], v140
	ds_read_b128 v[132:135], v140 offset:1024
	ds_read_b128 v[136:139], v140 offset:2048
	ds_read_b128 v[140:143], v140 offset:3072
	ds_read_b128 v[144:147], v156
	ds_read_b128 v[148:151], v156 offset:1024
	ds_read_b128 v[152:155], v156 offset:2048
	ds_read_b128 v[156:159], v156 offset:3072
	s_add_u32 s48, s92, 0x40000
	s_addc_u32 s49, s93, 0
	s_mov_b32 m0, s35
	ds_read_b128 v[188:191], v204 offset:32768
	ds_read_b128 v[192:195], v204 offset:33792
	ds_read_b128 v[196:199], v204 offset:34816
	ds_read_b128 v[206:209], v204 offset:35840
	ds_read_b128 v[210:213], v204 offset:36864
	ds_read_b128 v[214:217], v204 offset:37888
	ds_read_b128 v[238:241], v204 offset:38912
	global_load_lds_dwordx4 v180, s[48:49]
	s_mov_b32 m0, s90
	ds_read_b128 v[246:249], v204 offset:39936
	global_load_lds_dwordx4 v176, s[48:49]
	s_waitcnt vmcnt(8)
	s_waitcnt lgkmcnt(0)
	s_barrier
	v_mfma_f32_16x16x32_bf16 v[124:127], v[128:131], v[188:191], v[124:127]
	v_mfma_f32_16x16x32_bf16 v[120:123], v[136:139], v[188:191], v[120:123]
	v_mfma_f32_16x16x32_bf16 v[108:111], v[128:131], v[196:199], v[108:111]
	v_mfma_f32_16x16x32_bf16 v[104:107], v[136:139], v[196:199], v[104:107]
	v_mfma_f32_16x16x32_bf16 v[92:95], v[128:131], v[210:213], v[92:95]
	v_mfma_f32_16x16x32_bf16 v[88:91], v[136:139], v[210:213], v[88:91]
	v_mfma_f32_16x16x32_bf16 v[76:79], v[128:131], v[238:241], v[76:79]
	v_mfma_f32_16x16x32_bf16 v[72:75], v[136:139], v[238:241], v[72:75]
	v_mfma_f32_16x16x32_bf16 v[124:127], v[132:135], v[192:195], v[124:127]
	v_mfma_f32_16x16x32_bf16 v[120:123], v[140:143], v[192:195], v[120:123]
	v_mfma_f32_16x16x32_bf16 v[108:111], v[132:135], v[206:209], v[108:111]
	v_mfma_f32_16x16x32_bf16 v[104:107], v[140:143], v[206:209], v[104:107]
	v_mfma_f32_16x16x32_bf16 v[92:95], v[132:135], v[214:217], v[92:95]
	v_mfma_f32_16x16x32_bf16 v[88:91], v[140:143], v[214:217], v[88:91]
	v_mfma_f32_16x16x32_bf16 v[76:79], v[132:135], v[246:249], v[76:79]
	v_mfma_f32_16x16x32_bf16 v[72:75], v[140:143], v[246:249], v[72:75]
	v_mfma_f32_16x16x32_bf16 v[116:119], v[144:147], v[188:191], v[116:119]
	v_mfma_f32_16x16x32_bf16 v[112:115], v[152:155], v[188:191], v[112:115]
	v_mfma_f32_16x16x32_bf16 v[100:103], v[144:147], v[196:199], v[100:103]
	v_mfma_f32_16x16x32_bf16 v[96:99], v[152:155], v[196:199], v[96:99]
	v_mfma_f32_16x16x32_bf16 v[84:87], v[144:147], v[210:213], v[84:87]
	v_mfma_f32_16x16x32_bf16 v[80:83], v[152:155], v[210:213], v[80:83]
	v_mfma_f32_16x16x32_bf16 v[68:71], v[144:147], v[238:241], v[68:71]
	v_mfma_f32_16x16x32_bf16 v[64:67], v[152:155], v[238:241], v[64:67]
	v_mfma_f32_16x16x32_bf16 v[116:119], v[148:151], v[192:195], v[116:119]
	v_mfma_f32_16x16x32_bf16 v[112:115], v[156:159], v[192:195], v[112:115]
	v_mfma_f32_16x16x32_bf16 v[100:103], v[148:151], v[206:209], v[100:103]
	v_mfma_f32_16x16x32_bf16 v[96:99], v[156:159], v[206:209], v[96:99]
	v_mfma_f32_16x16x32_bf16 v[84:87], v[148:151], v[214:217], v[84:87]
	v_mfma_f32_16x16x32_bf16 v[80:83], v[156:159], v[214:217], v[80:83]
	v_mfma_f32_16x16x32_bf16 v[68:71], v[148:151], v[246:249], v[68:71]
	v_mfma_f32_16x16x32_bf16 v[64:67], v[156:159], v[246:249], v[64:67]
	s_barrier
	s_add_i32 s48, s50, s29
	s_add_i32 m0, s48, 0xffffff80
	ds_read_b128 v[188:191], v204 offset:49152
	ds_read_b128 v[192:195], v204 offset:50176
	ds_read_b128 v[196:199], v204 offset:51200
	global_load_lds_dwordx4 v178, s[14:15] offset:128
	s_add_i32 m0, s48, 0x1f80
	ds_read_b128 v[246:249], v204 offset:56320
	global_load_lds_dwordx4 v174, s[14:15] offset:128
	s_add_u32 s14, s14, 0x40080
	s_addc_u32 s15, s15, 0
	s_add_i32 s48, s51, s29
	s_mov_b32 m0, s48
	ds_read_b128 v[238:241], v204 offset:55296
	global_load_lds_dwordx4 v178, s[14:15]
	s_add_i32 m0, s48, 0x2000
	ds_read_b128 v[214:217], v204 offset:54272
	global_load_lds_dwordx4 v174, s[14:15]
	s_add_i32 m0, s19, 0xffffff80
	ds_read_b128 v[210:213], v204 offset:53248
	global_load_lds_dwordx4 v180, s[92:93] offset:128
	s_add_i32 m0, s33, 0xffffff80
	ds_read_b128 v[206:209], v204 offset:52224
	global_load_lds_dwordx4 v176, s[92:93] offset:128
	s_waitcnt vmcnt(8)
	s_waitcnt lgkmcnt(0)
	s_barrier
	v_mfma_f32_16x16x32_bf16 v[60:63], v[128:131], v[188:191], v[60:63]
	v_mfma_f32_16x16x32_bf16 v[56:59], v[136:139], v[188:191], v[56:59]
	v_mfma_f32_16x16x32_bf16 v[44:47], v[128:131], v[196:199], v[44:47]
	v_mfma_f32_16x16x32_bf16 v[40:43], v[136:139], v[196:199], v[40:43]
	v_mfma_f32_16x16x32_bf16 v[28:31], v[128:131], v[210:213], v[28:31]
	v_mfma_f32_16x16x32_bf16 v[24:27], v[136:139], v[210:213], v[24:27]
	v_mfma_f32_16x16x32_bf16 v[12:15], v[128:131], v[238:241], v[12:15]
	v_mfma_f32_16x16x32_bf16 v[8:11], v[136:139], v[238:241], v[8:11]
	v_mfma_f32_16x16x32_bf16 v[60:63], v[132:135], v[192:195], v[60:63]
	v_mfma_f32_16x16x32_bf16 v[56:59], v[140:143], v[192:195], v[56:59]
	v_mfma_f32_16x16x32_bf16 v[44:47], v[132:135], v[206:209], v[44:47]
	v_mfma_f32_16x16x32_bf16 v[40:43], v[140:143], v[206:209], v[40:43]
	v_mfma_f32_16x16x32_bf16 v[28:31], v[132:135], v[214:217], v[28:31]
	v_mfma_f32_16x16x32_bf16 v[24:27], v[140:143], v[214:217], v[24:27]
	v_mfma_f32_16x16x32_bf16 v[12:15], v[132:135], v[246:249], v[12:15]
	v_mfma_f32_16x16x32_bf16 v[8:11], v[140:143], v[246:249], v[8:11]
	v_mfma_f32_16x16x32_bf16 v[52:55], v[144:147], v[188:191], v[52:55]
	v_mfma_f32_16x16x32_bf16 v[48:51], v[152:155], v[188:191], v[48:51]
	v_mfma_f32_16x16x32_bf16 v[36:39], v[144:147], v[196:199], v[36:39]
	v_mfma_f32_16x16x32_bf16 v[32:35], v[152:155], v[196:199], v[32:35]
	v_mfma_f32_16x16x32_bf16 v[20:23], v[144:147], v[210:213], v[20:23]
	v_mfma_f32_16x16x32_bf16 v[16:19], v[152:155], v[210:213], v[16:19]
	v_mfma_f32_16x16x32_bf16 v[4:7], v[144:147], v[238:241], v[4:7]
	v_mfma_f32_16x16x32_bf16 v[0:3], v[152:155], v[238:241], v[0:3]
	v_mfma_f32_16x16x32_bf16 v[52:55], v[148:151], v[192:195], v[52:55]
	v_mfma_f32_16x16x32_bf16 v[48:51], v[156:159], v[192:195], v[48:51]
	v_mfma_f32_16x16x32_bf16 v[36:39], v[148:151], v[206:209], v[36:39]
	v_mfma_f32_16x16x32_bf16 v[32:35], v[156:159], v[206:209], v[32:35]
	v_mfma_f32_16x16x32_bf16 v[20:23], v[148:151], v[214:217], v[20:23]
	v_mfma_f32_16x16x32_bf16 v[16:19], v[156:159], v[214:217], v[16:19]
	v_mfma_f32_16x16x32_bf16 v[4:7], v[148:151], v[246:249], v[4:7]
	v_mfma_f32_16x16x32_bf16 v[0:3], v[156:159], v[246:249], v[0:3]
	s_barrier
	s_add_i32 s22, s22, 2
	s_add_u32 vcc_hi, vcc_hi, 0x100
	s_addc_u32 s21, s21, 0
	s_add_u32 s10, s10, 0x100
	s_addc_u32 s11, s11, 0
	s_cmp_gt_u32 s22, 13
	s_cbranch_scc0 .LBB0_139
	s_and_b64 vcc, exec, s[36:37]
	s_cbranch_vccz .LBB0_142
	s_barrier

.LBB0_178:
	s_add_u32 s10, s8, 0x100
	s_addc_u32 s11, s9, 0
	s_add_i32 s48, 0, 0x10000
	s_cmp_eq_u32 s22, 40
	s_cselect_b32 s15, s1, s11
	s_cselect_b32 s14, s0, s10
	s_cselect_b32 s13, s45, s96
	s_cselect_b32 s12, s44, s21
	s_add_i32 s49, 0, 0x14000
	v_add_u32_e32 v154, s48, v143
	v_add_u32_e32 v158, s49, v143
	ds_read_b128 v[138:141], v154
	ds_read_b128 v[146:149], v154 offset:1024
	ds_read_b128 v[150:153], v154 offset:2048
	ds_read_b128 v[154:157], v154 offset:3072
	ds_read_b128 v[174:177], v158
	ds_read_b128 v[178:181], v158 offset:1024
	ds_read_b128 v[182:185], v158 offset:2048
	ds_read_b128 v[186:189], v158 offset:3072
	s_add_i32 m0, s29, 0xc000
	ds_read_b128 v[190:193], v145
	ds_read_b128 v[194:197], v145 offset:1024
	ds_read_b128 v[198:201], v145 offset:2048
	ds_read_b128 v[202:205], v145 offset:3072
	ds_read_b128 v[206:209], v145 offset:4096
	ds_read_b128 v[210:213], v145 offset:5120
	ds_read_b128 v[214:217], v145 offset:6144
	global_load_lds_dwordx4 v136, s[8:9]
	s_add_i32 m0, s29, 0xe000
	ds_read_b128 v[238:241], v145 offset:7168
	global_load_lds_dwordx4 v134, s[8:9]
	s_waitcnt vmcnt(8)
	s_waitcnt lgkmcnt(0)
	s_barrier
	v_mfma_f32_16x16x32_bf16 v[124:127], v[138:141], v[190:193], v[124:127]
	v_mfma_f32_16x16x32_bf16 v[120:123], v[150:153], v[190:193], v[120:123]
	v_mfma_f32_16x16x32_bf16 v[108:111], v[138:141], v[198:201], v[108:111]
	v_mfma_f32_16x16x32_bf16 v[104:107], v[150:153], v[198:201], v[104:107]
	v_mfma_f32_16x16x32_bf16 v[92:95], v[138:141], v[206:209], v[92:95]
	v_mfma_f32_16x16x32_bf16 v[88:91], v[150:153], v[206:209], v[88:91]
	v_mfma_f32_16x16x32_bf16 v[76:79], v[138:141], v[214:217], v[76:79]
	v_mfma_f32_16x16x32_bf16 v[72:75], v[150:153], v[214:217], v[72:75]
	v_mfma_f32_16x16x32_bf16 v[124:127], v[146:149], v[194:197], v[124:127]
	v_mfma_f32_16x16x32_bf16 v[120:123], v[154:157], v[194:197], v[120:123]
	v_mfma_f32_16x16x32_bf16 v[108:111], v[146:149], v[202:205], v[108:111]
	v_mfma_f32_16x16x32_bf16 v[104:107], v[154:157], v[202:205], v[104:107]
	v_mfma_f32_16x16x32_bf16 v[92:95], v[146:149], v[210:213], v[92:95]
	v_mfma_f32_16x16x32_bf16 v[88:91], v[154:157], v[210:213], v[88:91]
	v_mfma_f32_16x16x32_bf16 v[76:79], v[146:149], v[238:241], v[76:79]
	v_mfma_f32_16x16x32_bf16 v[72:75], v[154:157], v[238:241], v[72:75]
	v_mfma_f32_16x16x32_bf16 v[116:119], v[174:177], v[190:193], v[116:119]
	v_mfma_f32_16x16x32_bf16 v[112:115], v[182:185], v[190:193], v[112:115]
	v_mfma_f32_16x16x32_bf16 v[100:103], v[174:177], v[198:201], v[100:103]
	v_mfma_f32_16x16x32_bf16 v[96:99], v[182:185], v[198:201], v[96:99]
	v_mfma_f32_16x16x32_bf16 v[84:87], v[174:177], v[206:209], v[84:87]
	v_mfma_f32_16x16x32_bf16 v[80:83], v[182:185], v[206:209], v[80:83]
	v_mfma_f32_16x16x32_bf16 v[68:71], v[174:177], v[214:217], v[68:71]
	v_mfma_f32_16x16x32_bf16 v[64:67], v[182:185], v[214:217], v[64:67]
	v_mfma_f32_16x16x32_bf16 v[116:119], v[178:181], v[194:197], v[116:119]
	v_mfma_f32_16x16x32_bf16 v[112:115], v[186:189], v[194:197], v[112:115]
	v_mfma_f32_16x16x32_bf16 v[100:103], v[178:181], v[202:205], v[100:103]
	v_mfma_f32_16x16x32_bf16 v[96:99], v[186:189], v[202:205], v[96:99]
	v_mfma_f32_16x16x32_bf16 v[84:87], v[178:181], v[210:213], v[84:87]
	v_mfma_f32_16x16x32_bf16 v[80:83], v[186:189], v[210:213], v[80:83]
	v_mfma_f32_16x16x32_bf16 v[68:71], v[178:181], v[238:241], v[68:71]
	v_mfma_f32_16x16x32_bf16 v[64:67], v[186:189], v[238:241], v[64:67]
	s_barrier
	s_add_i32 s8, s48, s28
	s_mov_b32 m0, s8
	ds_read_b128 v[190:193], v145 offset:16384
	ds_read_b128 v[194:197], v145 offset:17408
	ds_read_b128 v[198:201], v145 offset:18432
	ds_read_b128 v[202:205], v145 offset:19456
	global_load_lds_dwordx4 v160, s[12:13]
	s_add_i32 m0, s8, 0x2000
	s_add_u32 s8, s12, 0xb0000
	s_addc_u32 s9, s13, 0
	s_add_i32 s48, s49, s28
	global_load_lds_dwordx4 v132, s[12:13]
	s_mov_b32 m0, s48
	ds_read_b128 v[238:241], v145 offset:23552
	global_load_lds_dwordx4 v160, s[8:9]
	s_add_i32 m0, s48, 0x2000
	ds_read_b128 v[214:217], v145 offset:22528
	global_load_lds_dwordx4 v132, s[8:9]
	s_mov_b32 m0, s29
	ds_read_b128 v[210:213], v145 offset:21504
	global_load_lds_dwordx4 v128, s[14:15]
	s_mov_b32 m0, s30
	ds_read_b128 v[206:209], v145 offset:20480
	global_load_lds_dwordx4 v130, s[14:15]
	s_waitcnt vmcnt(8)
	s_waitcnt lgkmcnt(0)
	s_barrier
	v_mfma_f32_16x16x32_bf16 v[60:63], v[138:141], v[190:193], v[60:63]
	v_mfma_f32_16x16x32_bf16 v[56:59], v[150:153], v[190:193], v[56:59]
	v_mfma_f32_16x16x32_bf16 v[44:47], v[138:141], v[198:201], v[44:47]
	v_mfma_f32_16x16x32_bf16 v[40:43], v[150:153], v[198:201], v[40:43]
	v_mfma_f32_16x16x32_bf16 v[28:31], v[138:141], v[206:209], v[28:31]
	v_mfma_f32_16x16x32_bf16 v[24:27], v[150:153], v[206:209], v[24:27]
	v_mfma_f32_16x16x32_bf16 v[12:15], v[138:141], v[214:217], v[12:15]
	v_mfma_f32_16x16x32_bf16 v[8:11], v[150:153], v[214:217], v[8:11]
	v_mfma_f32_16x16x32_bf16 v[60:63], v[146:149], v[194:197], v[60:63]
	v_mfma_f32_16x16x32_bf16 v[56:59], v[154:157], v[194:197], v[56:59]
	v_mfma_f32_16x16x32_bf16 v[44:47], v[146:149], v[202:205], v[44:47]
	v_mfma_f32_16x16x32_bf16 v[40:43], v[154:157], v[202:205], v[40:43]
	v_mfma_f32_16x16x32_bf16 v[28:31], v[146:149], v[210:213], v[28:31]
	v_mfma_f32_16x16x32_bf16 v[24:27], v[154:157], v[210:213], v[24:27]
	v_mfma_f32_16x16x32_bf16 v[12:15], v[146:149], v[238:241], v[12:15]
	v_mfma_f32_16x16x32_bf16 v[8:11], v[154:157], v[238:241], v[8:11]
	v_mfma_f32_16x16x32_bf16 v[52:55], v[174:177], v[190:193], v[52:55]
	v_mfma_f32_16x16x32_bf16 v[48:51], v[182:185], v[190:193], v[48:51]
	v_mfma_f32_16x16x32_bf16 v[36:39], v[174:177], v[198:201], v[36:39]
	v_mfma_f32_16x16x32_bf16 v[32:35], v[182:185], v[198:201], v[32:35]
	v_mfma_f32_16x16x32_bf16 v[20:23], v[174:177], v[206:209], v[20:23]
	v_mfma_f32_16x16x32_bf16 v[16:19], v[182:185], v[206:209], v[16:19]
	v_mfma_f32_16x16x32_bf16 v[4:7], v[174:177], v[214:217], v[4:7]
	v_mfma_f32_16x16x32_bf16 v[0:3], v[182:185], v[214:217], v[0:3]
	v_mfma_f32_16x16x32_bf16 v[52:55], v[178:181], v[194:197], v[52:55]
	v_mfma_f32_16x16x32_bf16 v[48:51], v[186:189], v[194:197], v[48:51]
	v_mfma_f32_16x16x32_bf16 v[36:39], v[178:181], v[202:205], v[36:39]
	v_mfma_f32_16x16x32_bf16 v[32:35], v[186:189], v[202:205], v[32:35]
	v_mfma_f32_16x16x32_bf16 v[20:23], v[178:181], v[210:213], v[20:23]
	v_mfma_f32_16x16x32_bf16 v[16:19], v[186:189], v[210:213], v[16:19]
	v_mfma_f32_16x16x32_bf16 v[4:7], v[178:181], v[238:241], v[4:7]
	v_mfma_f32_16x16x32_bf16 v[0:3], v[186:189], v[238:241], v[0:3]
	s_barrier
	s_add_i32 s48, 0, 0x18000
	s_add_i32 s49, 0, 0x1c000
	v_add_u32_e32 v154, s48, v143
	v_add_u32_e32 v168, s49, v143
	ds_read_b128 v[138:141], v154
	ds_read_b128 v[146:149], v154 offset:1024
	ds_read_b128 v[150:153], v154 offset:2048
	ds_read_b128 v[154:157], v154 offset:3072
	ds_read_b128 v[174:177], v168
	ds_read_b128 v[178:181], v168 offset:1024
	ds_read_b128 v[182:185], v168 offset:2048
	ds_read_b128 v[186:189], v168 offset:3072
	s_add_u32 s8, s14, 0xb0000
	s_addc_u32 s9, s15, 0
	s_mov_b32 m0, s31
	ds_read_b128 v[190:193], v145 offset:32768
	ds_read_b128 v[194:197], v145 offset:33792
	ds_read_b128 v[198:201], v145 offset:34816
	ds_read_b128 v[202:205], v145 offset:35840
	ds_read_b128 v[206:209], v145 offset:36864
	ds_read_b128 v[210:213], v145 offset:37888
	ds_read_b128 v[214:217], v145 offset:38912
	global_load_lds_dwordx4 v128, s[8:9]
	s_mov_b32 m0, s33
	ds_read_b128 v[238:241], v145 offset:39936
	global_load_lds_dwordx4 v130, s[8:9]
	s_waitcnt vmcnt(8)
	s_waitcnt lgkmcnt(0)
	s_barrier
	v_mfma_f32_16x16x32_bf16 v[124:127], v[138:141], v[190:193], v[124:127]
	v_mfma_f32_16x16x32_bf16 v[120:123], v[150:153], v[190:193], v[120:123]
	v_mfma_f32_16x16x32_bf16 v[108:111], v[138:141], v[198:201], v[108:111]
	v_mfma_f32_16x16x32_bf16 v[104:107], v[150:153], v[198:201], v[104:107]
	v_mfma_f32_16x16x32_bf16 v[92:95], v[138:141], v[206:209], v[92:95]
	v_mfma_f32_16x16x32_bf16 v[88:91], v[150:153], v[206:209], v[88:91]
	v_mfma_f32_16x16x32_bf16 v[76:79], v[138:141], v[214:217], v[76:79]
	v_mfma_f32_16x16x32_bf16 v[72:75], v[150:153], v[214:217], v[72:75]
	v_mfma_f32_16x16x32_bf16 v[124:127], v[146:149], v[194:197], v[124:127]
	v_mfma_f32_16x16x32_bf16 v[120:123], v[154:157], v[194:197], v[120:123]
	v_mfma_f32_16x16x32_bf16 v[108:111], v[146:149], v[202:205], v[108:111]
	v_mfma_f32_16x16x32_bf16 v[104:107], v[154:157], v[202:205], v[104:107]
	v_mfma_f32_16x16x32_bf16 v[92:95], v[146:149], v[210:213], v[92:95]
	v_mfma_f32_16x16x32_bf16 v[88:91], v[154:157], v[210:213], v[88:91]
	v_mfma_f32_16x16x32_bf16 v[76:79], v[146:149], v[238:241], v[76:79]
	v_mfma_f32_16x16x32_bf16 v[72:75], v[154:157], v[238:241], v[72:75]
	v_mfma_f32_16x16x32_bf16 v[116:119], v[174:177], v[190:193], v[116:119]
	v_mfma_f32_16x16x32_bf16 v[112:115], v[182:185], v[190:193], v[112:115]
	v_mfma_f32_16x16x32_bf16 v[100:103], v[174:177], v[198:201], v[100:103]
	v_mfma_f32_16x16x32_bf16 v[96:99], v[182:185], v[198:201], v[96:99]
	v_mfma_f32_16x16x32_bf16 v[84:87], v[174:177], v[206:209], v[84:87]
	v_mfma_f32_16x16x32_bf16 v[80:83], v[182:185], v[206:209], v[80:83]
	v_mfma_f32_16x16x32_bf16 v[68:71], v[174:177], v[214:217], v[68:71]
	v_mfma_f32_16x16x32_bf16 v[64:67], v[182:185], v[214:217], v[64:67]
	v_mfma_f32_16x16x32_bf16 v[116:119], v[178:181], v[194:197], v[116:119]
	v_mfma_f32_16x16x32_bf16 v[112:115], v[186:189], v[194:197], v[112:115]
	v_mfma_f32_16x16x32_bf16 v[100:103], v[178:181], v[202:205], v[100:103]
	v_mfma_f32_16x16x32_bf16 v[96:99], v[186:189], v[202:205], v[96:99]
	v_mfma_f32_16x16x32_bf16 v[84:87], v[178:181], v[210:213], v[84:87]
	v_mfma_f32_16x16x32_bf16 v[80:83], v[186:189], v[210:213], v[80:83]
	v_mfma_f32_16x16x32_bf16 v[68:71], v[178:181], v[238:241], v[68:71]
	v_mfma_f32_16x16x32_bf16 v[64:67], v[186:189], v[238:241], v[64:67]
	s_barrier
	s_add_i32 s8, s48, s28
	s_add_i32 m0, s8, 0xffffff80
	ds_read_b128 v[190:193], v145 offset:49152
	ds_read_b128 v[194:197], v145 offset:50176
	ds_read_b128 v[198:201], v145 offset:51200
	ds_read_b128 v[202:205], v145 offset:52224
	global_load_lds_dwordx4 v160, s[12:13] offset:128
	s_add_i32 m0, s8, 0x1f80
	s_add_u32 s8, s12, 0xb0080
	s_addc_u32 s9, s13, 0
	global_load_lds_dwordx4 v132, s[12:13] offset:128
	s_add_i32 s12, s49, s28
	s_mov_b32 m0, s12
	ds_read_b128 v[238:241], v145 offset:56320
	global_load_lds_dwordx4 v160, s[8:9]
	s_add_i32 m0, s12, 0x2000
	ds_read_b128 v[214:217], v145 offset:55296
	global_load_lds_dwordx4 v132, s[8:9]
	s_add_i32 m0, s34, 0xffffff80
	ds_read_b128 v[210:213], v145 offset:54272
	global_load_lds_dwordx4 v128, s[14:15] offset:128
	s_add_i32 m0, s35, 0xffffff80
	ds_read_b128 v[206:209], v145 offset:53248
	global_load_lds_dwordx4 v130, s[14:15] offset:128
	s_waitcnt vmcnt(8)
	s_waitcnt lgkmcnt(0)
	s_barrier
	v_mfma_f32_16x16x32_bf16 v[60:63], v[138:141], v[190:193], v[60:63]
	v_mfma_f32_16x16x32_bf16 v[56:59], v[150:153], v[190:193], v[56:59]
	v_mfma_f32_16x16x32_bf16 v[44:47], v[138:141], v[198:201], v[44:47]
	v_mfma_f32_16x16x32_bf16 v[40:43], v[150:153], v[198:201], v[40:43]
	v_mfma_f32_16x16x32_bf16 v[28:31], v[138:141], v[206:209], v[28:31]
	v_mfma_f32_16x16x32_bf16 v[24:27], v[150:153], v[206:209], v[24:27]
	v_mfma_f32_16x16x32_bf16 v[12:15], v[138:141], v[214:217], v[12:15]
	v_mfma_f32_16x16x32_bf16 v[8:11], v[150:153], v[214:217], v[8:11]
	v_mfma_f32_16x16x32_bf16 v[60:63], v[146:149], v[194:197], v[60:63]
	v_mfma_f32_16x16x32_bf16 v[56:59], v[154:157], v[194:197], v[56:59]
	v_mfma_f32_16x16x32_bf16 v[44:47], v[146:149], v[202:205], v[44:47]
	v_mfma_f32_16x16x32_bf16 v[40:43], v[154:157], v[202:205], v[40:43]
	v_mfma_f32_16x16x32_bf16 v[28:31], v[146:149], v[210:213], v[28:31]
	v_mfma_f32_16x16x32_bf16 v[24:27], v[154:157], v[210:213], v[24:27]
	v_mfma_f32_16x16x32_bf16 v[12:15], v[146:149], v[238:241], v[12:15]
	v_mfma_f32_16x16x32_bf16 v[8:11], v[154:157], v[238:241], v[8:11]
	v_mfma_f32_16x16x32_bf16 v[52:55], v[174:177], v[190:193], v[52:55]
	v_mfma_f32_16x16x32_bf16 v[48:51], v[182:185], v[190:193], v[48:51]
	v_mfma_f32_16x16x32_bf16 v[36:39], v[174:177], v[198:201], v[36:39]
	v_mfma_f32_16x16x32_bf16 v[32:35], v[182:185], v[198:201], v[32:35]
	v_mfma_f32_16x16x32_bf16 v[20:23], v[174:177], v[206:209], v[20:23]
	v_mfma_f32_16x16x32_bf16 v[16:19], v[182:185], v[206:209], v[16:19]
	v_mfma_f32_16x16x32_bf16 v[4:7], v[174:177], v[214:217], v[4:7]
	v_mfma_f32_16x16x32_bf16 v[0:3], v[182:185], v[214:217], v[0:3]
	v_mfma_f32_16x16x32_bf16 v[52:55], v[178:181], v[194:197], v[52:55]
	v_mfma_f32_16x16x32_bf16 v[48:51], v[186:189], v[194:197], v[48:51]
	v_mfma_f32_16x16x32_bf16 v[36:39], v[178:181], v[202:205], v[36:39]
	v_mfma_f32_16x16x32_bf16 v[32:35], v[186:189], v[202:205], v[32:35]
	v_mfma_f32_16x16x32_bf16 v[20:23], v[178:181], v[210:213], v[20:23]
	v_mfma_f32_16x16x32_bf16 v[16:19], v[186:189], v[210:213], v[16:19]
	v_mfma_f32_16x16x32_bf16 v[4:7], v[178:181], v[238:241], v[4:7]
	v_mfma_f32_16x16x32_bf16 v[0:3], v[186:189], v[238:241], v[0:3]
	s_barrier
	s_add_i32 s22, s22, 2
	s_add_u32 s21, s21, 0x100
	s_addc_u32 s96, s96, 0
	s_cmp_gt_u32 s22, 41
	s_mov_b64 s[8:9], s[10:11]
	s_cbranch_scc0 .LBB0_178
	v_lshl_add_u32 v140, s20, 8, v142
	v_lshl_or_b32 v138, s93, 8, v144
	v_lshlrev_b32_e32 v141, 11, v140
	v_lshl_add_u32 v138, v138, 1, v141
	v_lshlrev_b32_e32 v139, 3, v140
	s_mov_b64 s[8:9], s[4:5]
	global_load_dwordx4 v[146:149], v138, s[8:9]
	global_load_dwordx4 v[150:153], v138, s[8:9] offset:256
	s_add_u32 s8, s8, 0x8000
	s_addc_u32 s9, s9, 0
	global_load_dwordx4 v[154:157], v138, s[8:9]
	global_load_dwordx4 v[162:165], v138, s[8:9] offset:256
	s_add_u32 s8, s8, 0x8000
	s_addc_u32 s9, s9, 0
	global_load_dwordx4 v[166:169], v138, s[8:9]
	global_load_dwordx4 v[174:177], v138, s[8:9] offset:256
	s_add_u32 s8, s8, 0x8000
	s_addc_u32 s9, s9, 0
	global_load_dwordx4 v[178:181], v138, s[8:9]
	global_load_dwordx4 v[182:185], v138, s[8:9] offset:256
	s_add_u32 s8, s8, 0x28000
	s_addc_u32 s9, s9, 0
	global_load_dwordx4 v[186:189], v138, s[8:9]
	global_load_dwordx4 v[190:193], v138, s[8:9] offset:256
	s_add_u32 s8, s8, 0x8000
	s_addc_u32 s9, s9, 0
	global_load_dwordx4 v[194:197], v138, s[8:9]
	global_load_dwordx4 v[198:201], v138, s[8:9] offset:256
	s_add_u32 s8, s8, 0x8000
	s_addc_u32 s9, s9, 0
	global_load_dwordx4 v[202:205], v138, s[8:9]
	global_load_dwordx4 v[206:209], v138, s[8:9] offset:256
	s_add_u32 s8, s8, 0x8000
	s_addc_u32 s9, s9, 0
	global_load_dwordx4 v[210:213], v138, s[8:9]
	global_load_dwordx4 v[214:217], v138, s[8:9] offset:256
	s_and_b64 vcc, exec, s[36:37]
	s_cbranch_vccz .LBB0_181
	s_barrier

.LBB0_212:
	s_add_u32 s12, s10, 0xfffc0080
	s_addc_u32 s13, s11, -1
	s_add_i32 s22, 0, 0x10000
	s_cmp_eq_u32 s21, 12
	s_cselect_b32 s15, s20, s13
	s_cselect_b32 s14, s37, s12
	s_cselect_b32 s13, s41, s97
	s_cselect_b32 s12, s91, s96
	s_add_i32 s50, 0, 0x14000
	v_add_u32_e32 v154, s22, v147
	v_add_u32_e32 v158, s50, v147
	ds_read_b128 v[138:141], v154
	ds_read_b128 v[142:145], v154 offset:1024
	ds_read_b128 v[150:153], v154 offset:2048
	ds_read_b128 v[154:157], v154 offset:3072
	ds_read_b128 v[174:177], v158
	ds_read_b128 v[178:181], v158 offset:1024
	ds_read_b128 v[182:185], v158 offset:2048
	ds_read_b128 v[186:189], v158 offset:3072
	s_add_i32 m0, s30, 0xc000
	ds_read_b128 v[190:193], v149
	ds_read_b128 v[194:197], v149 offset:1024
	ds_read_b128 v[198:201], v149 offset:2048
	ds_read_b128 v[202:205], v149 offset:3072
	ds_read_b128 v[206:209], v149 offset:4096
	ds_read_b128 v[210:213], v149 offset:5120
	ds_read_b128 v[214:217], v149 offset:6144
	global_load_lds_dwordx4 v136, s[10:11]
	s_add_i32 m0, s30, 0xe000
	ds_read_b128 v[238:241], v149 offset:7168
	global_load_lds_dwordx4 v134, s[10:11]
	s_waitcnt vmcnt(8)
	s_waitcnt lgkmcnt(0)
	s_barrier
	v_mfma_f32_16x16x32_bf16 v[124:127], v[138:141], v[190:193], v[124:127]
	v_mfma_f32_16x16x32_bf16 v[116:119], v[150:153], v[190:193], v[116:119]
	v_mfma_f32_16x16x32_bf16 v[108:111], v[138:141], v[198:201], v[108:111]
	v_mfma_f32_16x16x32_bf16 v[100:103], v[150:153], v[198:201], v[100:103]
	v_mfma_f32_16x16x32_bf16 v[92:95], v[138:141], v[206:209], v[92:95]
	v_mfma_f32_16x16x32_bf16 v[84:87], v[150:153], v[206:209], v[84:87]
	v_mfma_f32_16x16x32_bf16 v[76:79], v[138:141], v[214:217], v[76:79]
	v_mfma_f32_16x16x32_bf16 v[64:67], v[150:153], v[214:217], v[64:67]
	v_mfma_f32_16x16x32_bf16 v[124:127], v[142:145], v[194:197], v[124:127]
	v_mfma_f32_16x16x32_bf16 v[116:119], v[154:157], v[194:197], v[116:119]
	v_mfma_f32_16x16x32_bf16 v[108:111], v[142:145], v[202:205], v[108:111]
	v_mfma_f32_16x16x32_bf16 v[100:103], v[154:157], v[202:205], v[100:103]
	v_mfma_f32_16x16x32_bf16 v[92:95], v[142:145], v[210:213], v[92:95]
	v_mfma_f32_16x16x32_bf16 v[84:87], v[154:157], v[210:213], v[84:87]
	v_mfma_f32_16x16x32_bf16 v[76:79], v[142:145], v[238:241], v[76:79]
	v_mfma_f32_16x16x32_bf16 v[64:67], v[154:157], v[238:241], v[64:67]
	v_mfma_f32_16x16x32_bf16 v[120:123], v[174:177], v[190:193], v[120:123]
	v_mfma_f32_16x16x32_bf16 v[112:115], v[182:185], v[190:193], v[112:115]
	v_mfma_f32_16x16x32_bf16 v[104:107], v[174:177], v[198:201], v[104:107]
	v_mfma_f32_16x16x32_bf16 v[96:99], v[182:185], v[198:201], v[96:99]
	v_mfma_f32_16x16x32_bf16 v[88:91], v[174:177], v[206:209], v[88:91]
	v_mfma_f32_16x16x32_bf16 v[80:83], v[182:185], v[206:209], v[80:83]
	v_mfma_f32_16x16x32_bf16 v[72:75], v[174:177], v[214:217], v[72:75]
	v_mfma_f32_16x16x32_bf16 v[68:71], v[182:185], v[214:217], v[68:71]
	v_mfma_f32_16x16x32_bf16 v[120:123], v[178:181], v[194:197], v[120:123]
	v_mfma_f32_16x16x32_bf16 v[112:115], v[186:189], v[194:197], v[112:115]
	v_mfma_f32_16x16x32_bf16 v[104:107], v[178:181], v[202:205], v[104:107]
	v_mfma_f32_16x16x32_bf16 v[96:99], v[186:189], v[202:205], v[96:99]
	v_mfma_f32_16x16x32_bf16 v[88:91], v[178:181], v[210:213], v[88:91]
	v_mfma_f32_16x16x32_bf16 v[80:83], v[186:189], v[210:213], v[80:83]
	v_mfma_f32_16x16x32_bf16 v[72:75], v[178:181], v[238:241], v[72:75]
	v_mfma_f32_16x16x32_bf16 v[68:71], v[186:189], v[238:241], v[68:71]
	s_barrier
	s_add_i32 s22, s22, s28
	s_mov_b32 m0, s22
	ds_read_b128 v[190:193], v149 offset:16384
	ds_read_b128 v[194:197], v149 offset:17408
	ds_read_b128 v[198:201], v149 offset:18432
	ds_read_b128 v[202:205], v149 offset:19456
	global_load_lds_dwordx4 v160, s[12:13]
	s_add_i32 m0, s22, 0x2000
	s_add_u32 s48, s12, 0x40000
	s_addc_u32 s49, s13, 0
	s_add_i32 s22, s50, s28
	global_load_lds_dwordx4 v128, s[12:13]
	s_mov_b32 m0, s22
	ds_read_b128 v[238:241], v149 offset:23552
	global_load_lds_dwordx4 v160, s[48:49]
	s_add_i32 m0, s22, 0x2000
	ds_read_b128 v[214:217], v149 offset:22528
	global_load_lds_dwordx4 v128, s[48:49]
	s_mov_b32 m0, s30
	ds_read_b128 v[210:213], v149 offset:21504
	global_load_lds_dwordx4 v132, s[14:15]
	s_mov_b32 m0, s31
	ds_read_b128 v[206:209], v149 offset:20480
	global_load_lds_dwordx4 v130, s[14:15]
	s_waitcnt vmcnt(8)
	s_waitcnt lgkmcnt(0)
	s_barrier
	v_mfma_f32_16x16x32_bf16 v[60:63], v[138:141], v[190:193], v[60:63]
	v_mfma_f32_16x16x32_bf16 v[48:51], v[150:153], v[190:193], v[48:51]
	v_mfma_f32_16x16x32_bf16 v[44:47], v[138:141], v[198:201], v[44:47]
	v_mfma_f32_16x16x32_bf16 v[32:35], v[150:153], v[198:201], v[32:35]
	v_mfma_f32_16x16x32_bf16 v[28:31], v[138:141], v[206:209], v[28:31]
	v_mfma_f32_16x16x32_bf16 v[16:19], v[150:153], v[206:209], v[16:19]
	v_mfma_f32_16x16x32_bf16 v[12:15], v[138:141], v[214:217], v[12:15]
	v_mfma_f32_16x16x32_bf16 v[0:3], v[150:153], v[214:217], v[0:3]
	v_mfma_f32_16x16x32_bf16 v[60:63], v[142:145], v[194:197], v[60:63]
	v_mfma_f32_16x16x32_bf16 v[48:51], v[154:157], v[194:197], v[48:51]
	v_mfma_f32_16x16x32_bf16 v[44:47], v[142:145], v[202:205], v[44:47]
	v_mfma_f32_16x16x32_bf16 v[32:35], v[154:157], v[202:205], v[32:35]
	v_mfma_f32_16x16x32_bf16 v[28:31], v[142:145], v[210:213], v[28:31]
	v_mfma_f32_16x16x32_bf16 v[16:19], v[154:157], v[210:213], v[16:19]
	v_mfma_f32_16x16x32_bf16 v[12:15], v[142:145], v[238:241], v[12:15]
	v_mfma_f32_16x16x32_bf16 v[0:3], v[154:157], v[238:241], v[0:3]
	v_mfma_f32_16x16x32_bf16 v[56:59], v[174:177], v[190:193], v[56:59]
	v_mfma_f32_16x16x32_bf16 v[52:55], v[182:185], v[190:193], v[52:55]
	v_mfma_f32_16x16x32_bf16 v[40:43], v[174:177], v[198:201], v[40:43]
	v_mfma_f32_16x16x32_bf16 v[36:39], v[182:185], v[198:201], v[36:39]
	v_mfma_f32_16x16x32_bf16 v[24:27], v[174:177], v[206:209], v[24:27]
	v_mfma_f32_16x16x32_bf16 v[20:23], v[182:185], v[206:209], v[20:23]
	v_mfma_f32_16x16x32_bf16 v[8:11], v[174:177], v[214:217], v[8:11]
	v_mfma_f32_16x16x32_bf16 v[4:7], v[182:185], v[214:217], v[4:7]
	v_mfma_f32_16x16x32_bf16 v[56:59], v[178:181], v[194:197], v[56:59]
	v_mfma_f32_16x16x32_bf16 v[52:55], v[186:189], v[194:197], v[52:55]
	v_mfma_f32_16x16x32_bf16 v[40:43], v[178:181], v[202:205], v[40:43]
	v_mfma_f32_16x16x32_bf16 v[36:39], v[186:189], v[202:205], v[36:39]
	v_mfma_f32_16x16x32_bf16 v[24:27], v[178:181], v[210:213], v[24:27]
	v_mfma_f32_16x16x32_bf16 v[20:23], v[186:189], v[210:213], v[20:23]
	v_mfma_f32_16x16x32_bf16 v[8:11], v[178:181], v[238:241], v[8:11]
	v_mfma_f32_16x16x32_bf16 v[4:7], v[186:189], v[238:241], v[4:7]
	s_barrier
	s_add_i32 s22, 0, 0x18000
	s_add_i32 s48, 0, 0x1c000
	v_add_u32_e32 v154, s22, v147
	v_add_u32_e32 v168, s48, v147
	ds_read_b128 v[138:141], v154
	ds_read_b128 v[142:145], v154 offset:1024
	ds_read_b128 v[150:153], v154 offset:2048
	ds_read_b128 v[154:157], v154 offset:3072
	ds_read_b128 v[174:177], v168
	ds_read_b128 v[178:181], v168 offset:1024
	ds_read_b128 v[182:185], v168 offset:2048
	ds_read_b128 v[186:189], v168 offset:3072
	s_mov_b64 s[100:101], s[14:15]
	s_add_u32 s14, s14, 0x40000
	s_addc_u32 s15, s15, 0
	s_mov_b32 m0, s33
	ds_read_b128 v[190:193], v149 offset:32768
	ds_read_b128 v[194:197], v149 offset:33792
	ds_read_b128 v[198:201], v149 offset:34816
	ds_read_b128 v[202:205], v149 offset:35840
	ds_read_b128 v[206:209], v149 offset:36864
	ds_read_b128 v[210:213], v149 offset:37888
	ds_read_b128 v[214:217], v149 offset:38912
	global_load_lds_dwordx4 v132, s[14:15]
	s_mov_b32 m0, s34
	ds_read_b128 v[238:241], v149 offset:39936
	global_load_lds_dwordx4 v130, s[14:15]
	s_waitcnt vmcnt(8)
	s_waitcnt lgkmcnt(0)
	s_barrier
	v_mfma_f32_16x16x32_bf16 v[124:127], v[138:141], v[190:193], v[124:127]
	v_mfma_f32_16x16x32_bf16 v[116:119], v[150:153], v[190:193], v[116:119]
	v_mfma_f32_16x16x32_bf16 v[108:111], v[138:141], v[198:201], v[108:111]
	v_mfma_f32_16x16x32_bf16 v[100:103], v[150:153], v[198:201], v[100:103]
	v_mfma_f32_16x16x32_bf16 v[92:95], v[138:141], v[206:209], v[92:95]
	v_mfma_f32_16x16x32_bf16 v[84:87], v[150:153], v[206:209], v[84:87]
	v_mfma_f32_16x16x32_bf16 v[76:79], v[138:141], v[214:217], v[76:79]
	v_mfma_f32_16x16x32_bf16 v[64:67], v[150:153], v[214:217], v[64:67]
	v_mfma_f32_16x16x32_bf16 v[124:127], v[142:145], v[194:197], v[124:127]
	v_mfma_f32_16x16x32_bf16 v[116:119], v[154:157], v[194:197], v[116:119]
	v_mfma_f32_16x16x32_bf16 v[108:111], v[142:145], v[202:205], v[108:111]
	v_mfma_f32_16x16x32_bf16 v[100:103], v[154:157], v[202:205], v[100:103]
	v_mfma_f32_16x16x32_bf16 v[92:95], v[142:145], v[210:213], v[92:95]
	v_mfma_f32_16x16x32_bf16 v[84:87], v[154:157], v[210:213], v[84:87]
	v_mfma_f32_16x16x32_bf16 v[76:79], v[142:145], v[238:241], v[76:79]
	v_mfma_f32_16x16x32_bf16 v[64:67], v[154:157], v[238:241], v[64:67]
	v_mfma_f32_16x16x32_bf16 v[120:123], v[174:177], v[190:193], v[120:123]
	v_mfma_f32_16x16x32_bf16 v[112:115], v[182:185], v[190:193], v[112:115]
	v_mfma_f32_16x16x32_bf16 v[104:107], v[174:177], v[198:201], v[104:107]
	v_mfma_f32_16x16x32_bf16 v[96:99], v[182:185], v[198:201], v[96:99]
	v_mfma_f32_16x16x32_bf16 v[88:91], v[174:177], v[206:209], v[88:91]
	v_mfma_f32_16x16x32_bf16 v[80:83], v[182:185], v[206:209], v[80:83]
	v_mfma_f32_16x16x32_bf16 v[72:75], v[174:177], v[214:217], v[72:75]
	v_mfma_f32_16x16x32_bf16 v[68:71], v[182:185], v[214:217], v[68:71]
	v_mfma_f32_16x16x32_bf16 v[120:123], v[178:181], v[194:197], v[120:123]
	v_mfma_f32_16x16x32_bf16 v[112:115], v[186:189], v[194:197], v[112:115]
	v_mfma_f32_16x16x32_bf16 v[104:107], v[178:181], v[202:205], v[104:107]
	v_mfma_f32_16x16x32_bf16 v[96:99], v[186:189], v[202:205], v[96:99]
	v_mfma_f32_16x16x32_bf16 v[88:91], v[178:181], v[210:213], v[88:91]
	v_mfma_f32_16x16x32_bf16 v[80:83], v[186:189], v[210:213], v[80:83]
	v_mfma_f32_16x16x32_bf16 v[72:75], v[178:181], v[238:241], v[72:75]
	v_mfma_f32_16x16x32_bf16 v[68:71], v[186:189], v[238:241], v[68:71]
	s_barrier
	s_add_i32 s14, s22, s28
	s_add_i32 m0, s14, 0xffffff80
	ds_read_b128 v[190:193], v149 offset:49152
	ds_read_b128 v[194:197], v149 offset:50176
	ds_read_b128 v[198:201], v149 offset:51200
	global_load_lds_dwordx4 v160, s[12:13] offset:128
	s_add_i32 m0, s14, 0x1f80
	ds_read_b128 v[238:241], v149 offset:56320
	global_load_lds_dwordx4 v128, s[12:13] offset:128
	s_add_u32 s12, s12, 0x40080
	s_addc_u32 s13, s13, 0
	s_add_i32 s14, s48, s28
	s_mov_b32 m0, s14
	ds_read_b128 v[214:217], v149 offset:55296
	global_load_lds_dwordx4 v160, s[12:13]
	s_add_i32 m0, s14, 0x2000
	ds_read_b128 v[210:213], v149 offset:54272
	global_load_lds_dwordx4 v128, s[12:13]
	s_add_i32 m0, s35, 0xffffff80
	ds_read_b128 v[206:209], v149 offset:53248
	global_load_lds_dwordx4 v132, s[100:101] offset:128
	s_add_i32 m0, s90, 0xffffff80
	ds_read_b128 v[202:205], v149 offset:52224
	global_load_lds_dwordx4 v130, s[100:101] offset:128
	s_waitcnt vmcnt(8)
	s_waitcnt lgkmcnt(0)
	s_barrier
	v_mfma_f32_16x16x32_bf16 v[60:63], v[138:141], v[190:193], v[60:63]
	v_mfma_f32_16x16x32_bf16 v[48:51], v[150:153], v[190:193], v[48:51]
	v_mfma_f32_16x16x32_bf16 v[44:47], v[138:141], v[198:201], v[44:47]
	v_mfma_f32_16x16x32_bf16 v[32:35], v[150:153], v[198:201], v[32:35]
	v_mfma_f32_16x16x32_bf16 v[28:31], v[138:141], v[206:209], v[28:31]
	v_mfma_f32_16x16x32_bf16 v[16:19], v[150:153], v[206:209], v[16:19]
	v_mfma_f32_16x16x32_bf16 v[12:15], v[138:141], v[214:217], v[12:15]
	v_mfma_f32_16x16x32_bf16 v[0:3], v[150:153], v[214:217], v[0:3]
	v_mfma_f32_16x16x32_bf16 v[60:63], v[142:145], v[194:197], v[60:63]
	v_mfma_f32_16x16x32_bf16 v[48:51], v[154:157], v[194:197], v[48:51]
	v_mfma_f32_16x16x32_bf16 v[44:47], v[142:145], v[202:205], v[44:47]
	v_mfma_f32_16x16x32_bf16 v[32:35], v[154:157], v[202:205], v[32:35]
	v_mfma_f32_16x16x32_bf16 v[28:31], v[142:145], v[210:213], v[28:31]
	v_mfma_f32_16x16x32_bf16 v[16:19], v[154:157], v[210:213], v[16:19]
	v_mfma_f32_16x16x32_bf16 v[12:15], v[142:145], v[238:241], v[12:15]
	v_mfma_f32_16x16x32_bf16 v[0:3], v[154:157], v[238:241], v[0:3]
	v_mfma_f32_16x16x32_bf16 v[56:59], v[174:177], v[190:193], v[56:59]
	v_mfma_f32_16x16x32_bf16 v[52:55], v[182:185], v[190:193], v[52:55]
	v_mfma_f32_16x16x32_bf16 v[40:43], v[174:177], v[198:201], v[40:43]
	v_mfma_f32_16x16x32_bf16 v[36:39], v[182:185], v[198:201], v[36:39]
	v_mfma_f32_16x16x32_bf16 v[24:27], v[174:177], v[206:209], v[24:27]
	v_mfma_f32_16x16x32_bf16 v[20:23], v[182:185], v[206:209], v[20:23]
	v_mfma_f32_16x16x32_bf16 v[8:11], v[174:177], v[214:217], v[8:11]
	v_mfma_f32_16x16x32_bf16 v[4:7], v[182:185], v[214:217], v[4:7]
	v_mfma_f32_16x16x32_bf16 v[56:59], v[178:181], v[194:197], v[56:59]
	v_mfma_f32_16x16x32_bf16 v[52:55], v[186:189], v[194:197], v[52:55]
	v_mfma_f32_16x16x32_bf16 v[40:43], v[178:181], v[202:205], v[40:43]
	v_mfma_f32_16x16x32_bf16 v[36:39], v[186:189], v[202:205], v[36:39]
	v_mfma_f32_16x16x32_bf16 v[24:27], v[178:181], v[210:213], v[24:27]
	v_mfma_f32_16x16x32_bf16 v[20:23], v[186:189], v[210:213], v[20:23]
	v_mfma_f32_16x16x32_bf16 v[8:11], v[178:181], v[238:241], v[8:11]
	v_mfma_f32_16x16x32_bf16 v[4:7], v[186:189], v[238:241], v[4:7]
	s_barrier
	s_add_i32 s21, s21, 2
	s_add_u32 s96, s96, 0x100
	s_addc_u32 s97, s97, 0
	s_add_u32 s10, s10, 0x100
	s_addc_u32 s11, s11, 0
	s_cmp_gt_u32 s21, 13
	s_cbranch_scc0 .LBB0_212
	v_lshl_add_u32 v192, s8, 8, v146
	v_lshlrev_b32_e32 v192, 3, v192
	global_load_dwordx2 v[176:177], v192, s[4:5]
	global_load_dwordx2 v[178:179], v192, s[4:5] offset:128
	global_load_dwordx2 v[180:181], v192, s[4:5] offset:256
	global_load_dwordx2 v[182:183], v192, s[4:5] offset:384
	global_load_dwordx2 v[184:185], v192, s[4:5] offset:1024
	global_load_dwordx2 v[186:187], v192, s[4:5] offset:1152
	global_load_dwordx2 v[188:189], v192, s[4:5] offset:1280
	global_load_dwordx2 v[190:191], v192, s[4:5] offset:1408
	s_and_b64 vcc, exec, s[6:7]
	s_cbranch_vccz .LBB0_215
	s_barrier

.LBB0_310:
	s_add_u32 s12, vcc_lo, 0xfffc0080
	s_addc_u32 s13, vcc_hi, -1
	s_add_i32 s22, 0, 0x10000
	s_cmp_eq_u32 s21, 12
	s_cselect_b32 s93, s9, s13
	s_cselect_b32 s92, s20, s12
	s_cselect_b32 s13, s11, s91
	s_cselect_b32 s12, s45, s90
	s_add_i32 s50, 0, 0x14000
	v_add_u32_e32 v154, s22, v143
	v_add_u32_e32 v158, s50, v143
	ds_read_b128 v[138:141], v154
	ds_read_b128 v[146:149], v154 offset:1024
	ds_read_b128 v[150:153], v154 offset:2048
	ds_read_b128 v[154:157], v154 offset:3072
	ds_read_b128 v[174:177], v158
	ds_read_b128 v[178:181], v158 offset:1024
	ds_read_b128 v[182:185], v158 offset:2048
	ds_read_b128 v[186:189], v158 offset:3072
	s_add_i32 m0, s29, 0xc000
	ds_read_b128 v[190:193], v145
	ds_read_b128 v[194:197], v145 offset:1024
	ds_read_b128 v[198:201], v145 offset:2048
	ds_read_b128 v[202:205], v145 offset:3072
	ds_read_b128 v[206:209], v145 offset:4096
	ds_read_b128 v[210:213], v145 offset:5120
	ds_read_b128 v[214:217], v145 offset:6144
	global_load_lds_dwordx4 v136, vcc
	s_add_i32 m0, s29, 0xe000
	ds_read_b128 v[238:241], v145 offset:7168
	global_load_lds_dwordx4 v134, vcc
	s_waitcnt vmcnt(8)
	s_waitcnt lgkmcnt(0)
	s_barrier
	v_mfma_f32_16x16x32_bf16 v[124:127], v[138:141], v[190:193], v[124:127]
	v_mfma_f32_16x16x32_bf16 v[120:123], v[150:153], v[190:193], v[120:123]
	v_mfma_f32_16x16x32_bf16 v[108:111], v[138:141], v[198:201], v[108:111]
	v_mfma_f32_16x16x32_bf16 v[104:107], v[150:153], v[198:201], v[104:107]
	v_mfma_f32_16x16x32_bf16 v[92:95], v[138:141], v[206:209], v[92:95]
	v_mfma_f32_16x16x32_bf16 v[88:91], v[150:153], v[206:209], v[88:91]
	v_mfma_f32_16x16x32_bf16 v[76:79], v[138:141], v[214:217], v[76:79]
	v_mfma_f32_16x16x32_bf16 v[72:75], v[150:153], v[214:217], v[72:75]
	v_mfma_f32_16x16x32_bf16 v[124:127], v[146:149], v[194:197], v[124:127]
	v_mfma_f32_16x16x32_bf16 v[120:123], v[154:157], v[194:197], v[120:123]
	v_mfma_f32_16x16x32_bf16 v[108:111], v[146:149], v[202:205], v[108:111]
	v_mfma_f32_16x16x32_bf16 v[104:107], v[154:157], v[202:205], v[104:107]
	v_mfma_f32_16x16x32_bf16 v[92:95], v[146:149], v[210:213], v[92:95]
	v_mfma_f32_16x16x32_bf16 v[88:91], v[154:157], v[210:213], v[88:91]
	v_mfma_f32_16x16x32_bf16 v[76:79], v[146:149], v[238:241], v[76:79]
	v_mfma_f32_16x16x32_bf16 v[72:75], v[154:157], v[238:241], v[72:75]
	v_mfma_f32_16x16x32_bf16 v[116:119], v[174:177], v[190:193], v[116:119]
	v_mfma_f32_16x16x32_bf16 v[112:115], v[182:185], v[190:193], v[112:115]
	v_mfma_f32_16x16x32_bf16 v[100:103], v[174:177], v[198:201], v[100:103]
	v_mfma_f32_16x16x32_bf16 v[96:99], v[182:185], v[198:201], v[96:99]
	v_mfma_f32_16x16x32_bf16 v[84:87], v[174:177], v[206:209], v[84:87]
	v_mfma_f32_16x16x32_bf16 v[80:83], v[182:185], v[206:209], v[80:83]
	v_mfma_f32_16x16x32_bf16 v[68:71], v[174:177], v[214:217], v[68:71]
	v_mfma_f32_16x16x32_bf16 v[64:67], v[182:185], v[214:217], v[64:67]
	v_mfma_f32_16x16x32_bf16 v[116:119], v[178:181], v[194:197], v[116:119]
	v_mfma_f32_16x16x32_bf16 v[112:115], v[186:189], v[194:197], v[112:115]
	v_mfma_f32_16x16x32_bf16 v[100:103], v[178:181], v[202:205], v[100:103]
	v_mfma_f32_16x16x32_bf16 v[96:99], v[186:189], v[202:205], v[96:99]
	v_mfma_f32_16x16x32_bf16 v[84:87], v[178:181], v[210:213], v[84:87]
	v_mfma_f32_16x16x32_bf16 v[80:83], v[186:189], v[210:213], v[80:83]
	v_mfma_f32_16x16x32_bf16 v[68:71], v[178:181], v[238:241], v[68:71]
	v_mfma_f32_16x16x32_bf16 v[64:67], v[186:189], v[238:241], v[64:67]
	s_barrier
	s_add_i32 s22, s22, s28
	s_mov_b32 m0, s22
	ds_read_b128 v[190:193], v145 offset:16384
	ds_read_b128 v[194:197], v145 offset:17408
	ds_read_b128 v[198:201], v145 offset:18432
	ds_read_b128 v[202:205], v145 offset:19456
	global_load_lds_dwordx4 v160, s[12:13]
	s_add_i32 m0, s22, 0x2000
	s_add_u32 s48, s12, 0x40000
	s_addc_u32 s49, s13, 0
	s_add_i32 s22, s50, s28
	global_load_lds_dwordx4 v132, s[12:13]
	s_mov_b32 m0, s22
	ds_read_b128 v[238:241], v145 offset:23552
	global_load_lds_dwordx4 v160, s[48:49]
	s_add_i32 m0, s22, 0x2000
	ds_read_b128 v[214:217], v145 offset:22528
	global_load_lds_dwordx4 v132, s[48:49]
	s_mov_b32 m0, s29
	ds_read_b128 v[210:213], v145 offset:21504
	global_load_lds_dwordx4 v128, s[92:93]
	s_mov_b32 m0, s30
	ds_read_b128 v[206:209], v145 offset:20480
	global_load_lds_dwordx4 v130, s[92:93]
	s_waitcnt vmcnt(8)
	s_waitcnt lgkmcnt(0)
	s_barrier
	v_mfma_f32_16x16x32_bf16 v[60:63], v[138:141], v[190:193], v[60:63]
	v_mfma_f32_16x16x32_bf16 v[56:59], v[150:153], v[190:193], v[56:59]
	v_mfma_f32_16x16x32_bf16 v[44:47], v[138:141], v[198:201], v[44:47]
	v_mfma_f32_16x16x32_bf16 v[40:43], v[150:153], v[198:201], v[40:43]
	v_mfma_f32_16x16x32_bf16 v[28:31], v[138:141], v[206:209], v[28:31]
	v_mfma_f32_16x16x32_bf16 v[24:27], v[150:153], v[206:209], v[24:27]
	v_mfma_f32_16x16x32_bf16 v[12:15], v[138:141], v[214:217], v[12:15]
	v_mfma_f32_16x16x32_bf16 v[8:11], v[150:153], v[214:217], v[8:11]
	v_mfma_f32_16x16x32_bf16 v[60:63], v[146:149], v[194:197], v[60:63]
	v_mfma_f32_16x16x32_bf16 v[56:59], v[154:157], v[194:197], v[56:59]
	v_mfma_f32_16x16x32_bf16 v[44:47], v[146:149], v[202:205], v[44:47]
	v_mfma_f32_16x16x32_bf16 v[40:43], v[154:157], v[202:205], v[40:43]
	v_mfma_f32_16x16x32_bf16 v[28:31], v[146:149], v[210:213], v[28:31]
	v_mfma_f32_16x16x32_bf16 v[24:27], v[154:157], v[210:213], v[24:27]
	v_mfma_f32_16x16x32_bf16 v[12:15], v[146:149], v[238:241], v[12:15]
	v_mfma_f32_16x16x32_bf16 v[8:11], v[154:157], v[238:241], v[8:11]
	v_mfma_f32_16x16x32_bf16 v[52:55], v[174:177], v[190:193], v[52:55]
	v_mfma_f32_16x16x32_bf16 v[48:51], v[182:185], v[190:193], v[48:51]
	v_mfma_f32_16x16x32_bf16 v[36:39], v[174:177], v[198:201], v[36:39]
	v_mfma_f32_16x16x32_bf16 v[32:35], v[182:185], v[198:201], v[32:35]
	v_mfma_f32_16x16x32_bf16 v[20:23], v[174:177], v[206:209], v[20:23]
	v_mfma_f32_16x16x32_bf16 v[16:19], v[182:185], v[206:209], v[16:19]
	v_mfma_f32_16x16x32_bf16 v[4:7], v[174:177], v[214:217], v[4:7]
	v_mfma_f32_16x16x32_bf16 v[0:3], v[182:185], v[214:217], v[0:3]
	v_mfma_f32_16x16x32_bf16 v[52:55], v[178:181], v[194:197], v[52:55]
	v_mfma_f32_16x16x32_bf16 v[48:51], v[186:189], v[194:197], v[48:51]
	v_mfma_f32_16x16x32_bf16 v[36:39], v[178:181], v[202:205], v[36:39]
	v_mfma_f32_16x16x32_bf16 v[32:35], v[186:189], v[202:205], v[32:35]
	v_mfma_f32_16x16x32_bf16 v[20:23], v[178:181], v[210:213], v[20:23]
	v_mfma_f32_16x16x32_bf16 v[16:19], v[186:189], v[210:213], v[16:19]
	v_mfma_f32_16x16x32_bf16 v[4:7], v[178:181], v[238:241], v[4:7]
	v_mfma_f32_16x16x32_bf16 v[0:3], v[186:189], v[238:241], v[0:3]
	s_barrier
	s_add_i32 s22, 0, 0x18000
	s_add_i32 s50, 0, 0x1c000
	v_add_u32_e32 v154, s22, v143
	v_add_u32_e32 v168, s50, v143
	ds_read_b128 v[138:141], v154
	ds_read_b128 v[146:149], v154 offset:1024
	ds_read_b128 v[150:153], v154 offset:2048
	ds_read_b128 v[154:157], v154 offset:3072
	ds_read_b128 v[174:177], v168
	ds_read_b128 v[178:181], v168 offset:1024
	ds_read_b128 v[182:185], v168 offset:2048
	ds_read_b128 v[186:189], v168 offset:3072
	s_add_u32 s48, s92, 0x40000
	s_addc_u32 s49, s93, 0
	s_mov_b32 m0, s31
	ds_read_b128 v[190:193], v145 offset:32768
	ds_read_b128 v[194:197], v145 offset:33792
	ds_read_b128 v[198:201], v145 offset:34816
	ds_read_b128 v[202:205], v145 offset:35840
	ds_read_b128 v[206:209], v145 offset:36864
	ds_read_b128 v[210:213], v145 offset:37888
	ds_read_b128 v[214:217], v145 offset:38912
	global_load_lds_dwordx4 v128, s[48:49]
	s_mov_b32 m0, s33
	ds_read_b128 v[238:241], v145 offset:39936
	global_load_lds_dwordx4 v130, s[48:49]
	s_waitcnt vmcnt(8)
	s_waitcnt lgkmcnt(0)
	s_barrier
	v_mfma_f32_16x16x32_bf16 v[124:127], v[138:141], v[190:193], v[124:127]
	v_mfma_f32_16x16x32_bf16 v[120:123], v[150:153], v[190:193], v[120:123]
	v_mfma_f32_16x16x32_bf16 v[108:111], v[138:141], v[198:201], v[108:111]
	v_mfma_f32_16x16x32_bf16 v[104:107], v[150:153], v[198:201], v[104:107]
	v_mfma_f32_16x16x32_bf16 v[92:95], v[138:141], v[206:209], v[92:95]
	v_mfma_f32_16x16x32_bf16 v[88:91], v[150:153], v[206:209], v[88:91]
	v_mfma_f32_16x16x32_bf16 v[76:79], v[138:141], v[214:217], v[76:79]
	v_mfma_f32_16x16x32_bf16 v[72:75], v[150:153], v[214:217], v[72:75]
	v_mfma_f32_16x16x32_bf16 v[124:127], v[146:149], v[194:197], v[124:127]
	v_mfma_f32_16x16x32_bf16 v[120:123], v[154:157], v[194:197], v[120:123]
	v_mfma_f32_16x16x32_bf16 v[108:111], v[146:149], v[202:205], v[108:111]
	v_mfma_f32_16x16x32_bf16 v[104:107], v[154:157], v[202:205], v[104:107]
	v_mfma_f32_16x16x32_bf16 v[92:95], v[146:149], v[210:213], v[92:95]
	v_mfma_f32_16x16x32_bf16 v[88:91], v[154:157], v[210:213], v[88:91]
	v_mfma_f32_16x16x32_bf16 v[76:79], v[146:149], v[238:241], v[76:79]
	v_mfma_f32_16x16x32_bf16 v[72:75], v[154:157], v[238:241], v[72:75]
	v_mfma_f32_16x16x32_bf16 v[116:119], v[174:177], v[190:193], v[116:119]
	v_mfma_f32_16x16x32_bf16 v[112:115], v[182:185], v[190:193], v[112:115]
	v_mfma_f32_16x16x32_bf16 v[100:103], v[174:177], v[198:201], v[100:103]
	v_mfma_f32_16x16x32_bf16 v[96:99], v[182:185], v[198:201], v[96:99]
	v_mfma_f32_16x16x32_bf16 v[84:87], v[174:177], v[206:209], v[84:87]
	v_mfma_f32_16x16x32_bf16 v[80:83], v[182:185], v[206:209], v[80:83]
	v_mfma_f32_16x16x32_bf16 v[68:71], v[174:177], v[214:217], v[68:71]
	v_mfma_f32_16x16x32_bf16 v[64:67], v[182:185], v[214:217], v[64:67]
	v_mfma_f32_16x16x32_bf16 v[116:119], v[178:181], v[194:197], v[116:119]
	v_mfma_f32_16x16x32_bf16 v[112:115], v[186:189], v[194:197], v[112:115]
	v_mfma_f32_16x16x32_bf16 v[100:103], v[178:181], v[202:205], v[100:103]
	v_mfma_f32_16x16x32_bf16 v[96:99], v[186:189], v[202:205], v[96:99]
	v_mfma_f32_16x16x32_bf16 v[84:87], v[178:181], v[210:213], v[84:87]
	v_mfma_f32_16x16x32_bf16 v[80:83], v[186:189], v[210:213], v[80:83]
	v_mfma_f32_16x16x32_bf16 v[68:71], v[178:181], v[238:241], v[68:71]
	v_mfma_f32_16x16x32_bf16 v[64:67], v[186:189], v[238:241], v[64:67]
	s_barrier
	s_add_i32 s22, s22, s28
	s_add_i32 m0, s22, 0xffffff80
	ds_read_b128 v[190:193], v145 offset:49152
	ds_read_b128 v[194:197], v145 offset:50176
	ds_read_b128 v[198:201], v145 offset:51200
	global_load_lds_dwordx4 v160, s[12:13] offset:128
	s_add_i32 m0, s22, 0x1f80
	ds_read_b128 v[238:241], v145 offset:56320
	global_load_lds_dwordx4 v132, s[12:13] offset:128
	s_add_u32 s12, s12, 0x40080
	s_addc_u32 s13, s13, 0
	s_add_i32 s22, s50, s28
	s_mov_b32 m0, s22
	ds_read_b128 v[214:217], v145 offset:55296
	global_load_lds_dwordx4 v160, s[12:13]
	s_add_i32 m0, s22, 0x2000
	ds_read_b128 v[210:213], v145 offset:54272
	global_load_lds_dwordx4 v132, s[12:13]
	s_add_i32 m0, s34, 0xffffff80
	ds_read_b128 v[206:209], v145 offset:53248
	global_load_lds_dwordx4 v128, s[92:93] offset:128
	s_add_i32 m0, s35, 0xffffff80
	ds_read_b128 v[202:205], v145 offset:52224
	global_load_lds_dwordx4 v130, s[92:93] offset:128
	s_waitcnt vmcnt(8)
	s_waitcnt lgkmcnt(0)
	s_barrier
	v_mfma_f32_16x16x32_bf16 v[60:63], v[138:141], v[190:193], v[60:63]
	v_mfma_f32_16x16x32_bf16 v[56:59], v[150:153], v[190:193], v[56:59]
	v_mfma_f32_16x16x32_bf16 v[44:47], v[138:141], v[198:201], v[44:47]
	v_mfma_f32_16x16x32_bf16 v[40:43], v[150:153], v[198:201], v[40:43]
	v_mfma_f32_16x16x32_bf16 v[28:31], v[138:141], v[206:209], v[28:31]
	v_mfma_f32_16x16x32_bf16 v[24:27], v[150:153], v[206:209], v[24:27]
	v_mfma_f32_16x16x32_bf16 v[12:15], v[138:141], v[214:217], v[12:15]
	v_mfma_f32_16x16x32_bf16 v[8:11], v[150:153], v[214:217], v[8:11]
	v_mfma_f32_16x16x32_bf16 v[60:63], v[146:149], v[194:197], v[60:63]
	v_mfma_f32_16x16x32_bf16 v[56:59], v[154:157], v[194:197], v[56:59]
	v_mfma_f32_16x16x32_bf16 v[44:47], v[146:149], v[202:205], v[44:47]
	v_mfma_f32_16x16x32_bf16 v[40:43], v[154:157], v[202:205], v[40:43]
	v_mfma_f32_16x16x32_bf16 v[28:31], v[146:149], v[210:213], v[28:31]
	v_mfma_f32_16x16x32_bf16 v[24:27], v[154:157], v[210:213], v[24:27]
	v_mfma_f32_16x16x32_bf16 v[12:15], v[146:149], v[238:241], v[12:15]
	v_mfma_f32_16x16x32_bf16 v[8:11], v[154:157], v[238:241], v[8:11]
	v_mfma_f32_16x16x32_bf16 v[52:55], v[174:177], v[190:193], v[52:55]
	v_mfma_f32_16x16x32_bf16 v[48:51], v[182:185], v[190:193], v[48:51]
	v_mfma_f32_16x16x32_bf16 v[36:39], v[174:177], v[198:201], v[36:39]
	v_mfma_f32_16x16x32_bf16 v[32:35], v[182:185], v[198:201], v[32:35]
	v_mfma_f32_16x16x32_bf16 v[20:23], v[174:177], v[206:209], v[20:23]
	v_mfma_f32_16x16x32_bf16 v[16:19], v[182:185], v[206:209], v[16:19]
	v_mfma_f32_16x16x32_bf16 v[4:7], v[174:177], v[214:217], v[4:7]
	v_mfma_f32_16x16x32_bf16 v[0:3], v[182:185], v[214:217], v[0:3]
	v_mfma_f32_16x16x32_bf16 v[52:55], v[178:181], v[194:197], v[52:55]
	v_mfma_f32_16x16x32_bf16 v[48:51], v[186:189], v[194:197], v[48:51]
	v_mfma_f32_16x16x32_bf16 v[36:39], v[178:181], v[202:205], v[36:39]
	v_mfma_f32_16x16x32_bf16 v[32:35], v[186:189], v[202:205], v[32:35]
	v_mfma_f32_16x16x32_bf16 v[20:23], v[178:181], v[210:213], v[20:23]
	v_mfma_f32_16x16x32_bf16 v[16:19], v[186:189], v[210:213], v[16:19]
	v_mfma_f32_16x16x32_bf16 v[4:7], v[178:181], v[238:241], v[4:7]
	v_mfma_f32_16x16x32_bf16 v[0:3], v[186:189], v[238:241], v[0:3]
	s_barrier
	s_add_i32 s21, s21, 2
	s_add_u32 s90, s90, 0x100
	s_addc_u32 s91, s91, 0
	s_add_u32 vcc_lo, vcc_lo, 0x100
	s_addc_u32 vcc_hi, vcc_hi, 0
	s_cmp_gt_u32 s21, 13
	s_cbranch_scc0 .LBB0_310
	v_lshl_add_u32 v140, s36, 8, v142
	v_lshl_or_b32 v138, s44, 8, v144
	v_lshlrev_b32_e32 v141, 11, v140
	v_lshl_add_u32 v138, v138, 1, v141
	v_lshlrev_b32_e32 v139, 3, v140
	s_mov_b64 s[12:13], s[2:3]
	global_load_dwordx4 v[146:149], v138, s[12:13]
	global_load_dwordx4 v[150:153], v138, s[12:13] offset:256
	s_add_u32 s12, s12, 0x8000
	s_addc_u32 s13, s13, 0
	global_load_dwordx4 v[154:157], v138, s[12:13]
	global_load_dwordx4 v[162:165], v138, s[12:13] offset:256
	s_add_u32 s12, s12, 0x8000
	s_addc_u32 s13, s13, 0
	global_load_dwordx4 v[166:169], v138, s[12:13]
	global_load_dwordx4 v[174:177], v138, s[12:13] offset:256
	s_add_u32 s12, s12, 0x8000
	s_addc_u32 s13, s13, 0
	global_load_dwordx4 v[178:181], v138, s[12:13]
	global_load_dwordx4 v[182:185], v138, s[12:13] offset:256
	s_add_u32 s12, s12, 0x28000
	s_addc_u32 s13, s13, 0
	global_load_dwordx4 v[186:189], v138, s[12:13]
	global_load_dwordx4 v[190:193], v138, s[12:13] offset:256
	s_add_u32 s12, s12, 0x8000
	s_addc_u32 s13, s13, 0
	global_load_dwordx4 v[194:197], v138, s[12:13]
	global_load_dwordx4 v[198:201], v138, s[12:13] offset:256
	s_add_u32 s12, s12, 0x8000
	s_addc_u32 s13, s13, 0
	global_load_dwordx4 v[202:205], v138, s[12:13]
	global_load_dwordx4 v[206:209], v138, s[12:13] offset:256
	s_add_u32 s12, s12, 0x8000
	s_addc_u32 s13, s13, 0
	global_load_dwordx4 v[210:213], v138, s[12:13]
	global_load_dwordx4 v[214:217], v138, s[12:13] offset:256
	s_and_b64 vcc, exec, s[6:7]
	s_cbranch_vccz .LBB0_313
	s_barrier

.LBB0_399:
	s_add_u32 s8, s0, 0xfffc0080
	s_addc_u32 s9, s1, -1
	s_add_i32 s22, 0, 0x10000
	s_cmp_eq_u32 s21, 12
	s_cselect_b32 s11, s7, s9
	s_cselect_b32 s10, s19, s8
	s_cselect_b32 s9, s20, s91
	s_cselect_b32 s8, s33, s90
	s_add_i32 s48, 0, 0x14000
	v_add_u32_e32 v152, s22, v157
	v_add_u32_e32 v162, s48, v157
	ds_read_b128 v[128:131], v152
	ds_read_b128 v[144:147], v152 offset:1024
	ds_read_b128 v[148:151], v152 offset:2048
	ds_read_b128 v[152:155], v152 offset:3072
	ds_read_b128 v[176:179], v162
	ds_read_b128 v[180:183], v162 offset:1024
	ds_read_b128 v[184:187], v162 offset:2048
	ds_read_b128 v[188:191], v162 offset:3072
	s_add_i32 m0, s27, 0xc000
	ds_read_b128 v[192:195], v159
	ds_read_b128 v[196:199], v159 offset:1024
	ds_read_b128 v[200:203], v159 offset:2048
	ds_read_b128 v[204:207], v159 offset:3072
	ds_read_b128 v[208:211], v159 offset:4096
	ds_read_b128 v[212:215], v159 offset:5120
	ds_read_b128 v[238:241], v159 offset:6144
	global_load_lds_dwordx4 v142, s[0:1]
	s_add_i32 m0, s27, 0xe000
	ds_read_b128 v[246:249], v159 offset:7168
	global_load_lds_dwordx4 v140, s[0:1]
	s_waitcnt vmcnt(8)
	s_waitcnt lgkmcnt(0)
	s_barrier
	v_mfma_f32_16x16x32_bf16 v[124:127], v[128:131], v[192:195], v[124:127]
	v_mfma_f32_16x16x32_bf16 v[116:119], v[148:151], v[192:195], v[116:119]
	v_mfma_f32_16x16x32_bf16 v[108:111], v[128:131], v[200:203], v[108:111]
	v_mfma_f32_16x16x32_bf16 v[100:103], v[148:151], v[200:203], v[100:103]
	v_mfma_f32_16x16x32_bf16 v[92:95], v[128:131], v[208:211], v[92:95]
	v_mfma_f32_16x16x32_bf16 v[84:87], v[148:151], v[208:211], v[84:87]
	v_mfma_f32_16x16x32_bf16 v[76:79], v[128:131], v[238:241], v[76:79]
	v_mfma_f32_16x16x32_bf16 v[68:71], v[148:151], v[238:241], v[68:71]
	v_mfma_f32_16x16x32_bf16 v[124:127], v[144:147], v[196:199], v[124:127]
	v_mfma_f32_16x16x32_bf16 v[116:119], v[152:155], v[196:199], v[116:119]
	v_mfma_f32_16x16x32_bf16 v[108:111], v[144:147], v[204:207], v[108:111]
	v_mfma_f32_16x16x32_bf16 v[100:103], v[152:155], v[204:207], v[100:103]
	v_mfma_f32_16x16x32_bf16 v[92:95], v[144:147], v[212:215], v[92:95]
	v_mfma_f32_16x16x32_bf16 v[84:87], v[152:155], v[212:215], v[84:87]
	v_mfma_f32_16x16x32_bf16 v[76:79], v[144:147], v[246:249], v[76:79]
	v_mfma_f32_16x16x32_bf16 v[68:71], v[152:155], v[246:249], v[68:71]
	v_mfma_f32_16x16x32_bf16 v[120:123], v[176:179], v[192:195], v[120:123]
	v_mfma_f32_16x16x32_bf16 v[112:115], v[184:187], v[192:195], v[112:115]
	v_mfma_f32_16x16x32_bf16 v[104:107], v[176:179], v[200:203], v[104:107]
	v_mfma_f32_16x16x32_bf16 v[96:99], v[184:187], v[200:203], v[96:99]
	v_mfma_f32_16x16x32_bf16 v[88:91], v[176:179], v[208:211], v[88:91]
	v_mfma_f32_16x16x32_bf16 v[80:83], v[184:187], v[208:211], v[80:83]
	v_mfma_f32_16x16x32_bf16 v[72:75], v[176:179], v[238:241], v[72:75]
	v_mfma_f32_16x16x32_bf16 v[64:67], v[184:187], v[238:241], v[64:67]
	v_mfma_f32_16x16x32_bf16 v[120:123], v[180:183], v[196:199], v[120:123]
	v_mfma_f32_16x16x32_bf16 v[112:115], v[188:191], v[196:199], v[112:115]
	v_mfma_f32_16x16x32_bf16 v[104:107], v[180:183], v[204:207], v[104:107]
	v_mfma_f32_16x16x32_bf16 v[96:99], v[188:191], v[204:207], v[96:99]
	v_mfma_f32_16x16x32_bf16 v[88:91], v[180:183], v[212:215], v[88:91]
	v_mfma_f32_16x16x32_bf16 v[80:83], v[188:191], v[212:215], v[80:83]
	v_mfma_f32_16x16x32_bf16 v[72:75], v[180:183], v[246:249], v[72:75]
	v_mfma_f32_16x16x32_bf16 v[64:67], v[188:191], v[246:249], v[64:67]
	s_barrier
	s_add_i32 s22, s22, s25
	s_mov_b32 m0, s22
	ds_read_b128 v[192:195], v159 offset:16384
	ds_read_b128 v[196:199], v159 offset:17408
	ds_read_b128 v[200:203], v159 offset:18432
	ds_read_b128 v[204:207], v159 offset:19456
	global_load_lds_dwordx4 v136, s[8:9]
	s_add_i32 m0, s22, 0x2000
	s_add_u32 vcc_lo, s8, 0x40000
	s_addc_u32 vcc_hi, s9, 0
	s_add_i32 s22, s48, s25
	global_load_lds_dwordx4 v132, s[8:9]
	s_mov_b32 m0, s22
	ds_read_b128 v[246:249], v159 offset:23552
	global_load_lds_dwordx4 v136, vcc
	s_add_i32 m0, s22, 0x2000
	ds_read_b128 v[238:241], v159 offset:22528
	global_load_lds_dwordx4 v132, vcc
	s_mov_b32 m0, s27
	ds_read_b128 v[212:215], v159 offset:21504
	global_load_lds_dwordx4 v138, s[10:11]
	s_mov_b32 m0, s45
	ds_read_b128 v[208:211], v159 offset:20480
	global_load_lds_dwordx4 v134, s[10:11]
	s_waitcnt vmcnt(8)
	s_waitcnt lgkmcnt(0)
	s_barrier
	v_mfma_f32_16x16x32_bf16 v[60:63], v[128:131], v[192:195], v[60:63]
	v_mfma_f32_16x16x32_bf16 v[52:55], v[148:151], v[192:195], v[52:55]
	v_mfma_f32_16x16x32_bf16 v[44:47], v[128:131], v[200:203], v[44:47]
	v_mfma_f32_16x16x32_bf16 v[36:39], v[148:151], v[200:203], v[36:39]
	v_mfma_f32_16x16x32_bf16 v[28:31], v[128:131], v[208:211], v[28:31]
	v_mfma_f32_16x16x32_bf16 v[20:23], v[148:151], v[208:211], v[20:23]
	v_mfma_f32_16x16x32_bf16 v[12:15], v[128:131], v[238:241], v[12:15]
	v_mfma_f32_16x16x32_bf16 v[4:7], v[148:151], v[238:241], v[4:7]
	v_mfma_f32_16x16x32_bf16 v[60:63], v[144:147], v[196:199], v[60:63]
	v_mfma_f32_16x16x32_bf16 v[52:55], v[152:155], v[196:199], v[52:55]
	v_mfma_f32_16x16x32_bf16 v[44:47], v[144:147], v[204:207], v[44:47]
	v_mfma_f32_16x16x32_bf16 v[36:39], v[152:155], v[204:207], v[36:39]
	v_mfma_f32_16x16x32_bf16 v[28:31], v[144:147], v[212:215], v[28:31]
	v_mfma_f32_16x16x32_bf16 v[20:23], v[152:155], v[212:215], v[20:23]
	v_mfma_f32_16x16x32_bf16 v[12:15], v[144:147], v[246:249], v[12:15]
	v_mfma_f32_16x16x32_bf16 v[4:7], v[152:155], v[246:249], v[4:7]
	v_mfma_f32_16x16x32_bf16 v[56:59], v[176:179], v[192:195], v[56:59]
	v_mfma_f32_16x16x32_bf16 v[48:51], v[184:187], v[192:195], v[48:51]
	v_mfma_f32_16x16x32_bf16 v[40:43], v[176:179], v[200:203], v[40:43]
	v_mfma_f32_16x16x32_bf16 v[32:35], v[184:187], v[200:203], v[32:35]
	v_mfma_f32_16x16x32_bf16 v[24:27], v[176:179], v[208:211], v[24:27]
	v_mfma_f32_16x16x32_bf16 v[16:19], v[184:187], v[208:211], v[16:19]
	v_mfma_f32_16x16x32_bf16 v[8:11], v[176:179], v[238:241], v[8:11]
	v_mfma_f32_16x16x32_bf16 v[0:3], v[184:187], v[238:241], v[0:3]
	v_mfma_f32_16x16x32_bf16 v[56:59], v[180:183], v[196:199], v[56:59]
	v_mfma_f32_16x16x32_bf16 v[48:51], v[188:191], v[196:199], v[48:51]
	v_mfma_f32_16x16x32_bf16 v[40:43], v[180:183], v[204:207], v[40:43]
	v_mfma_f32_16x16x32_bf16 v[32:35], v[188:191], v[204:207], v[32:35]
	v_mfma_f32_16x16x32_bf16 v[24:27], v[180:183], v[212:215], v[24:27]
	v_mfma_f32_16x16x32_bf16 v[16:19], v[188:191], v[212:215], v[16:19]
	v_mfma_f32_16x16x32_bf16 v[8:11], v[180:183], v[246:249], v[8:11]
	v_mfma_f32_16x16x32_bf16 v[0:3], v[188:191], v[246:249], v[0:3]
	s_barrier
	s_add_i32 s22, 0, 0x18000
	s_add_i32 s48, 0, 0x1c000
	v_add_u32_e32 v152, s22, v157
	v_add_u32_e32 v170, s48, v157
	ds_read_b128 v[128:131], v152
	ds_read_b128 v[144:147], v152 offset:1024
	ds_read_b128 v[148:151], v152 offset:2048
	ds_read_b128 v[152:155], v152 offset:3072
	ds_read_b128 v[176:179], v170
	ds_read_b128 v[180:183], v170 offset:1024
	ds_read_b128 v[184:187], v170 offset:2048
	ds_read_b128 v[188:191], v170 offset:3072
	s_mov_b64 s[100:101], s[10:11]
	s_add_u32 s10, s10, 0x40000
	s_addc_u32 s11, s11, 0
	s_mov_b32 m0, s28
	ds_read_b128 v[192:195], v159 offset:32768
	ds_read_b128 v[196:199], v159 offset:33792
	ds_read_b128 v[200:203], v159 offset:34816
	ds_read_b128 v[204:207], v159 offset:35840
	ds_read_b128 v[208:211], v159 offset:36864
	ds_read_b128 v[212:215], v159 offset:37888
	ds_read_b128 v[238:241], v159 offset:38912
	global_load_lds_dwordx4 v138, s[10:11]
	s_mov_b32 m0, s29
	ds_read_b128 v[246:249], v159 offset:39936
	global_load_lds_dwordx4 v134, s[10:11]
	s_waitcnt vmcnt(8)
	s_waitcnt lgkmcnt(0)
	s_barrier
	v_mfma_f32_16x16x32_bf16 v[124:127], v[128:131], v[192:195], v[124:127]
	v_mfma_f32_16x16x32_bf16 v[116:119], v[148:151], v[192:195], v[116:119]
	v_mfma_f32_16x16x32_bf16 v[108:111], v[128:131], v[200:203], v[108:111]
	v_mfma_f32_16x16x32_bf16 v[100:103], v[148:151], v[200:203], v[100:103]
	v_mfma_f32_16x16x32_bf16 v[92:95], v[128:131], v[208:211], v[92:95]
	v_mfma_f32_16x16x32_bf16 v[84:87], v[148:151], v[208:211], v[84:87]
	v_mfma_f32_16x16x32_bf16 v[76:79], v[128:131], v[238:241], v[76:79]
	v_mfma_f32_16x16x32_bf16 v[68:71], v[148:151], v[238:241], v[68:71]
	v_mfma_f32_16x16x32_bf16 v[124:127], v[144:147], v[196:199], v[124:127]
	v_mfma_f32_16x16x32_bf16 v[116:119], v[152:155], v[196:199], v[116:119]
	v_mfma_f32_16x16x32_bf16 v[108:111], v[144:147], v[204:207], v[108:111]
	v_mfma_f32_16x16x32_bf16 v[100:103], v[152:155], v[204:207], v[100:103]
	v_mfma_f32_16x16x32_bf16 v[92:95], v[144:147], v[212:215], v[92:95]
	v_mfma_f32_16x16x32_bf16 v[84:87], v[152:155], v[212:215], v[84:87]
	v_mfma_f32_16x16x32_bf16 v[76:79], v[144:147], v[246:249], v[76:79]
	v_mfma_f32_16x16x32_bf16 v[68:71], v[152:155], v[246:249], v[68:71]
	v_mfma_f32_16x16x32_bf16 v[120:123], v[176:179], v[192:195], v[120:123]
	v_mfma_f32_16x16x32_bf16 v[112:115], v[184:187], v[192:195], v[112:115]
	v_mfma_f32_16x16x32_bf16 v[104:107], v[176:179], v[200:203], v[104:107]
	v_mfma_f32_16x16x32_bf16 v[96:99], v[184:187], v[200:203], v[96:99]
	v_mfma_f32_16x16x32_bf16 v[88:91], v[176:179], v[208:211], v[88:91]
	v_mfma_f32_16x16x32_bf16 v[80:83], v[184:187], v[208:211], v[80:83]
	v_mfma_f32_16x16x32_bf16 v[72:75], v[176:179], v[238:241], v[72:75]
	v_mfma_f32_16x16x32_bf16 v[64:67], v[184:187], v[238:241], v[64:67]
	v_mfma_f32_16x16x32_bf16 v[120:123], v[180:183], v[196:199], v[120:123]
	v_mfma_f32_16x16x32_bf16 v[112:115], v[188:191], v[196:199], v[112:115]
	v_mfma_f32_16x16x32_bf16 v[104:107], v[180:183], v[204:207], v[104:107]
	v_mfma_f32_16x16x32_bf16 v[96:99], v[188:191], v[204:207], v[96:99]
	v_mfma_f32_16x16x32_bf16 v[88:91], v[180:183], v[212:215], v[88:91]
	v_mfma_f32_16x16x32_bf16 v[80:83], v[188:191], v[212:215], v[80:83]
	v_mfma_f32_16x16x32_bf16 v[72:75], v[180:183], v[246:249], v[72:75]
	v_mfma_f32_16x16x32_bf16 v[64:67], v[188:191], v[246:249], v[64:67]
	s_barrier
	s_add_i32 s10, s22, s25
	s_add_i32 m0, s10, 0xffffff80
	ds_read_b128 v[192:195], v159 offset:49152
	ds_read_b128 v[196:199], v159 offset:50176
	ds_read_b128 v[200:203], v159 offset:51200
	global_load_lds_dwordx4 v136, s[8:9] offset:128
	s_add_i32 m0, s10, 0x1f80
	ds_read_b128 v[246:249], v159 offset:56320
	global_load_lds_dwordx4 v132, s[8:9] offset:128
	s_add_u32 s8, s8, 0x40080
	s_addc_u32 s9, s9, 0
	s_add_i32 s10, s48, s25
	s_mov_b32 m0, s10
	ds_read_b128 v[238:241], v159 offset:55296
	global_load_lds_dwordx4 v136, s[8:9]
	s_add_i32 m0, s10, 0x2000
	ds_read_b128 v[212:215], v159 offset:54272
	global_load_lds_dwordx4 v132, s[8:9]
	s_add_i32 m0, s30, 0xffffff80
	ds_read_b128 v[208:211], v159 offset:53248
	global_load_lds_dwordx4 v138, s[100:101] offset:128
	s_add_i32 m0, s31, 0xffffff80
	ds_read_b128 v[204:207], v159 offset:52224
	global_load_lds_dwordx4 v134, s[100:101] offset:128
	s_waitcnt vmcnt(8)
	s_waitcnt lgkmcnt(0)
	s_barrier
	v_mfma_f32_16x16x32_bf16 v[60:63], v[128:131], v[192:195], v[60:63]
	v_mfma_f32_16x16x32_bf16 v[52:55], v[148:151], v[192:195], v[52:55]
	v_mfma_f32_16x16x32_bf16 v[44:47], v[128:131], v[200:203], v[44:47]
	v_mfma_f32_16x16x32_bf16 v[36:39], v[148:151], v[200:203], v[36:39]
	v_mfma_f32_16x16x32_bf16 v[28:31], v[128:131], v[208:211], v[28:31]
	v_mfma_f32_16x16x32_bf16 v[20:23], v[148:151], v[208:211], v[20:23]
	v_mfma_f32_16x16x32_bf16 v[12:15], v[128:131], v[238:241], v[12:15]
	v_mfma_f32_16x16x32_bf16 v[4:7], v[148:151], v[238:241], v[4:7]
	v_mfma_f32_16x16x32_bf16 v[60:63], v[144:147], v[196:199], v[60:63]
	v_mfma_f32_16x16x32_bf16 v[52:55], v[152:155], v[196:199], v[52:55]
	v_mfma_f32_16x16x32_bf16 v[44:47], v[144:147], v[204:207], v[44:47]
	v_mfma_f32_16x16x32_bf16 v[36:39], v[152:155], v[204:207], v[36:39]
	v_mfma_f32_16x16x32_bf16 v[28:31], v[144:147], v[212:215], v[28:31]
	v_mfma_f32_16x16x32_bf16 v[20:23], v[152:155], v[212:215], v[20:23]
	v_mfma_f32_16x16x32_bf16 v[12:15], v[144:147], v[246:249], v[12:15]
	v_mfma_f32_16x16x32_bf16 v[4:7], v[152:155], v[246:249], v[4:7]
	v_mfma_f32_16x16x32_bf16 v[56:59], v[176:179], v[192:195], v[56:59]
	v_mfma_f32_16x16x32_bf16 v[48:51], v[184:187], v[192:195], v[48:51]
	v_mfma_f32_16x16x32_bf16 v[40:43], v[176:179], v[200:203], v[40:43]
	v_mfma_f32_16x16x32_bf16 v[32:35], v[184:187], v[200:203], v[32:35]
	v_mfma_f32_16x16x32_bf16 v[24:27], v[176:179], v[208:211], v[24:27]
	v_mfma_f32_16x16x32_bf16 v[16:19], v[184:187], v[208:211], v[16:19]
	v_mfma_f32_16x16x32_bf16 v[8:11], v[176:179], v[238:241], v[8:11]
	v_mfma_f32_16x16x32_bf16 v[0:3], v[184:187], v[238:241], v[0:3]
	v_mfma_f32_16x16x32_bf16 v[56:59], v[180:183], v[196:199], v[56:59]
	v_mfma_f32_16x16x32_bf16 v[48:51], v[188:191], v[196:199], v[48:51]
	v_mfma_f32_16x16x32_bf16 v[40:43], v[180:183], v[204:207], v[40:43]
	v_mfma_f32_16x16x32_bf16 v[32:35], v[188:191], v[204:207], v[32:35]
	v_mfma_f32_16x16x32_bf16 v[24:27], v[180:183], v[212:215], v[24:27]
	v_mfma_f32_16x16x32_bf16 v[16:19], v[188:191], v[212:215], v[16:19]
	v_mfma_f32_16x16x32_bf16 v[8:11], v[180:183], v[246:249], v[8:11]
	v_mfma_f32_16x16x32_bf16 v[0:3], v[188:191], v[246:249], v[0:3]
	s_barrier
	s_add_i32 s21, s21, 2
	s_add_u32 s90, s90, 0x100
	s_addc_u32 s91, s91, 0
	s_add_u32 s0, s0, 0x100
	s_addc_u32 s1, s1, 0
	s_cmp_gt_u32 s21, 13
	s_cbranch_scc0 .LBB0_399
	v_lshl_add_u32 v212, s44, 8, v156
	v_lshlrev_b32_e32 v212, 3, v212
	global_load_dwordx2 v[196:197], v212, s[36:37]
	global_load_dwordx2 v[198:199], v212, s[36:37] offset:128
	global_load_dwordx2 v[200:201], v212, s[36:37] offset:256
	global_load_dwordx2 v[202:203], v212, s[36:37] offset:384
	global_load_dwordx2 v[204:205], v212, s[36:37] offset:1024
	global_load_dwordx2 v[206:207], v212, s[36:37] offset:1152
	global_load_dwordx2 v[208:209], v212, s[36:37] offset:1280
	global_load_dwordx2 v[210:211], v212, s[36:37] offset:1408
	s_and_b64 vcc, exec, s[92:93]
	s_cbranch_vccnz .LBB0_404
	s_cmp_gt_i32 s35, 3
	s_mov_b64 s[0:1], -1
	s_cbranch_scc1 .LBB0_405

.LBB0_439:
	s_add_u32 s10, s8, 0x100
	s_addc_u32 s11, s9, 0
	s_add_i32 s48, 0, 0x10000
	s_cmp_eq_u32 s22, 40
	s_cselect_b32 s15, s1, s11
	s_cselect_b32 s14, s0, s10
	s_cselect_b32 s13, s45, s92
	s_cselect_b32 s12, s44, s21
	s_add_i32 s49, 0, 0x14000
	v_add_u32_e32 v154, s48, v143
	v_add_u32_e32 v158, s49, v143
	ds_read_b128 v[138:141], v154
	ds_read_b128 v[146:149], v154 offset:1024
	ds_read_b128 v[150:153], v154 offset:2048
	ds_read_b128 v[154:157], v154 offset:3072
	ds_read_b128 v[174:177], v158
	ds_read_b128 v[178:181], v158 offset:1024
	ds_read_b128 v[182:185], v158 offset:2048
	ds_read_b128 v[186:189], v158 offset:3072
	s_add_i32 m0, s29, 0xc000
	ds_read_b128 v[190:193], v145
	ds_read_b128 v[194:197], v145 offset:1024
	ds_read_b128 v[198:201], v145 offset:2048
	ds_read_b128 v[202:205], v145 offset:3072
	ds_read_b128 v[206:209], v145 offset:4096
	ds_read_b128 v[210:213], v145 offset:5120
	ds_read_b128 v[214:217], v145 offset:6144
	global_load_lds_dwordx4 v136, s[8:9]
	s_add_i32 m0, s29, 0xe000
	ds_read_b128 v[238:241], v145 offset:7168
	global_load_lds_dwordx4 v134, s[8:9]
	s_waitcnt vmcnt(8)
	s_waitcnt lgkmcnt(0)
	s_barrier
	v_mfma_f32_16x16x32_bf16 v[124:127], v[138:141], v[190:193], v[124:127]
	v_mfma_f32_16x16x32_bf16 v[120:123], v[150:153], v[190:193], v[120:123]
	v_mfma_f32_16x16x32_bf16 v[108:111], v[138:141], v[198:201], v[108:111]
	v_mfma_f32_16x16x32_bf16 v[104:107], v[150:153], v[198:201], v[104:107]
	v_mfma_f32_16x16x32_bf16 v[92:95], v[138:141], v[206:209], v[92:95]
	v_mfma_f32_16x16x32_bf16 v[88:91], v[150:153], v[206:209], v[88:91]
	v_mfma_f32_16x16x32_bf16 v[76:79], v[138:141], v[214:217], v[76:79]
	v_mfma_f32_16x16x32_bf16 v[72:75], v[150:153], v[214:217], v[72:75]
	v_mfma_f32_16x16x32_bf16 v[124:127], v[146:149], v[194:197], v[124:127]
	v_mfma_f32_16x16x32_bf16 v[120:123], v[154:157], v[194:197], v[120:123]
	v_mfma_f32_16x16x32_bf16 v[108:111], v[146:149], v[202:205], v[108:111]
	v_mfma_f32_16x16x32_bf16 v[104:107], v[154:157], v[202:205], v[104:107]
	v_mfma_f32_16x16x32_bf16 v[92:95], v[146:149], v[210:213], v[92:95]
	v_mfma_f32_16x16x32_bf16 v[88:91], v[154:157], v[210:213], v[88:91]
	v_mfma_f32_16x16x32_bf16 v[76:79], v[146:149], v[238:241], v[76:79]
	v_mfma_f32_16x16x32_bf16 v[72:75], v[154:157], v[238:241], v[72:75]
	v_mfma_f32_16x16x32_bf16 v[116:119], v[174:177], v[190:193], v[116:119]
	v_mfma_f32_16x16x32_bf16 v[112:115], v[182:185], v[190:193], v[112:115]
	v_mfma_f32_16x16x32_bf16 v[100:103], v[174:177], v[198:201], v[100:103]
	v_mfma_f32_16x16x32_bf16 v[96:99], v[182:185], v[198:201], v[96:99]
	v_mfma_f32_16x16x32_bf16 v[84:87], v[174:177], v[206:209], v[84:87]
	v_mfma_f32_16x16x32_bf16 v[80:83], v[182:185], v[206:209], v[80:83]
	v_mfma_f32_16x16x32_bf16 v[68:71], v[174:177], v[214:217], v[68:71]
	v_mfma_f32_16x16x32_bf16 v[64:67], v[182:185], v[214:217], v[64:67]
	v_mfma_f32_16x16x32_bf16 v[116:119], v[178:181], v[194:197], v[116:119]
	v_mfma_f32_16x16x32_bf16 v[112:115], v[186:189], v[194:197], v[112:115]
	v_mfma_f32_16x16x32_bf16 v[100:103], v[178:181], v[202:205], v[100:103]
	v_mfma_f32_16x16x32_bf16 v[96:99], v[186:189], v[202:205], v[96:99]
	v_mfma_f32_16x16x32_bf16 v[84:87], v[178:181], v[210:213], v[84:87]
	v_mfma_f32_16x16x32_bf16 v[80:83], v[186:189], v[210:213], v[80:83]
	v_mfma_f32_16x16x32_bf16 v[68:71], v[178:181], v[238:241], v[68:71]
	v_mfma_f32_16x16x32_bf16 v[64:67], v[186:189], v[238:241], v[64:67]
	s_barrier
	s_add_i32 s8, s48, s28
	s_mov_b32 m0, s8
	ds_read_b128 v[190:193], v145 offset:16384
	ds_read_b128 v[194:197], v145 offset:17408
	ds_read_b128 v[198:201], v145 offset:18432
	ds_read_b128 v[202:205], v145 offset:19456
	global_load_lds_dwordx4 v160, s[12:13]
	s_add_i32 m0, s8, 0x2000
	s_add_u32 s8, s12, 0xb0000
	s_addc_u32 s9, s13, 0
	s_add_i32 s48, s49, s28
	global_load_lds_dwordx4 v132, s[12:13]
	s_mov_b32 m0, s48
	ds_read_b128 v[238:241], v145 offset:23552
	global_load_lds_dwordx4 v160, s[8:9]
	s_add_i32 m0, s48, 0x2000
	ds_read_b128 v[214:217], v145 offset:22528
	global_load_lds_dwordx4 v132, s[8:9]
	s_mov_b32 m0, s29
	ds_read_b128 v[210:213], v145 offset:21504
	global_load_lds_dwordx4 v128, s[14:15]
	s_mov_b32 m0, s30
	ds_read_b128 v[206:209], v145 offset:20480
	global_load_lds_dwordx4 v130, s[14:15]
	s_waitcnt vmcnt(8)
	s_waitcnt lgkmcnt(0)
	s_barrier
	v_mfma_f32_16x16x32_bf16 v[60:63], v[138:141], v[190:193], v[60:63]
	v_mfma_f32_16x16x32_bf16 v[56:59], v[150:153], v[190:193], v[56:59]
	v_mfma_f32_16x16x32_bf16 v[44:47], v[138:141], v[198:201], v[44:47]
	v_mfma_f32_16x16x32_bf16 v[40:43], v[150:153], v[198:201], v[40:43]
	v_mfma_f32_16x16x32_bf16 v[28:31], v[138:141], v[206:209], v[28:31]
	v_mfma_f32_16x16x32_bf16 v[24:27], v[150:153], v[206:209], v[24:27]
	v_mfma_f32_16x16x32_bf16 v[12:15], v[138:141], v[214:217], v[12:15]
	v_mfma_f32_16x16x32_bf16 v[8:11], v[150:153], v[214:217], v[8:11]
	v_mfma_f32_16x16x32_bf16 v[60:63], v[146:149], v[194:197], v[60:63]
	v_mfma_f32_16x16x32_bf16 v[56:59], v[154:157], v[194:197], v[56:59]
	v_mfma_f32_16x16x32_bf16 v[44:47], v[146:149], v[202:205], v[44:47]
	v_mfma_f32_16x16x32_bf16 v[40:43], v[154:157], v[202:205], v[40:43]
	v_mfma_f32_16x16x32_bf16 v[28:31], v[146:149], v[210:213], v[28:31]
	v_mfma_f32_16x16x32_bf16 v[24:27], v[154:157], v[210:213], v[24:27]
	v_mfma_f32_16x16x32_bf16 v[12:15], v[146:149], v[238:241], v[12:15]
	v_mfma_f32_16x16x32_bf16 v[8:11], v[154:157], v[238:241], v[8:11]
	v_mfma_f32_16x16x32_bf16 v[52:55], v[174:177], v[190:193], v[52:55]
	v_mfma_f32_16x16x32_bf16 v[48:51], v[182:185], v[190:193], v[48:51]
	v_mfma_f32_16x16x32_bf16 v[36:39], v[174:177], v[198:201], v[36:39]
	v_mfma_f32_16x16x32_bf16 v[32:35], v[182:185], v[198:201], v[32:35]
	v_mfma_f32_16x16x32_bf16 v[20:23], v[174:177], v[206:209], v[20:23]
	v_mfma_f32_16x16x32_bf16 v[16:19], v[182:185], v[206:209], v[16:19]
	v_mfma_f32_16x16x32_bf16 v[4:7], v[174:177], v[214:217], v[4:7]
	v_mfma_f32_16x16x32_bf16 v[0:3], v[182:185], v[214:217], v[0:3]
	v_mfma_f32_16x16x32_bf16 v[52:55], v[178:181], v[194:197], v[52:55]
	v_mfma_f32_16x16x32_bf16 v[48:51], v[186:189], v[194:197], v[48:51]
	v_mfma_f32_16x16x32_bf16 v[36:39], v[178:181], v[202:205], v[36:39]
	v_mfma_f32_16x16x32_bf16 v[32:35], v[186:189], v[202:205], v[32:35]
	v_mfma_f32_16x16x32_bf16 v[20:23], v[178:181], v[210:213], v[20:23]
	v_mfma_f32_16x16x32_bf16 v[16:19], v[186:189], v[210:213], v[16:19]
	v_mfma_f32_16x16x32_bf16 v[4:7], v[178:181], v[238:241], v[4:7]
	v_mfma_f32_16x16x32_bf16 v[0:3], v[186:189], v[238:241], v[0:3]
	s_barrier
	s_add_i32 s48, 0, 0x18000
	s_add_i32 s49, 0, 0x1c000
	v_add_u32_e32 v154, s48, v143
	v_add_u32_e32 v168, s49, v143
	ds_read_b128 v[138:141], v154
	ds_read_b128 v[146:149], v154 offset:1024
	ds_read_b128 v[150:153], v154 offset:2048
	ds_read_b128 v[154:157], v154 offset:3072
	ds_read_b128 v[174:177], v168
	ds_read_b128 v[178:181], v168 offset:1024
	ds_read_b128 v[182:185], v168 offset:2048
	ds_read_b128 v[186:189], v168 offset:3072
	s_add_u32 s8, s14, 0xb0000
	s_addc_u32 s9, s15, 0
	s_mov_b32 m0, s31
	ds_read_b128 v[190:193], v145 offset:32768
	ds_read_b128 v[194:197], v145 offset:33792
	ds_read_b128 v[198:201], v145 offset:34816
	ds_read_b128 v[202:205], v145 offset:35840
	ds_read_b128 v[206:209], v145 offset:36864
	ds_read_b128 v[210:213], v145 offset:37888
	ds_read_b128 v[214:217], v145 offset:38912
	global_load_lds_dwordx4 v128, s[8:9]
	s_mov_b32 m0, s33
	ds_read_b128 v[238:241], v145 offset:39936
	global_load_lds_dwordx4 v130, s[8:9]
	s_waitcnt vmcnt(8)
	s_waitcnt lgkmcnt(0)
	s_barrier
	v_mfma_f32_16x16x32_bf16 v[124:127], v[138:141], v[190:193], v[124:127]
	v_mfma_f32_16x16x32_bf16 v[120:123], v[150:153], v[190:193], v[120:123]
	v_mfma_f32_16x16x32_bf16 v[108:111], v[138:141], v[198:201], v[108:111]
	v_mfma_f32_16x16x32_bf16 v[104:107], v[150:153], v[198:201], v[104:107]
	v_mfma_f32_16x16x32_bf16 v[92:95], v[138:141], v[206:209], v[92:95]
	v_mfma_f32_16x16x32_bf16 v[88:91], v[150:153], v[206:209], v[88:91]
	v_mfma_f32_16x16x32_bf16 v[76:79], v[138:141], v[214:217], v[76:79]
	v_mfma_f32_16x16x32_bf16 v[72:75], v[150:153], v[214:217], v[72:75]
	v_mfma_f32_16x16x32_bf16 v[124:127], v[146:149], v[194:197], v[124:127]
	v_mfma_f32_16x16x32_bf16 v[120:123], v[154:157], v[194:197], v[120:123]
	v_mfma_f32_16x16x32_bf16 v[108:111], v[146:149], v[202:205], v[108:111]
	v_mfma_f32_16x16x32_bf16 v[104:107], v[154:157], v[202:205], v[104:107]
	v_mfma_f32_16x16x32_bf16 v[92:95], v[146:149], v[210:213], v[92:95]
	v_mfma_f32_16x16x32_bf16 v[88:91], v[154:157], v[210:213], v[88:91]
	v_mfma_f32_16x16x32_bf16 v[76:79], v[146:149], v[238:241], v[76:79]
	v_mfma_f32_16x16x32_bf16 v[72:75], v[154:157], v[238:241], v[72:75]
	v_mfma_f32_16x16x32_bf16 v[116:119], v[174:177], v[190:193], v[116:119]
	v_mfma_f32_16x16x32_bf16 v[112:115], v[182:185], v[190:193], v[112:115]
	v_mfma_f32_16x16x32_bf16 v[100:103], v[174:177], v[198:201], v[100:103]
	v_mfma_f32_16x16x32_bf16 v[96:99], v[182:185], v[198:201], v[96:99]
	v_mfma_f32_16x16x32_bf16 v[84:87], v[174:177], v[206:209], v[84:87]
	v_mfma_f32_16x16x32_bf16 v[80:83], v[182:185], v[206:209], v[80:83]
	v_mfma_f32_16x16x32_bf16 v[68:71], v[174:177], v[214:217], v[68:71]
	v_mfma_f32_16x16x32_bf16 v[64:67], v[182:185], v[214:217], v[64:67]
	v_mfma_f32_16x16x32_bf16 v[116:119], v[178:181], v[194:197], v[116:119]
	v_mfma_f32_16x16x32_bf16 v[112:115], v[186:189], v[194:197], v[112:115]
	v_mfma_f32_16x16x32_bf16 v[100:103], v[178:181], v[202:205], v[100:103]
	v_mfma_f32_16x16x32_bf16 v[96:99], v[186:189], v[202:205], v[96:99]
	v_mfma_f32_16x16x32_bf16 v[84:87], v[178:181], v[210:213], v[84:87]
	v_mfma_f32_16x16x32_bf16 v[80:83], v[186:189], v[210:213], v[80:83]
	v_mfma_f32_16x16x32_bf16 v[68:71], v[178:181], v[238:241], v[68:71]
	v_mfma_f32_16x16x32_bf16 v[64:67], v[186:189], v[238:241], v[64:67]
	s_barrier
	s_add_i32 s8, s48, s28
	s_add_i32 m0, s8, 0xffffff80
	ds_read_b128 v[190:193], v145 offset:49152
	ds_read_b128 v[194:197], v145 offset:50176
	ds_read_b128 v[198:201], v145 offset:51200
	ds_read_b128 v[202:205], v145 offset:52224
	global_load_lds_dwordx4 v160, s[12:13] offset:128
	s_add_i32 m0, s8, 0x1f80
	s_add_u32 s8, s12, 0xb0080
	s_addc_u32 s9, s13, 0
	global_load_lds_dwordx4 v132, s[12:13] offset:128
	s_add_i32 s12, s49, s28
	s_mov_b32 m0, s12
	ds_read_b128 v[238:241], v145 offset:56320
	global_load_lds_dwordx4 v160, s[8:9]
	s_add_i32 m0, s12, 0x2000
	ds_read_b128 v[214:217], v145 offset:55296
	global_load_lds_dwordx4 v132, s[8:9]
	s_add_i32 m0, s34, 0xffffff80
	ds_read_b128 v[210:213], v145 offset:54272
	global_load_lds_dwordx4 v128, s[14:15] offset:128
	s_add_i32 m0, s35, 0xffffff80
	ds_read_b128 v[206:209], v145 offset:53248
	global_load_lds_dwordx4 v130, s[14:15] offset:128
	s_waitcnt vmcnt(8)
	s_waitcnt lgkmcnt(0)
	s_barrier
	v_mfma_f32_16x16x32_bf16 v[60:63], v[138:141], v[190:193], v[60:63]
	v_mfma_f32_16x16x32_bf16 v[56:59], v[150:153], v[190:193], v[56:59]
	v_mfma_f32_16x16x32_bf16 v[44:47], v[138:141], v[198:201], v[44:47]
	v_mfma_f32_16x16x32_bf16 v[40:43], v[150:153], v[198:201], v[40:43]
	v_mfma_f32_16x16x32_bf16 v[28:31], v[138:141], v[206:209], v[28:31]
	v_mfma_f32_16x16x32_bf16 v[24:27], v[150:153], v[206:209], v[24:27]
	v_mfma_f32_16x16x32_bf16 v[12:15], v[138:141], v[214:217], v[12:15]
	v_mfma_f32_16x16x32_bf16 v[8:11], v[150:153], v[214:217], v[8:11]
	v_mfma_f32_16x16x32_bf16 v[60:63], v[146:149], v[194:197], v[60:63]
	v_mfma_f32_16x16x32_bf16 v[56:59], v[154:157], v[194:197], v[56:59]
	v_mfma_f32_16x16x32_bf16 v[44:47], v[146:149], v[202:205], v[44:47]
	v_mfma_f32_16x16x32_bf16 v[40:43], v[154:157], v[202:205], v[40:43]
	v_mfma_f32_16x16x32_bf16 v[28:31], v[146:149], v[210:213], v[28:31]
	v_mfma_f32_16x16x32_bf16 v[24:27], v[154:157], v[210:213], v[24:27]
	v_mfma_f32_16x16x32_bf16 v[12:15], v[146:149], v[238:241], v[12:15]
	v_mfma_f32_16x16x32_bf16 v[8:11], v[154:157], v[238:241], v[8:11]
	v_mfma_f32_16x16x32_bf16 v[52:55], v[174:177], v[190:193], v[52:55]
	v_mfma_f32_16x16x32_bf16 v[48:51], v[182:185], v[190:193], v[48:51]
	v_mfma_f32_16x16x32_bf16 v[36:39], v[174:177], v[198:201], v[36:39]
	v_mfma_f32_16x16x32_bf16 v[32:35], v[182:185], v[198:201], v[32:35]
	v_mfma_f32_16x16x32_bf16 v[20:23], v[174:177], v[206:209], v[20:23]
	v_mfma_f32_16x16x32_bf16 v[16:19], v[182:185], v[206:209], v[16:19]
	v_mfma_f32_16x16x32_bf16 v[4:7], v[174:177], v[214:217], v[4:7]
	v_mfma_f32_16x16x32_bf16 v[0:3], v[182:185], v[214:217], v[0:3]
	v_mfma_f32_16x16x32_bf16 v[52:55], v[178:181], v[194:197], v[52:55]
	v_mfma_f32_16x16x32_bf16 v[48:51], v[186:189], v[194:197], v[48:51]
	v_mfma_f32_16x16x32_bf16 v[36:39], v[178:181], v[202:205], v[36:39]
	v_mfma_f32_16x16x32_bf16 v[32:35], v[186:189], v[202:205], v[32:35]
	v_mfma_f32_16x16x32_bf16 v[20:23], v[178:181], v[210:213], v[20:23]
	v_mfma_f32_16x16x32_bf16 v[16:19], v[186:189], v[210:213], v[16:19]
	v_mfma_f32_16x16x32_bf16 v[4:7], v[178:181], v[238:241], v[4:7]
	v_mfma_f32_16x16x32_bf16 v[0:3], v[186:189], v[238:241], v[0:3]
	s_barrier
	s_add_i32 s22, s22, 2
	s_add_u32 s21, s21, 0x100
	s_addc_u32 s92, s92, 0
	s_cmp_gt_u32 s22, 41
	s_mov_b64 s[8:9], s[10:11]
	s_cbranch_scc0 .LBB0_439
	v_lshl_add_u32 v140, s20, 8, v142
	v_lshl_or_b32 v138, s91, 8, v144
	v_lshlrev_b32_e32 v141, 11, v140
	v_lshl_add_u32 v138, v138, 1, v141
	v_lshlrev_b32_e32 v139, 3, v140
	s_mov_b64 s[8:9], s[4:5]
	global_load_dwordx4 v[146:149], v138, s[8:9]
	global_load_dwordx4 v[150:153], v138, s[8:9] offset:256
	s_add_u32 s8, s8, 0x8000
	s_addc_u32 s9, s9, 0
	global_load_dwordx4 v[154:157], v138, s[8:9]
	global_load_dwordx4 v[162:165], v138, s[8:9] offset:256
	s_add_u32 s8, s8, 0x8000
	s_addc_u32 s9, s9, 0
	global_load_dwordx4 v[166:169], v138, s[8:9]
	global_load_dwordx4 v[174:177], v138, s[8:9] offset:256
	s_add_u32 s8, s8, 0x8000
	s_addc_u32 s9, s9, 0
	global_load_dwordx4 v[178:181], v138, s[8:9]
	global_load_dwordx4 v[182:185], v138, s[8:9] offset:256
	s_add_u32 s8, s8, 0x28000
	s_addc_u32 s9, s9, 0
	global_load_dwordx4 v[186:189], v138, s[8:9]
	global_load_dwordx4 v[190:193], v138, s[8:9] offset:256
	s_add_u32 s8, s8, 0x8000
	s_addc_u32 s9, s9, 0
	global_load_dwordx4 v[194:197], v138, s[8:9]
	global_load_dwordx4 v[198:201], v138, s[8:9] offset:256
	s_add_u32 s8, s8, 0x8000
	s_addc_u32 s9, s9, 0
	global_load_dwordx4 v[202:205], v138, s[8:9]
	global_load_dwordx4 v[206:209], v138, s[8:9] offset:256
	s_add_u32 s8, s8, 0x8000
	s_addc_u32 s9, s9, 0
	global_load_dwordx4 v[210:213], v138, s[8:9]
	global_load_dwordx4 v[214:217], v138, s[8:9] offset:256
	s_and_b64 vcc, exec, s[36:37]
	s_cbranch_vccz .LBB0_442
	s_barrier

.LBB0_474:
	s_add_u32 s12, s10, 0xfffc0080
	s_addc_u32 s13, s11, -1
	s_add_i32 s22, 0, 0x10000
	s_cmp_eq_u32 s21, 12
	s_cselect_b32 s15, s20, s13
	s_cselect_b32 s14, s37, s12
	s_cselect_b32 s13, s41, s93
	s_cselect_b32 s12, s91, s92
	s_add_i32 s48, 0, 0x14000
	v_add_u32_e32 v154, s22, v147
	v_add_u32_e32 v158, s48, v147
	ds_read_b128 v[138:141], v154
	ds_read_b128 v[142:145], v154 offset:1024
	ds_read_b128 v[150:153], v154 offset:2048
	ds_read_b128 v[154:157], v154 offset:3072
	ds_read_b128 v[174:177], v158
	ds_read_b128 v[178:181], v158 offset:1024
	ds_read_b128 v[182:185], v158 offset:2048
	ds_read_b128 v[186:189], v158 offset:3072
	s_add_i32 m0, s30, 0xc000
	ds_read_b128 v[190:193], v149
	ds_read_b128 v[194:197], v149 offset:1024
	ds_read_b128 v[198:201], v149 offset:2048
	ds_read_b128 v[202:205], v149 offset:3072
	ds_read_b128 v[206:209], v149 offset:4096
	ds_read_b128 v[210:213], v149 offset:5120
	ds_read_b128 v[214:217], v149 offset:6144
	global_load_lds_dwordx4 v136, s[10:11]
	s_add_i32 m0, s30, 0xe000
	ds_read_b128 v[238:241], v149 offset:7168
	global_load_lds_dwordx4 v134, s[10:11]
	s_waitcnt vmcnt(8)
	s_waitcnt lgkmcnt(0)
	s_barrier
	v_mfma_f32_16x16x32_bf16 v[124:127], v[138:141], v[190:193], v[124:127]
	v_mfma_f32_16x16x32_bf16 v[116:119], v[150:153], v[190:193], v[116:119]
	v_mfma_f32_16x16x32_bf16 v[108:111], v[138:141], v[198:201], v[108:111]
	v_mfma_f32_16x16x32_bf16 v[100:103], v[150:153], v[198:201], v[100:103]
	v_mfma_f32_16x16x32_bf16 v[92:95], v[138:141], v[206:209], v[92:95]
	v_mfma_f32_16x16x32_bf16 v[84:87], v[150:153], v[206:209], v[84:87]
	v_mfma_f32_16x16x32_bf16 v[76:79], v[138:141], v[214:217], v[76:79]
	v_mfma_f32_16x16x32_bf16 v[64:67], v[150:153], v[214:217], v[64:67]
	v_mfma_f32_16x16x32_bf16 v[124:127], v[142:145], v[194:197], v[124:127]
	v_mfma_f32_16x16x32_bf16 v[116:119], v[154:157], v[194:197], v[116:119]
	v_mfma_f32_16x16x32_bf16 v[108:111], v[142:145], v[202:205], v[108:111]
	v_mfma_f32_16x16x32_bf16 v[100:103], v[154:157], v[202:205], v[100:103]
	v_mfma_f32_16x16x32_bf16 v[92:95], v[142:145], v[210:213], v[92:95]
	v_mfma_f32_16x16x32_bf16 v[84:87], v[154:157], v[210:213], v[84:87]
	v_mfma_f32_16x16x32_bf16 v[76:79], v[142:145], v[238:241], v[76:79]
	v_mfma_f32_16x16x32_bf16 v[64:67], v[154:157], v[238:241], v[64:67]
	v_mfma_f32_16x16x32_bf16 v[120:123], v[174:177], v[190:193], v[120:123]
	v_mfma_f32_16x16x32_bf16 v[112:115], v[182:185], v[190:193], v[112:115]
	v_mfma_f32_16x16x32_bf16 v[104:107], v[174:177], v[198:201], v[104:107]
	v_mfma_f32_16x16x32_bf16 v[96:99], v[182:185], v[198:201], v[96:99]
	v_mfma_f32_16x16x32_bf16 v[88:91], v[174:177], v[206:209], v[88:91]
	v_mfma_f32_16x16x32_bf16 v[80:83], v[182:185], v[206:209], v[80:83]
	v_mfma_f32_16x16x32_bf16 v[72:75], v[174:177], v[214:217], v[72:75]
	v_mfma_f32_16x16x32_bf16 v[68:71], v[182:185], v[214:217], v[68:71]
	v_mfma_f32_16x16x32_bf16 v[120:123], v[178:181], v[194:197], v[120:123]
	v_mfma_f32_16x16x32_bf16 v[112:115], v[186:189], v[194:197], v[112:115]
	v_mfma_f32_16x16x32_bf16 v[104:107], v[178:181], v[202:205], v[104:107]
	v_mfma_f32_16x16x32_bf16 v[96:99], v[186:189], v[202:205], v[96:99]
	v_mfma_f32_16x16x32_bf16 v[88:91], v[178:181], v[210:213], v[88:91]
	v_mfma_f32_16x16x32_bf16 v[80:83], v[186:189], v[210:213], v[80:83]
	v_mfma_f32_16x16x32_bf16 v[72:75], v[178:181], v[238:241], v[72:75]
	v_mfma_f32_16x16x32_bf16 v[68:71], v[186:189], v[238:241], v[68:71]
	s_barrier
	s_add_i32 s22, s22, s28
	s_mov_b32 m0, s22
	ds_read_b128 v[190:193], v149 offset:16384
	ds_read_b128 v[194:197], v149 offset:17408
	ds_read_b128 v[198:201], v149 offset:18432
	ds_read_b128 v[202:205], v149 offset:19456
	global_load_lds_dwordx4 v160, s[12:13]
	s_add_i32 m0, s22, 0x2000
	s_add_u32 s96, s12, 0x40000
	s_addc_u32 s97, s13, 0
	s_add_i32 s22, s48, s28
	global_load_lds_dwordx4 v128, s[12:13]
	s_mov_b32 m0, s22
	ds_read_b128 v[238:241], v149 offset:23552
	global_load_lds_dwordx4 v160, s[96:97]
	s_add_i32 m0, s22, 0x2000
	ds_read_b128 v[214:217], v149 offset:22528
	global_load_lds_dwordx4 v128, s[96:97]
	s_mov_b32 m0, s30
	ds_read_b128 v[210:213], v149 offset:21504
	global_load_lds_dwordx4 v132, s[14:15]
	s_mov_b32 m0, s31
	ds_read_b128 v[206:209], v149 offset:20480
	global_load_lds_dwordx4 v130, s[14:15]
	s_waitcnt vmcnt(8)
	s_waitcnt lgkmcnt(0)
	s_barrier
	v_mfma_f32_16x16x32_bf16 v[60:63], v[138:141], v[190:193], v[60:63]
	v_mfma_f32_16x16x32_bf16 v[48:51], v[150:153], v[190:193], v[48:51]
	v_mfma_f32_16x16x32_bf16 v[44:47], v[138:141], v[198:201], v[44:47]
	v_mfma_f32_16x16x32_bf16 v[32:35], v[150:153], v[198:201], v[32:35]
	v_mfma_f32_16x16x32_bf16 v[28:31], v[138:141], v[206:209], v[28:31]
	v_mfma_f32_16x16x32_bf16 v[16:19], v[150:153], v[206:209], v[16:19]
	v_mfma_f32_16x16x32_bf16 v[12:15], v[138:141], v[214:217], v[12:15]
	v_mfma_f32_16x16x32_bf16 v[0:3], v[150:153], v[214:217], v[0:3]
	v_mfma_f32_16x16x32_bf16 v[60:63], v[142:145], v[194:197], v[60:63]
	v_mfma_f32_16x16x32_bf16 v[48:51], v[154:157], v[194:197], v[48:51]
	v_mfma_f32_16x16x32_bf16 v[44:47], v[142:145], v[202:205], v[44:47]
	v_mfma_f32_16x16x32_bf16 v[32:35], v[154:157], v[202:205], v[32:35]
	v_mfma_f32_16x16x32_bf16 v[28:31], v[142:145], v[210:213], v[28:31]
	v_mfma_f32_16x16x32_bf16 v[16:19], v[154:157], v[210:213], v[16:19]
	v_mfma_f32_16x16x32_bf16 v[12:15], v[142:145], v[238:241], v[12:15]
	v_mfma_f32_16x16x32_bf16 v[0:3], v[154:157], v[238:241], v[0:3]
	v_mfma_f32_16x16x32_bf16 v[56:59], v[174:177], v[190:193], v[56:59]
	v_mfma_f32_16x16x32_bf16 v[52:55], v[182:185], v[190:193], v[52:55]
	v_mfma_f32_16x16x32_bf16 v[40:43], v[174:177], v[198:201], v[40:43]
	v_mfma_f32_16x16x32_bf16 v[36:39], v[182:185], v[198:201], v[36:39]
	v_mfma_f32_16x16x32_bf16 v[24:27], v[174:177], v[206:209], v[24:27]
	v_mfma_f32_16x16x32_bf16 v[20:23], v[182:185], v[206:209], v[20:23]
	v_mfma_f32_16x16x32_bf16 v[8:11], v[174:177], v[214:217], v[8:11]
	v_mfma_f32_16x16x32_bf16 v[4:7], v[182:185], v[214:217], v[4:7]
	v_mfma_f32_16x16x32_bf16 v[56:59], v[178:181], v[194:197], v[56:59]
	v_mfma_f32_16x16x32_bf16 v[52:55], v[186:189], v[194:197], v[52:55]
	v_mfma_f32_16x16x32_bf16 v[40:43], v[178:181], v[202:205], v[40:43]
	v_mfma_f32_16x16x32_bf16 v[36:39], v[186:189], v[202:205], v[36:39]
	v_mfma_f32_16x16x32_bf16 v[24:27], v[178:181], v[210:213], v[24:27]
	v_mfma_f32_16x16x32_bf16 v[20:23], v[186:189], v[210:213], v[20:23]
	v_mfma_f32_16x16x32_bf16 v[8:11], v[178:181], v[238:241], v[8:11]
	v_mfma_f32_16x16x32_bf16 v[4:7], v[186:189], v[238:241], v[4:7]
	s_barrier
	s_add_i32 s22, 0, 0x18000
	s_add_i32 s48, 0, 0x1c000
	v_add_u32_e32 v154, s22, v147
	v_add_u32_e32 v168, s48, v147
	ds_read_b128 v[138:141], v154
	ds_read_b128 v[142:145], v154 offset:1024
	ds_read_b128 v[150:153], v154 offset:2048
	ds_read_b128 v[154:157], v154 offset:3072
	ds_read_b128 v[174:177], v168
	ds_read_b128 v[178:181], v168 offset:1024
	ds_read_b128 v[182:185], v168 offset:2048
	ds_read_b128 v[186:189], v168 offset:3072
	s_mov_b64 s[100:101], s[14:15]
	s_add_u32 s14, s14, 0x40000
	s_addc_u32 s15, s15, 0
	s_mov_b32 m0, s33
	ds_read_b128 v[190:193], v149 offset:32768
	ds_read_b128 v[194:197], v149 offset:33792
	ds_read_b128 v[198:201], v149 offset:34816
	ds_read_b128 v[202:205], v149 offset:35840
	ds_read_b128 v[206:209], v149 offset:36864
	ds_read_b128 v[210:213], v149 offset:37888
	ds_read_b128 v[214:217], v149 offset:38912
	global_load_lds_dwordx4 v132, s[14:15]
	s_mov_b32 m0, s34
	ds_read_b128 v[238:241], v149 offset:39936
	global_load_lds_dwordx4 v130, s[14:15]
	s_waitcnt vmcnt(8)
	s_waitcnt lgkmcnt(0)
	s_barrier
	v_mfma_f32_16x16x32_bf16 v[124:127], v[138:141], v[190:193], v[124:127]
	v_mfma_f32_16x16x32_bf16 v[116:119], v[150:153], v[190:193], v[116:119]
	v_mfma_f32_16x16x32_bf16 v[108:111], v[138:141], v[198:201], v[108:111]
	v_mfma_f32_16x16x32_bf16 v[100:103], v[150:153], v[198:201], v[100:103]
	v_mfma_f32_16x16x32_bf16 v[92:95], v[138:141], v[206:209], v[92:95]
	v_mfma_f32_16x16x32_bf16 v[84:87], v[150:153], v[206:209], v[84:87]
	v_mfma_f32_16x16x32_bf16 v[76:79], v[138:141], v[214:217], v[76:79]
	v_mfma_f32_16x16x32_bf16 v[64:67], v[150:153], v[214:217], v[64:67]
	v_mfma_f32_16x16x32_bf16 v[124:127], v[142:145], v[194:197], v[124:127]
	v_mfma_f32_16x16x32_bf16 v[116:119], v[154:157], v[194:197], v[116:119]
	v_mfma_f32_16x16x32_bf16 v[108:111], v[142:145], v[202:205], v[108:111]
	v_mfma_f32_16x16x32_bf16 v[100:103], v[154:157], v[202:205], v[100:103]
	v_mfma_f32_16x16x32_bf16 v[92:95], v[142:145], v[210:213], v[92:95]
	v_mfma_f32_16x16x32_bf16 v[84:87], v[154:157], v[210:213], v[84:87]
	v_mfma_f32_16x16x32_bf16 v[76:79], v[142:145], v[238:241], v[76:79]
	v_mfma_f32_16x16x32_bf16 v[64:67], v[154:157], v[238:241], v[64:67]
	v_mfma_f32_16x16x32_bf16 v[120:123], v[174:177], v[190:193], v[120:123]
	v_mfma_f32_16x16x32_bf16 v[112:115], v[182:185], v[190:193], v[112:115]
	v_mfma_f32_16x16x32_bf16 v[104:107], v[174:177], v[198:201], v[104:107]
	v_mfma_f32_16x16x32_bf16 v[96:99], v[182:185], v[198:201], v[96:99]
	v_mfma_f32_16x16x32_bf16 v[88:91], v[174:177], v[206:209], v[88:91]
	v_mfma_f32_16x16x32_bf16 v[80:83], v[182:185], v[206:209], v[80:83]
	v_mfma_f32_16x16x32_bf16 v[72:75], v[174:177], v[214:217], v[72:75]
	v_mfma_f32_16x16x32_bf16 v[68:71], v[182:185], v[214:217], v[68:71]
	v_mfma_f32_16x16x32_bf16 v[120:123], v[178:181], v[194:197], v[120:123]
	v_mfma_f32_16x16x32_bf16 v[112:115], v[186:189], v[194:197], v[112:115]
	v_mfma_f32_16x16x32_bf16 v[104:107], v[178:181], v[202:205], v[104:107]
	v_mfma_f32_16x16x32_bf16 v[96:99], v[186:189], v[202:205], v[96:99]
	v_mfma_f32_16x16x32_bf16 v[88:91], v[178:181], v[210:213], v[88:91]
	v_mfma_f32_16x16x32_bf16 v[80:83], v[186:189], v[210:213], v[80:83]
	v_mfma_f32_16x16x32_bf16 v[72:75], v[178:181], v[238:241], v[72:75]
	v_mfma_f32_16x16x32_bf16 v[68:71], v[186:189], v[238:241], v[68:71]
	s_barrier
	s_add_i32 s14, s22, s28
	s_add_i32 m0, s14, 0xffffff80
	ds_read_b128 v[190:193], v149 offset:49152
	ds_read_b128 v[194:197], v149 offset:50176
	ds_read_b128 v[198:201], v149 offset:51200
	global_load_lds_dwordx4 v160, s[12:13] offset:128
	s_add_i32 m0, s14, 0x1f80
	ds_read_b128 v[238:241], v149 offset:56320
	global_load_lds_dwordx4 v128, s[12:13] offset:128
	s_add_u32 s12, s12, 0x40080
	s_addc_u32 s13, s13, 0
	s_add_i32 s14, s48, s28
	s_mov_b32 m0, s14
	ds_read_b128 v[214:217], v149 offset:55296
	global_load_lds_dwordx4 v160, s[12:13]
	s_add_i32 m0, s14, 0x2000
	ds_read_b128 v[210:213], v149 offset:54272
	global_load_lds_dwordx4 v128, s[12:13]
	s_add_i32 m0, s35, 0xffffff80
	ds_read_b128 v[206:209], v149 offset:53248
	global_load_lds_dwordx4 v132, s[100:101] offset:128
	s_add_i32 m0, s90, 0xffffff80
	ds_read_b128 v[202:205], v149 offset:52224
	global_load_lds_dwordx4 v130, s[100:101] offset:128
	s_waitcnt vmcnt(8)
	s_waitcnt lgkmcnt(0)
	s_barrier
	v_mfma_f32_16x16x32_bf16 v[60:63], v[138:141], v[190:193], v[60:63]
	v_mfma_f32_16x16x32_bf16 v[48:51], v[150:153], v[190:193], v[48:51]
	v_mfma_f32_16x16x32_bf16 v[44:47], v[138:141], v[198:201], v[44:47]
	v_mfma_f32_16x16x32_bf16 v[32:35], v[150:153], v[198:201], v[32:35]
	v_mfma_f32_16x16x32_bf16 v[28:31], v[138:141], v[206:209], v[28:31]
	v_mfma_f32_16x16x32_bf16 v[16:19], v[150:153], v[206:209], v[16:19]
	v_mfma_f32_16x16x32_bf16 v[12:15], v[138:141], v[214:217], v[12:15]
	v_mfma_f32_16x16x32_bf16 v[0:3], v[150:153], v[214:217], v[0:3]
	v_mfma_f32_16x16x32_bf16 v[60:63], v[142:145], v[194:197], v[60:63]
	v_mfma_f32_16x16x32_bf16 v[48:51], v[154:157], v[194:197], v[48:51]
	v_mfma_f32_16x16x32_bf16 v[44:47], v[142:145], v[202:205], v[44:47]
	v_mfma_f32_16x16x32_bf16 v[32:35], v[154:157], v[202:205], v[32:35]
	v_mfma_f32_16x16x32_bf16 v[28:31], v[142:145], v[210:213], v[28:31]
	v_mfma_f32_16x16x32_bf16 v[16:19], v[154:157], v[210:213], v[16:19]
	v_mfma_f32_16x16x32_bf16 v[12:15], v[142:145], v[238:241], v[12:15]
	v_mfma_f32_16x16x32_bf16 v[0:3], v[154:157], v[238:241], v[0:3]
	v_mfma_f32_16x16x32_bf16 v[56:59], v[174:177], v[190:193], v[56:59]
	v_mfma_f32_16x16x32_bf16 v[52:55], v[182:185], v[190:193], v[52:55]
	v_mfma_f32_16x16x32_bf16 v[40:43], v[174:177], v[198:201], v[40:43]
	v_mfma_f32_16x16x32_bf16 v[36:39], v[182:185], v[198:201], v[36:39]
	v_mfma_f32_16x16x32_bf16 v[24:27], v[174:177], v[206:209], v[24:27]
	v_mfma_f32_16x16x32_bf16 v[20:23], v[182:185], v[206:209], v[20:23]
	v_mfma_f32_16x16x32_bf16 v[8:11], v[174:177], v[214:217], v[8:11]
	v_mfma_f32_16x16x32_bf16 v[4:7], v[182:185], v[214:217], v[4:7]
	v_mfma_f32_16x16x32_bf16 v[56:59], v[178:181], v[194:197], v[56:59]
	v_mfma_f32_16x16x32_bf16 v[52:55], v[186:189], v[194:197], v[52:55]
	v_mfma_f32_16x16x32_bf16 v[40:43], v[178:181], v[202:205], v[40:43]
	v_mfma_f32_16x16x32_bf16 v[36:39], v[186:189], v[202:205], v[36:39]
	v_mfma_f32_16x16x32_bf16 v[24:27], v[178:181], v[210:213], v[24:27]
	v_mfma_f32_16x16x32_bf16 v[20:23], v[186:189], v[210:213], v[20:23]
	v_mfma_f32_16x16x32_bf16 v[8:11], v[178:181], v[238:241], v[8:11]
	v_mfma_f32_16x16x32_bf16 v[4:7], v[186:189], v[238:241], v[4:7]
	s_barrier
	s_add_i32 s21, s21, 2
	s_add_u32 s92, s92, 0x100
	s_addc_u32 s93, s93, 0
	s_add_u32 s10, s10, 0x100
	s_addc_u32 s11, s11, 0
	s_cmp_gt_u32 s21, 13
	s_cbranch_scc0 .LBB0_474
	v_lshl_add_u32 v192, s8, 8, v146
	v_lshlrev_b32_e32 v192, 3, v192
	global_load_dwordx2 v[176:177], v192, s[4:5]
	global_load_dwordx2 v[178:179], v192, s[4:5] offset:128
	global_load_dwordx2 v[180:181], v192, s[4:5] offset:256
	global_load_dwordx2 v[182:183], v192, s[4:5] offset:384
	global_load_dwordx2 v[184:185], v192, s[4:5] offset:1024
	global_load_dwordx2 v[186:187], v192, s[4:5] offset:1152
	global_load_dwordx2 v[188:189], v192, s[4:5] offset:1280
	global_load_dwordx2 v[190:191], v192, s[4:5] offset:1408
	s_and_b64 vcc, exec, s[6:7]
	s_cbranch_vccz .LBB0_477
	s_barrier

	.amdhsa_kernel _ZN2mk10fwd_kernelENS_4ArgsE
		.amdhsa_group_segment_fixed_size 0
		.amdhsa_private_segment_fixed_size 0
		.amdhsa_kernarg_size 424
		.amdhsa_user_sgpr_count 2
		.amdhsa_user_sgpr_dispatch_ptr 0
		.amdhsa_user_sgpr_queue_ptr 0
		.amdhsa_user_sgpr_kernarg_segment_ptr 1
		.amdhsa_user_sgpr_dispatch_id 0
		.amdhsa_user_sgpr_kernarg_preload_length 0
		.amdhsa_user_sgpr_kernarg_preload_offset 0
		.amdhsa_user_sgpr_private_segment_size 0
		.amdhsa_uses_dynamic_stack 0
		.amdhsa_enable_private_segment 0
		.amdhsa_system_sgpr_workgroup_id_x 1
		.amdhsa_system_sgpr_workgroup_id_y 0
		.amdhsa_system_sgpr_workgroup_id_z 0
		.amdhsa_system_sgpr_workgroup_info 0
		.amdhsa_system_vgpr_workitem_id 2
		.amdhsa_next_free_vgpr 256
		.amdhsa_next_free_sgpr 102
		.amdhsa_accum_offset 256
		.amdhsa_reserve_vcc 1
		.amdhsa_float_round_mode_32 0
		.amdhsa_float_round_mode_16_64 0
		.amdhsa_float_denorm_mode_32 3
		.amdhsa_float_denorm_mode_16_64 3
		.amdhsa_dx10_clamp 1
		.amdhsa_ieee_mode 1
		.amdhsa_fp16_overflow 0
		.amdhsa_tg_split 0
		.amdhsa_exception_fp_ieee_invalid_op 0
		.amdhsa_exception_fp_denorm_src 0
		.amdhsa_exception_fp_ieee_div_zero 0
		.amdhsa_exception_fp_ieee_overflow 0
		.amdhsa_exception_fp_ieee_underflow 0
		.amdhsa_exception_fp_ieee_inexact 0
		.amdhsa_exception_int_div_zero 0
	.end_amdhsa_kernel

amdhsa.kernels:
  - .agpr_count:     0
    .args:
      - .offset:         0
        .size:           168
        .value_kind:     by_value
      - .offset:         168
        .size:           4
        .value_kind:     hidden_block_count_x
      - .offset:         172
        .size:           4
        .value_kind:     hidden_block_count_y
      - .offset:         176
        .size:           4
        .value_kind:     hidden_block_count_z
      - .offset:         180
        .size:           2
        .value_kind:     hidden_group_size_x
      - .offset:         182
        .size:           2
        .value_kind:     hidden_group_size_y
      - .offset:         184
        .size:           2
        .value_kind:     hidden_group_size_z
      - .offset:         186
        .size:           2
        .value_kind:     hidden_remainder_x
      - .offset:         188
        .size:           2
        .value_kind:     hidden_remainder_y
      - .offset:         190
        .size:           2
        .value_kind:     hidden_remainder_z
      - .offset:         208
        .size:           8
        .value_kind:     hidden_global_offset_x
      - .offset:         216
        .size:           8
        .value_kind:     hidden_global_offset_y
      - .offset:         224
        .size:           8
        .value_kind:     hidden_global_offset_z
      - .offset:         232
        .size:           2
        .value_kind:     hidden_grid_dims
      - .offset:         256
        .size:           8
        .value_kind:     hidden_multigrid_sync_arg
      - .offset:         288
        .size:           4
        .value_kind:     hidden_dynamic_lds_size
    .group_segment_fixed_size: 0
    .kernarg_segment_align: 8
    .kernarg_segment_size: 424
    .language:       OpenCL C
    .language_version:
      - 2
      - 0
    .max_flat_workgroup_size: 512
    .name:           _ZN2mk10fwd_kernelENS_4ArgsE
    .private_segment_fixed_size: 0
    .sgpr_count:     108
    .sgpr_spill_count: 109
    .symbol:         _ZN2mk10fwd_kernelENS_4ArgsE.kd
    .uniform_work_group_size: 1
    .uses_dynamic_stack: false
    .vgpr_count:     256
    .vgpr_spill_count: 0
    .wavefront_size: 64
